# y partial sums reduced over 4 lanes only (4 partials per row in 32 KB of LDS, 16 KB static) instead of 8
# baseline (speedup 1.0000x reference)
.LBB0_100:
	s_or_b64 exec, exec, s[10:11]
	s_waitcnt lgkmcnt(0)
	s_barrier
	v_lshrrev_b32_e32 v244, 4, v134
	v_lshl_add_u32 v244, v244, 9, v162
	ds_read_b128 v[4:7], v244
	ds_read_b128 v[8:11], v244 offset:256
	ds_read_b128 v[200:203], v244 offset:512
	ds_read_b128 v[204:207], v244 offset:768
	s_add_i32 s68, s68, 1
	s_cmp_eq_u32 s68, 64
	s_waitcnt lgkmcnt(0)
	v_pk_add_f32 v[4:5], v[4:5], v[200:201]
	v_pk_add_f32 v[6:7], v[6:7], v[202:203]
	v_pk_add_f32 v[8:9], v[8:9], v[204:205]
	v_pk_add_f32 v[10:11], v[10:11], v[206:207]
	v_pk_add_f32 v[10:11], v[6:7], v[10:11]
	v_pk_add_f32 v[8:9], v[4:5], v[8:9]
	ds_read_b128 v[4:7], v160
	s_waitcnt lgkmcnt(0)
	v_pk_add_f32 v[6:7], v[10:11], v[6:7]
	v_pk_add_f32 v[4:5], v[8:9], v[4:5]
	s_nop 0
	v_cvt_pk_bf16_f32 v4, v4, v5
	v_cvt_pk_bf16_f32 v5, v6, v7
	v_lshlrev_b64 v[6:7], 11, v[128:129]
	v_lshl_add_u64 v[6:7], v[108:109], 0, v[6:7]
	global_store_dwordx2 v[6:7], v[4:5], off
	s_cbranch_scc1 .LBB0_143

.LBB0_131:
	s_or_b64 exec, exec, s[10:11]
	s_waitcnt lgkmcnt(0)
	s_barrier
	v_mbcnt_lo_u32_b32 v197, -1, 0
	v_mbcnt_hi_u32_b32 v197, -1, v197
	v_lshlrev_b32_e32 v197, 3, v197
	v_add_u32_e32 v197, 0xe000, v197
	v_cndmask_b32_e64 v196, v197, v161, s[8:9]
	v_add_u32_e32 v69, 0xffffe800, v185
	v_mbcnt_lo_u32_b32 v197, -1, 0
	v_mbcnt_hi_u32_b32 v197, -1, v197
	v_and_b32_e32 v197, 12, v197
	v_lshlrev_b32_e32 v197, 6, v197
	v_add_u32_e32 v196, 0xe800, v185
	v_add_u32_e32 v196, v197, v196
	s_mov_b32 s10, 0x11111111
	s_mov_b32 s11, 0x11111111
	ds_read_b128 v[8:11], v152 offset:16128
	ds_read_b128 v[12:15], v152 offset:24320
	ds_read_b128 v[16:19], v152 offset:32512
	ds_read_b128 v[20:23], v152 offset:40704
	ds_read_b64 v[64:65], v69 offset:7936
	ds_read_b128 v[28:31], v152 offset:15872
	ds_read_b128 v[32:35], v152 offset:24064
	ds_read_b128 v[36:39], v152 offset:32256
	ds_read_b128 v[40:43], v152 offset:40448
	ds_read_b64 v[66:67], v69 offset:7680
	ds_read_b128 v[48:51], v152 offset:15616
	ds_read_b128 v[52:55], v152 offset:23808
	ds_read_b128 v[56:59], v152 offset:32000
	ds_read_b128 v[60:63], v152 offset:40192
	ds_read_b64 v[130:131], v69 offset:7424
	s_waitcnt lgkmcnt(10)
	v_mul_f32_e32 v194, v186, v8
	v_mul_f32_e32 v195, v190, v8
	v_mul_f32_e32 v132, v186, v20
	v_mul_f32_e32 v133, v190, v20
	v_fmac_f32_e32 v194, v187, v9
	v_fmac_f32_e32 v195, v191, v9
	v_fmac_f32_e32 v132, v187, v21
	v_fmac_f32_e32 v133, v191, v21
	v_fmac_f32_e32 v194, v188, v10
	v_fmac_f32_e32 v195, v192, v10
	v_fmac_f32_e32 v132, v188, v22
	v_fmac_f32_e32 v133, v192, v22
	v_fmac_f32_e32 v194, v189, v11
	v_fmac_f32_e32 v195, v193, v11
	v_fmac_f32_e32 v132, v189, v23
	v_fmac_f32_e32 v133, v193, v23
	v_add_f32_dpp v194, v194, v194 quad_perm:[1,0,3,2] row_mask:0xf bank_mask:0xf bound_ctrl:1
	v_add_f32_dpp v195, v195, v195 quad_perm:[1,0,3,2] row_mask:0xf bank_mask:0xf bound_ctrl:1
	v_add_f32_dpp v132, v132, v132 quad_perm:[1,0,3,2] row_mask:0xf bank_mask:0xf bound_ctrl:1
	v_add_f32_dpp v133, v133, v133 quad_perm:[1,0,3,2] row_mask:0xf bank_mask:0xf bound_ctrl:1
	v_add_f32_dpp v194, v194, v194 quad_perm:[2,3,0,1] row_mask:0xf bank_mask:0xf bound_ctrl:1
	v_add_f32_dpp v195, v195, v195 quad_perm:[2,3,0,1] row_mask:0xf bank_mask:0xf bound_ctrl:1
	v_add_f32_dpp v132, v132, v132 quad_perm:[2,3,0,1] row_mask:0xf bank_mask:0xf bound_ctrl:1
	v_add_f32_dpp v133, v133, v133 quad_perm:[2,3,0,1] row_mask:0xf bank_mask:0xf bound_ctrl:1
	v_add_f32_dpp v194, v194, v194 row_half_mirror row_mask:0xf bank_mask:0xf bound_ctrl:1
	v_add_f32_dpp v195, v195, v195 row_half_mirror row_mask:0xf bank_mask:0xf bound_ctrl:1
	v_fmac_f32_e32 v186, v64, v16
	v_fmac_f32_e32 v187, v64, v17
	v_add_f32_dpp v194, v194, v194 row_mirror row_mask:0xf bank_mask:0xf bound_ctrl:1
	v_add_f32_dpp v195, v195, v195 row_mirror row_mask:0xf bank_mask:0xf bound_ctrl:1
	v_fmac_f32_e32 v188, v64, v18
	v_fmac_f32_e32 v189, v64, v19
	v_fmac_f32_e32 v190, v65, v16
	v_fmac_f32_e32 v191, v65, v17
	v_fmac_f32_e32 v192, v65, v18
	v_fmac_f32_e32 v193, v65, v19
	v_fmac_f32_e32 v186, v194, v12
	v_fmac_f32_e32 v187, v194, v13
	v_fmac_f32_e32 v188, v194, v14
	v_fmac_f32_e32 v189, v194, v15
	v_fmac_f32_e32 v190, v195, v12
	v_fmac_f32_e32 v191, v195, v13
	v_fmac_f32_e32 v192, v195, v14
	v_fmac_f32_e32 v193, v195, v15
	ds_read_b128 v[8:11], v152 offset:15360
	ds_read_b128 v[12:15], v152 offset:23552
	ds_read_b128 v[16:19], v152 offset:31744
	ds_read_b128 v[20:23], v152 offset:39936
	ds_read_b64 v[64:65], v69 offset:7168
	s_waitcnt lgkmcnt(10)
	v_mul_f32_e32 v194, v186, v28
	v_mul_f32_e32 v195, v190, v28
	v_mul_f32_e32 v238, v186, v40
	v_mul_f32_e32 v239, v190, v40
	v_fmac_f32_e32 v194, v187, v29
	v_fmac_f32_e32 v195, v191, v29
	v_fmac_f32_e32 v238, v187, v41
	v_fmac_f32_e32 v239, v191, v41
	v_fmac_f32_e32 v194, v188, v30
	v_fmac_f32_e32 v195, v192, v30
	v_fmac_f32_e32 v238, v188, v42
	v_fmac_f32_e32 v239, v192, v42
	v_fmac_f32_e32 v194, v189, v31
	v_fmac_f32_e32 v195, v193, v31
	v_fmac_f32_e32 v238, v189, v43
	v_fmac_f32_e32 v239, v193, v43
	v_add_f32_dpp v194, v194, v194 quad_perm:[1,0,3,2] row_mask:0xf bank_mask:0xf bound_ctrl:1
	v_add_f32_dpp v195, v195, v195 quad_perm:[1,0,3,2] row_mask:0xf bank_mask:0xf bound_ctrl:1
	v_add_f32_dpp v238, v238, v238 quad_perm:[1,0,3,2] row_mask:0xf bank_mask:0xf bound_ctrl:1
	v_add_f32_dpp v239, v239, v239 quad_perm:[1,0,3,2] row_mask:0xf bank_mask:0xf bound_ctrl:1
	v_add_f32_dpp v194, v194, v194 quad_perm:[2,3,0,1] row_mask:0xf bank_mask:0xf bound_ctrl:1
	v_add_f32_dpp v195, v195, v195 quad_perm:[2,3,0,1] row_mask:0xf bank_mask:0xf bound_ctrl:1
	v_add_f32_dpp v238, v238, v238 quad_perm:[2,3,0,1] row_mask:0xf bank_mask:0xf bound_ctrl:1
	v_add_f32_dpp v239, v239, v239 quad_perm:[2,3,0,1] row_mask:0xf bank_mask:0xf bound_ctrl:1
	v_add_f32_dpp v194, v194, v194 row_half_mirror row_mask:0xf bank_mask:0xf bound_ctrl:1
	v_add_f32_dpp v195, v195, v195 row_half_mirror row_mask:0xf bank_mask:0xf bound_ctrl:1
	v_fmac_f32_e32 v186, v66, v36
	v_fmac_f32_e32 v187, v66, v37
	v_add_f32_dpp v194, v194, v194 row_mirror row_mask:0xf bank_mask:0xf bound_ctrl:1
	v_add_f32_dpp v195, v195, v195 row_mirror row_mask:0xf bank_mask:0xf bound_ctrl:1
	v_fmac_f32_e32 v188, v66, v38
	v_fmac_f32_e32 v189, v66, v39
	v_fmac_f32_e32 v190, v67, v36
	v_fmac_f32_e32 v191, v67, v37
	v_fmac_f32_e32 v192, v67, v38
	v_fmac_f32_e32 v193, v67, v39
	v_fmac_f32_e32 v186, v194, v32
	v_fmac_f32_e32 v187, v194, v33
	v_fmac_f32_e32 v188, v194, v34
	v_fmac_f32_e32 v189, v194, v35
	v_fmac_f32_e32 v190, v195, v32
	v_fmac_f32_e32 v191, v195, v33
	v_fmac_f32_e32 v192, v195, v34
	v_fmac_f32_e32 v193, v195, v35
	s_mov_b64 exec, s[10:11]
	ds_write2st64_b64 v196, v[132:133], v[238:239] offset0:62 offset1:60
	s_mov_b64 exec, -1
	ds_read_b128 v[28:31], v152 offset:15104
	ds_read_b128 v[32:35], v152 offset:23296
	ds_read_b128 v[36:39], v152 offset:31488
	ds_read_b128 v[40:43], v152 offset:39680
	ds_read_b64 v[66:67], v69 offset:6912
	s_waitcnt lgkmcnt(11)
	v_mul_f32_e32 v194, v186, v48
	v_mul_f32_e32 v195, v190, v48
	v_mul_f32_e32 v132, v186, v60
	v_mul_f32_e32 v133, v190, v60
	v_fmac_f32_e32 v194, v187, v49
	v_fmac_f32_e32 v195, v191, v49
	v_fmac_f32_e32 v132, v187, v61
	v_fmac_f32_e32 v133, v191, v61
	v_fmac_f32_e32 v194, v188, v50
	v_fmac_f32_e32 v195, v192, v50
	v_fmac_f32_e32 v132, v188, v62
	v_fmac_f32_e32 v133, v192, v62
	v_fmac_f32_e32 v194, v189, v51
	v_fmac_f32_e32 v195, v193, v51
	v_fmac_f32_e32 v132, v189, v63
	v_fmac_f32_e32 v133, v193, v63
	v_add_f32_dpp v194, v194, v194 quad_perm:[1,0,3,2] row_mask:0xf bank_mask:0xf bound_ctrl:1
	v_add_f32_dpp v195, v195, v195 quad_perm:[1,0,3,2] row_mask:0xf bank_mask:0xf bound_ctrl:1
	v_add_f32_dpp v132, v132, v132 quad_perm:[1,0,3,2] row_mask:0xf bank_mask:0xf bound_ctrl:1
	v_add_f32_dpp v133, v133, v133 quad_perm:[1,0,3,2] row_mask:0xf bank_mask:0xf bound_ctrl:1
	v_add_f32_dpp v194, v194, v194 quad_perm:[2,3,0,1] row_mask:0xf bank_mask:0xf bound_ctrl:1
	v_add_f32_dpp v195, v195, v195 quad_perm:[2,3,0,1] row_mask:0xf bank_mask:0xf bound_ctrl:1
	v_add_f32_dpp v132, v132, v132 quad_perm:[2,3,0,1] row_mask:0xf bank_mask:0xf bound_ctrl:1
	v_add_f32_dpp v133, v133, v133 quad_perm:[2,3,0,1] row_mask:0xf bank_mask:0xf bound_ctrl:1
	v_add_f32_dpp v194, v194, v194 row_half_mirror row_mask:0xf bank_mask:0xf bound_ctrl:1
	v_add_f32_dpp v195, v195, v195 row_half_mirror row_mask:0xf bank_mask:0xf bound_ctrl:1
	v_fmac_f32_e32 v186, v130, v56
	v_fmac_f32_e32 v187, v130, v57
	v_add_f32_dpp v194, v194, v194 row_mirror row_mask:0xf bank_mask:0xf bound_ctrl:1
	v_add_f32_dpp v195, v195, v195 row_mirror row_mask:0xf bank_mask:0xf bound_ctrl:1
	v_fmac_f32_e32 v188, v130, v58
	v_fmac_f32_e32 v189, v130, v59
	v_fmac_f32_e32 v190, v131, v56
	v_fmac_f32_e32 v191, v131, v57
	v_fmac_f32_e32 v192, v131, v58
	v_fmac_f32_e32 v193, v131, v59
	v_fmac_f32_e32 v186, v194, v52
	v_fmac_f32_e32 v187, v194, v53
	v_fmac_f32_e32 v188, v194, v54
	v_fmac_f32_e32 v189, v194, v55
	v_fmac_f32_e32 v190, v195, v52
	v_fmac_f32_e32 v191, v195, v53
	v_fmac_f32_e32 v192, v195, v54
	v_fmac_f32_e32 v193, v195, v55
	ds_read_b128 v[48:51], v152 offset:14848
	ds_read_b128 v[52:55], v152 offset:23040
	ds_read_b128 v[56:59], v152 offset:31232
	ds_read_b128 v[60:63], v152 offset:39424
	ds_read_b64 v[130:131], v69 offset:6656
	s_waitcnt lgkmcnt(11)
	v_mul_f32_e32 v194, v186, v8
	v_mul_f32_e32 v195, v190, v8
	v_mul_f32_e32 v238, v186, v20
	v_mul_f32_e32 v239, v190, v20
	v_fmac_f32_e32 v194, v187, v9
	v_fmac_f32_e32 v195, v191, v9
	v_fmac_f32_e32 v238, v187, v21
	v_fmac_f32_e32 v239, v191, v21
	v_fmac_f32_e32 v194, v188, v10
	v_fmac_f32_e32 v195, v192, v10
	v_fmac_f32_e32 v238, v188, v22
	v_fmac_f32_e32 v239, v192, v22
	v_fmac_f32_e32 v194, v189, v11
	v_fmac_f32_e32 v195, v193, v11
	v_fmac_f32_e32 v238, v189, v23
	v_fmac_f32_e32 v239, v193, v23
	v_add_f32_dpp v194, v194, v194 quad_perm:[1,0,3,2] row_mask:0xf bank_mask:0xf bound_ctrl:1
	v_add_f32_dpp v195, v195, v195 quad_perm:[1,0,3,2] row_mask:0xf bank_mask:0xf bound_ctrl:1
	v_add_f32_dpp v238, v238, v238 quad_perm:[1,0,3,2] row_mask:0xf bank_mask:0xf bound_ctrl:1
	v_add_f32_dpp v239, v239, v239 quad_perm:[1,0,3,2] row_mask:0xf bank_mask:0xf bound_ctrl:1
	v_add_f32_dpp v194, v194, v194 quad_perm:[2,3,0,1] row_mask:0xf bank_mask:0xf bound_ctrl:1
	v_add_f32_dpp v195, v195, v195 quad_perm:[2,3,0,1] row_mask:0xf bank_mask:0xf bound_ctrl:1
	v_add_f32_dpp v238, v238, v238 quad_perm:[2,3,0,1] row_mask:0xf bank_mask:0xf bound_ctrl:1
	v_add_f32_dpp v239, v239, v239 quad_perm:[2,3,0,1] row_mask:0xf bank_mask:0xf bound_ctrl:1
	v_add_f32_dpp v194, v194, v194 row_half_mirror row_mask:0xf bank_mask:0xf bound_ctrl:1
	v_add_f32_dpp v195, v195, v195 row_half_mirror row_mask:0xf bank_mask:0xf bound_ctrl:1
	v_fmac_f32_e32 v186, v64, v16
	v_fmac_f32_e32 v187, v64, v17
	v_add_f32_dpp v194, v194, v194 row_mirror row_mask:0xf bank_mask:0xf bound_ctrl:1
	v_add_f32_dpp v195, v195, v195 row_mirror row_mask:0xf bank_mask:0xf bound_ctrl:1
	v_fmac_f32_e32 v188, v64, v18
	v_fmac_f32_e32 v189, v64, v19
	v_fmac_f32_e32 v190, v65, v16
	v_fmac_f32_e32 v191, v65, v17
	v_fmac_f32_e32 v192, v65, v18
	v_fmac_f32_e32 v193, v65, v19
	v_fmac_f32_e32 v186, v194, v12
	v_fmac_f32_e32 v187, v194, v13
	v_fmac_f32_e32 v188, v194, v14
	v_fmac_f32_e32 v189, v194, v15
	v_fmac_f32_e32 v190, v195, v12
	v_fmac_f32_e32 v191, v195, v13
	v_fmac_f32_e32 v192, v195, v14
	v_fmac_f32_e32 v193, v195, v15
	s_mov_b64 exec, s[10:11]
	ds_write2st64_b64 v196, v[132:133], v[238:239] offset0:58 offset1:56
	s_mov_b64 exec, -1
	ds_read_b128 v[8:11], v152 offset:14592
	ds_read_b128 v[12:15], v152 offset:22784
	ds_read_b128 v[16:19], v152 offset:30976
	ds_read_b128 v[20:23], v152 offset:39168
	ds_read_b64 v[64:65], v69 offset:6400
	s_waitcnt lgkmcnt(11)
	v_mul_f32_e32 v194, v186, v28
	v_mul_f32_e32 v195, v190, v28
	v_mul_f32_e32 v132, v186, v40
	v_mul_f32_e32 v133, v190, v40
	v_fmac_f32_e32 v194, v187, v29
	v_fmac_f32_e32 v195, v191, v29
	v_fmac_f32_e32 v132, v187, v41
	v_fmac_f32_e32 v133, v191, v41
	v_fmac_f32_e32 v194, v188, v30
	v_fmac_f32_e32 v195, v192, v30
	v_fmac_f32_e32 v132, v188, v42
	v_fmac_f32_e32 v133, v192, v42
	v_fmac_f32_e32 v194, v189, v31
	v_fmac_f32_e32 v195, v193, v31
	v_fmac_f32_e32 v132, v189, v43
	v_fmac_f32_e32 v133, v193, v43
	v_add_f32_dpp v194, v194, v194 quad_perm:[1,0,3,2] row_mask:0xf bank_mask:0xf bound_ctrl:1
	v_add_f32_dpp v195, v195, v195 quad_perm:[1,0,3,2] row_mask:0xf bank_mask:0xf bound_ctrl:1
	v_add_f32_dpp v132, v132, v132 quad_perm:[1,0,3,2] row_mask:0xf bank_mask:0xf bound_ctrl:1
	v_add_f32_dpp v133, v133, v133 quad_perm:[1,0,3,2] row_mask:0xf bank_mask:0xf bound_ctrl:1
	v_add_f32_dpp v194, v194, v194 quad_perm:[2,3,0,1] row_mask:0xf bank_mask:0xf bound_ctrl:1
	v_add_f32_dpp v195, v195, v195 quad_perm:[2,3,0,1] row_mask:0xf bank_mask:0xf bound_ctrl:1
	v_add_f32_dpp v132, v132, v132 quad_perm:[2,3,0,1] row_mask:0xf bank_mask:0xf bound_ctrl:1
	v_add_f32_dpp v133, v133, v133 quad_perm:[2,3,0,1] row_mask:0xf bank_mask:0xf bound_ctrl:1
	v_add_f32_dpp v194, v194, v194 row_half_mirror row_mask:0xf bank_mask:0xf bound_ctrl:1
	v_add_f32_dpp v195, v195, v195 row_half_mirror row_mask:0xf bank_mask:0xf bound_ctrl:1
	v_fmac_f32_e32 v186, v66, v36
	v_fmac_f32_e32 v187, v66, v37
	v_add_f32_dpp v194, v194, v194 row_mirror row_mask:0xf bank_mask:0xf bound_ctrl:1
	v_add_f32_dpp v195, v195, v195 row_mirror row_mask:0xf bank_mask:0xf bound_ctrl:1
	v_fmac_f32_e32 v188, v66, v38
	v_fmac_f32_e32 v189, v66, v39
	v_fmac_f32_e32 v190, v67, v36
	v_fmac_f32_e32 v191, v67, v37
	v_fmac_f32_e32 v192, v67, v38
	v_fmac_f32_e32 v193, v67, v39
	v_fmac_f32_e32 v186, v194, v32
	v_fmac_f32_e32 v187, v194, v33
	v_fmac_f32_e32 v188, v194, v34
	v_fmac_f32_e32 v189, v194, v35
	v_fmac_f32_e32 v190, v195, v32
	v_fmac_f32_e32 v191, v195, v33
	v_fmac_f32_e32 v192, v195, v34
	v_fmac_f32_e32 v193, v195, v35
	ds_read_b128 v[28:31], v152 offset:14336
	ds_read_b128 v[32:35], v152 offset:22528
	ds_read_b128 v[36:39], v152 offset:30720
	ds_read_b128 v[40:43], v152 offset:38912
	ds_read_b64 v[66:67], v69 offset:6144
	s_waitcnt lgkmcnt(11)
	v_mul_f32_e32 v194, v186, v48
	v_mul_f32_e32 v195, v190, v48
	v_mul_f32_e32 v238, v186, v60
	v_mul_f32_e32 v239, v190, v60
	v_fmac_f32_e32 v194, v187, v49
	v_fmac_f32_e32 v195, v191, v49
	v_fmac_f32_e32 v238, v187, v61
	v_fmac_f32_e32 v239, v191, v61
	v_fmac_f32_e32 v194, v188, v50
	v_fmac_f32_e32 v195, v192, v50
	v_fmac_f32_e32 v238, v188, v62
	v_fmac_f32_e32 v239, v192, v62
	v_fmac_f32_e32 v194, v189, v51
	v_fmac_f32_e32 v195, v193, v51
	v_fmac_f32_e32 v238, v189, v63
	v_fmac_f32_e32 v239, v193, v63
	v_add_f32_dpp v194, v194, v194 quad_perm:[1,0,3,2] row_mask:0xf bank_mask:0xf bound_ctrl:1
	v_add_f32_dpp v195, v195, v195 quad_perm:[1,0,3,2] row_mask:0xf bank_mask:0xf bound_ctrl:1
	v_add_f32_dpp v238, v238, v238 quad_perm:[1,0,3,2] row_mask:0xf bank_mask:0xf bound_ctrl:1
	v_add_f32_dpp v239, v239, v239 quad_perm:[1,0,3,2] row_mask:0xf bank_mask:0xf bound_ctrl:1
	v_add_f32_dpp v194, v194, v194 quad_perm:[2,3,0,1] row_mask:0xf bank_mask:0xf bound_ctrl:1
	v_add_f32_dpp v195, v195, v195 quad_perm:[2,3,0,1] row_mask:0xf bank_mask:0xf bound_ctrl:1
	v_add_f32_dpp v238, v238, v238 quad_perm:[2,3,0,1] row_mask:0xf bank_mask:0xf bound_ctrl:1
	v_add_f32_dpp v239, v239, v239 quad_perm:[2,3,0,1] row_mask:0xf bank_mask:0xf bound_ctrl:1
	v_add_f32_dpp v194, v194, v194 row_half_mirror row_mask:0xf bank_mask:0xf bound_ctrl:1
	v_add_f32_dpp v195, v195, v195 row_half_mirror row_mask:0xf bank_mask:0xf bound_ctrl:1
	v_fmac_f32_e32 v186, v130, v56
	v_fmac_f32_e32 v187, v130, v57
	v_add_f32_dpp v194, v194, v194 row_mirror row_mask:0xf bank_mask:0xf bound_ctrl:1
	v_add_f32_dpp v195, v195, v195 row_mirror row_mask:0xf bank_mask:0xf bound_ctrl:1
	v_fmac_f32_e32 v188, v130, v58
	v_fmac_f32_e32 v189, v130, v59
	v_fmac_f32_e32 v190, v131, v56
	v_fmac_f32_e32 v191, v131, v57
	v_fmac_f32_e32 v192, v131, v58
	v_fmac_f32_e32 v193, v131, v59
	v_fmac_f32_e32 v186, v194, v52
	v_fmac_f32_e32 v187, v194, v53
	v_fmac_f32_e32 v188, v194, v54
	v_fmac_f32_e32 v189, v194, v55
	v_fmac_f32_e32 v190, v195, v52
	v_fmac_f32_e32 v191, v195, v53
	v_fmac_f32_e32 v192, v195, v54
	v_fmac_f32_e32 v193, v195, v55
	s_mov_b64 exec, s[10:11]
	ds_write2st64_b64 v196, v[132:133], v[238:239] offset0:54 offset1:52
	s_mov_b64 exec, -1
	ds_read_b128 v[48:51], v152 offset:14080
	ds_read_b128 v[52:55], v152 offset:22272
	ds_read_b128 v[56:59], v152 offset:30464
	ds_read_b128 v[60:63], v152 offset:38656
	ds_read_b64 v[130:131], v69 offset:5888
	s_waitcnt lgkmcnt(11)
	v_mul_f32_e32 v194, v186, v8
	v_mul_f32_e32 v195, v190, v8
	v_mul_f32_e32 v132, v186, v20
	v_mul_f32_e32 v133, v190, v20
	v_fmac_f32_e32 v194, v187, v9
	v_fmac_f32_e32 v195, v191, v9
	v_fmac_f32_e32 v132, v187, v21
	v_fmac_f32_e32 v133, v191, v21
	v_fmac_f32_e32 v194, v188, v10
	v_fmac_f32_e32 v195, v192, v10
	v_fmac_f32_e32 v132, v188, v22
	v_fmac_f32_e32 v133, v192, v22
	v_fmac_f32_e32 v194, v189, v11
	v_fmac_f32_e32 v195, v193, v11
	v_fmac_f32_e32 v132, v189, v23
	v_fmac_f32_e32 v133, v193, v23
	v_add_f32_dpp v194, v194, v194 quad_perm:[1,0,3,2] row_mask:0xf bank_mask:0xf bound_ctrl:1
	v_add_f32_dpp v195, v195, v195 quad_perm:[1,0,3,2] row_mask:0xf bank_mask:0xf bound_ctrl:1
	v_add_f32_dpp v132, v132, v132 quad_perm:[1,0,3,2] row_mask:0xf bank_mask:0xf bound_ctrl:1
	v_add_f32_dpp v133, v133, v133 quad_perm:[1,0,3,2] row_mask:0xf bank_mask:0xf bound_ctrl:1
	v_add_f32_dpp v194, v194, v194 quad_perm:[2,3,0,1] row_mask:0xf bank_mask:0xf bound_ctrl:1
	v_add_f32_dpp v195, v195, v195 quad_perm:[2,3,0,1] row_mask:0xf bank_mask:0xf bound_ctrl:1
	v_add_f32_dpp v132, v132, v132 quad_perm:[2,3,0,1] row_mask:0xf bank_mask:0xf bound_ctrl:1
	v_add_f32_dpp v133, v133, v133 quad_perm:[2,3,0,1] row_mask:0xf bank_mask:0xf bound_ctrl:1
	v_add_f32_dpp v194, v194, v194 row_half_mirror row_mask:0xf bank_mask:0xf bound_ctrl:1
	v_add_f32_dpp v195, v195, v195 row_half_mirror row_mask:0xf bank_mask:0xf bound_ctrl:1
	v_fmac_f32_e32 v186, v64, v16
	v_fmac_f32_e32 v187, v64, v17
	v_add_f32_dpp v194, v194, v194 row_mirror row_mask:0xf bank_mask:0xf bound_ctrl:1
	v_add_f32_dpp v195, v195, v195 row_mirror row_mask:0xf bank_mask:0xf bound_ctrl:1
	v_fmac_f32_e32 v188, v64, v18
	v_fmac_f32_e32 v189, v64, v19
	v_fmac_f32_e32 v190, v65, v16
	v_fmac_f32_e32 v191, v65, v17
	v_fmac_f32_e32 v192, v65, v18
	v_fmac_f32_e32 v193, v65, v19
	v_fmac_f32_e32 v186, v194, v12
	v_fmac_f32_e32 v187, v194, v13
	v_fmac_f32_e32 v188, v194, v14
	v_fmac_f32_e32 v189, v194, v15
	v_fmac_f32_e32 v190, v195, v12
	v_fmac_f32_e32 v191, v195, v13
	v_fmac_f32_e32 v192, v195, v14
	v_fmac_f32_e32 v193, v195, v15
	ds_read_b128 v[8:11], v152 offset:13824
	ds_read_b128 v[12:15], v152 offset:22016
	ds_read_b128 v[16:19], v152 offset:30208
	ds_read_b128 v[20:23], v152 offset:38400
	ds_read_b64 v[64:65], v69 offset:5632
	s_waitcnt lgkmcnt(11)
	v_mul_f32_e32 v194, v186, v28
	v_mul_f32_e32 v195, v190, v28
	v_mul_f32_e32 v238, v186, v40
	v_mul_f32_e32 v239, v190, v40
	v_fmac_f32_e32 v194, v187, v29
	v_fmac_f32_e32 v195, v191, v29
	v_fmac_f32_e32 v238, v187, v41
	v_fmac_f32_e32 v239, v191, v41
	v_fmac_f32_e32 v194, v188, v30
	v_fmac_f32_e32 v195, v192, v30
	v_fmac_f32_e32 v238, v188, v42
	v_fmac_f32_e32 v239, v192, v42
	v_fmac_f32_e32 v194, v189, v31
	v_fmac_f32_e32 v195, v193, v31
	v_fmac_f32_e32 v238, v189, v43
	v_fmac_f32_e32 v239, v193, v43
	v_add_f32_dpp v194, v194, v194 quad_perm:[1,0,3,2] row_mask:0xf bank_mask:0xf bound_ctrl:1
	v_add_f32_dpp v195, v195, v195 quad_perm:[1,0,3,2] row_mask:0xf bank_mask:0xf bound_ctrl:1
	v_add_f32_dpp v238, v238, v238 quad_perm:[1,0,3,2] row_mask:0xf bank_mask:0xf bound_ctrl:1
	v_add_f32_dpp v239, v239, v239 quad_perm:[1,0,3,2] row_mask:0xf bank_mask:0xf bound_ctrl:1
	v_add_f32_dpp v194, v194, v194 quad_perm:[2,3,0,1] row_mask:0xf bank_mask:0xf bound_ctrl:1
	v_add_f32_dpp v195, v195, v195 quad_perm:[2,3,0,1] row_mask:0xf bank_mask:0xf bound_ctrl:1
	v_add_f32_dpp v238, v238, v238 quad_perm:[2,3,0,1] row_mask:0xf bank_mask:0xf bound_ctrl:1
	v_add_f32_dpp v239, v239, v239 quad_perm:[2,3,0,1] row_mask:0xf bank_mask:0xf bound_ctrl:1
	v_add_f32_dpp v194, v194, v194 row_half_mirror row_mask:0xf bank_mask:0xf bound_ctrl:1
	v_add_f32_dpp v195, v195, v195 row_half_mirror row_mask:0xf bank_mask:0xf bound_ctrl:1
	v_fmac_f32_e32 v186, v66, v36
	v_fmac_f32_e32 v187, v66, v37
	v_add_f32_dpp v194, v194, v194 row_mirror row_mask:0xf bank_mask:0xf bound_ctrl:1
	v_add_f32_dpp v195, v195, v195 row_mirror row_mask:0xf bank_mask:0xf bound_ctrl:1
	v_fmac_f32_e32 v188, v66, v38
	v_fmac_f32_e32 v189, v66, v39
	v_fmac_f32_e32 v190, v67, v36
	v_fmac_f32_e32 v191, v67, v37
	v_fmac_f32_e32 v192, v67, v38
	v_fmac_f32_e32 v193, v67, v39
	v_fmac_f32_e32 v186, v194, v32
	v_fmac_f32_e32 v187, v194, v33
	v_fmac_f32_e32 v188, v194, v34
	v_fmac_f32_e32 v189, v194, v35
	v_fmac_f32_e32 v190, v195, v32
	v_fmac_f32_e32 v191, v195, v33
	v_fmac_f32_e32 v192, v195, v34
	v_fmac_f32_e32 v193, v195, v35
	s_mov_b64 exec, s[10:11]
	ds_write2st64_b64 v196, v[132:133], v[238:239] offset0:50 offset1:48
	s_mov_b64 exec, -1
	ds_read_b128 v[28:31], v152 offset:13568
	ds_read_b128 v[32:35], v152 offset:21760
	ds_read_b128 v[36:39], v152 offset:29952
	ds_read_b128 v[40:43], v152 offset:38144
	ds_read_b64 v[66:67], v69 offset:5376
	s_waitcnt lgkmcnt(11)
	v_mul_f32_e32 v194, v186, v48
	v_mul_f32_e32 v195, v190, v48
	v_mul_f32_e32 v132, v186, v60
	v_mul_f32_e32 v133, v190, v60
	v_fmac_f32_e32 v194, v187, v49
	v_fmac_f32_e32 v195, v191, v49
	v_fmac_f32_e32 v132, v187, v61
	v_fmac_f32_e32 v133, v191, v61
	v_fmac_f32_e32 v194, v188, v50
	v_fmac_f32_e32 v195, v192, v50
	v_fmac_f32_e32 v132, v188, v62
	v_fmac_f32_e32 v133, v192, v62
	v_fmac_f32_e32 v194, v189, v51
	v_fmac_f32_e32 v195, v193, v51
	v_fmac_f32_e32 v132, v189, v63
	v_fmac_f32_e32 v133, v193, v63
	v_add_f32_dpp v194, v194, v194 quad_perm:[1,0,3,2] row_mask:0xf bank_mask:0xf bound_ctrl:1
	v_add_f32_dpp v195, v195, v195 quad_perm:[1,0,3,2] row_mask:0xf bank_mask:0xf bound_ctrl:1
	v_add_f32_dpp v132, v132, v132 quad_perm:[1,0,3,2] row_mask:0xf bank_mask:0xf bound_ctrl:1
	v_add_f32_dpp v133, v133, v133 quad_perm:[1,0,3,2] row_mask:0xf bank_mask:0xf bound_ctrl:1
	v_add_f32_dpp v194, v194, v194 quad_perm:[2,3,0,1] row_mask:0xf bank_mask:0xf bound_ctrl:1
	v_add_f32_dpp v195, v195, v195 quad_perm:[2,3,0,1] row_mask:0xf bank_mask:0xf bound_ctrl:1
	v_add_f32_dpp v132, v132, v132 quad_perm:[2,3,0,1] row_mask:0xf bank_mask:0xf bound_ctrl:1
	v_add_f32_dpp v133, v133, v133 quad_perm:[2,3,0,1] row_mask:0xf bank_mask:0xf bound_ctrl:1
	v_add_f32_dpp v194, v194, v194 row_half_mirror row_mask:0xf bank_mask:0xf bound_ctrl:1
	v_add_f32_dpp v195, v195, v195 row_half_mirror row_mask:0xf bank_mask:0xf bound_ctrl:1
	v_fmac_f32_e32 v186, v130, v56
	v_fmac_f32_e32 v187, v130, v57
	v_add_f32_dpp v194, v194, v194 row_mirror row_mask:0xf bank_mask:0xf bound_ctrl:1
	v_add_f32_dpp v195, v195, v195 row_mirror row_mask:0xf bank_mask:0xf bound_ctrl:1
	v_fmac_f32_e32 v188, v130, v58
	v_fmac_f32_e32 v189, v130, v59
	v_fmac_f32_e32 v190, v131, v56
	v_fmac_f32_e32 v191, v131, v57
	v_fmac_f32_e32 v192, v131, v58
	v_fmac_f32_e32 v193, v131, v59
	v_fmac_f32_e32 v186, v194, v52
	v_fmac_f32_e32 v187, v194, v53
	v_fmac_f32_e32 v188, v194, v54
	v_fmac_f32_e32 v189, v194, v55
	v_fmac_f32_e32 v190, v195, v52
	v_fmac_f32_e32 v191, v195, v53
	v_fmac_f32_e32 v192, v195, v54
	v_fmac_f32_e32 v193, v195, v55
	ds_read_b128 v[48:51], v152 offset:13312
	ds_read_b128 v[52:55], v152 offset:21504
	ds_read_b128 v[56:59], v152 offset:29696
	ds_read_b128 v[60:63], v152 offset:37888
	ds_read_b64 v[130:131], v69 offset:5120
	s_waitcnt lgkmcnt(11)
	v_mul_f32_e32 v194, v186, v8
	v_mul_f32_e32 v195, v190, v8
	v_mul_f32_e32 v238, v186, v20
	v_mul_f32_e32 v239, v190, v20
	v_fmac_f32_e32 v194, v187, v9
	v_fmac_f32_e32 v195, v191, v9
	v_fmac_f32_e32 v238, v187, v21
	v_fmac_f32_e32 v239, v191, v21
	v_fmac_f32_e32 v194, v188, v10
	v_fmac_f32_e32 v195, v192, v10
	v_fmac_f32_e32 v238, v188, v22
	v_fmac_f32_e32 v239, v192, v22
	v_fmac_f32_e32 v194, v189, v11
	v_fmac_f32_e32 v195, v193, v11
	v_fmac_f32_e32 v238, v189, v23
	v_fmac_f32_e32 v239, v193, v23
	v_add_f32_dpp v194, v194, v194 quad_perm:[1,0,3,2] row_mask:0xf bank_mask:0xf bound_ctrl:1
	v_add_f32_dpp v195, v195, v195 quad_perm:[1,0,3,2] row_mask:0xf bank_mask:0xf bound_ctrl:1
	v_add_f32_dpp v238, v238, v238 quad_perm:[1,0,3,2] row_mask:0xf bank_mask:0xf bound_ctrl:1
	v_add_f32_dpp v239, v239, v239 quad_perm:[1,0,3,2] row_mask:0xf bank_mask:0xf bound_ctrl:1
	v_add_f32_dpp v194, v194, v194 quad_perm:[2,3,0,1] row_mask:0xf bank_mask:0xf bound_ctrl:1
	v_add_f32_dpp v195, v195, v195 quad_perm:[2,3,0,1] row_mask:0xf bank_mask:0xf bound_ctrl:1
	v_add_f32_dpp v238, v238, v238 quad_perm:[2,3,0,1] row_mask:0xf bank_mask:0xf bound_ctrl:1
	v_add_f32_dpp v239, v239, v239 quad_perm:[2,3,0,1] row_mask:0xf bank_mask:0xf bound_ctrl:1
	v_add_f32_dpp v194, v194, v194 row_half_mirror row_mask:0xf bank_mask:0xf bound_ctrl:1
	v_add_f32_dpp v195, v195, v195 row_half_mirror row_mask:0xf bank_mask:0xf bound_ctrl:1
	v_fmac_f32_e32 v186, v64, v16
	v_fmac_f32_e32 v187, v64, v17
	v_add_f32_dpp v194, v194, v194 row_mirror row_mask:0xf bank_mask:0xf bound_ctrl:1
	v_add_f32_dpp v195, v195, v195 row_mirror row_mask:0xf bank_mask:0xf bound_ctrl:1
	v_fmac_f32_e32 v188, v64, v18
	v_fmac_f32_e32 v189, v64, v19
	v_fmac_f32_e32 v190, v65, v16
	v_fmac_f32_e32 v191, v65, v17
	v_fmac_f32_e32 v192, v65, v18
	v_fmac_f32_e32 v193, v65, v19
	v_fmac_f32_e32 v186, v194, v12
	v_fmac_f32_e32 v187, v194, v13
	v_fmac_f32_e32 v188, v194, v14
	v_fmac_f32_e32 v189, v194, v15
	v_fmac_f32_e32 v190, v195, v12
	v_fmac_f32_e32 v191, v195, v13
	v_fmac_f32_e32 v192, v195, v14
	v_fmac_f32_e32 v193, v195, v15
	s_mov_b64 exec, s[10:11]
	ds_write2st64_b64 v196, v[132:133], v[238:239] offset0:46 offset1:44
	s_mov_b64 exec, -1
	ds_read_b128 v[8:11], v152 offset:13056
	ds_read_b128 v[12:15], v152 offset:21248
	ds_read_b128 v[16:19], v152 offset:29440
	ds_read_b128 v[20:23], v152 offset:37632
	ds_read_b64 v[64:65], v69 offset:4864
	s_waitcnt lgkmcnt(11)
	v_mul_f32_e32 v194, v186, v28
	v_mul_f32_e32 v195, v190, v28
	v_mul_f32_e32 v132, v186, v40
	v_mul_f32_e32 v133, v190, v40
	v_fmac_f32_e32 v194, v187, v29
	v_fmac_f32_e32 v195, v191, v29
	v_fmac_f32_e32 v132, v187, v41
	v_fmac_f32_e32 v133, v191, v41
	v_fmac_f32_e32 v194, v188, v30
	v_fmac_f32_e32 v195, v192, v30
	v_fmac_f32_e32 v132, v188, v42
	v_fmac_f32_e32 v133, v192, v42
	v_fmac_f32_e32 v194, v189, v31
	v_fmac_f32_e32 v195, v193, v31
	v_fmac_f32_e32 v132, v189, v43
	v_fmac_f32_e32 v133, v193, v43
	v_add_f32_dpp v194, v194, v194 quad_perm:[1,0,3,2] row_mask:0xf bank_mask:0xf bound_ctrl:1
	v_add_f32_dpp v195, v195, v195 quad_perm:[1,0,3,2] row_mask:0xf bank_mask:0xf bound_ctrl:1
	v_add_f32_dpp v132, v132, v132 quad_perm:[1,0,3,2] row_mask:0xf bank_mask:0xf bound_ctrl:1
	v_add_f32_dpp v133, v133, v133 quad_perm:[1,0,3,2] row_mask:0xf bank_mask:0xf bound_ctrl:1
	v_add_f32_dpp v194, v194, v194 quad_perm:[2,3,0,1] row_mask:0xf bank_mask:0xf bound_ctrl:1
	v_add_f32_dpp v195, v195, v195 quad_perm:[2,3,0,1] row_mask:0xf bank_mask:0xf bound_ctrl:1
	v_add_f32_dpp v132, v132, v132 quad_perm:[2,3,0,1] row_mask:0xf bank_mask:0xf bound_ctrl:1
	v_add_f32_dpp v133, v133, v133 quad_perm:[2,3,0,1] row_mask:0xf bank_mask:0xf bound_ctrl:1
	v_add_f32_dpp v194, v194, v194 row_half_mirror row_mask:0xf bank_mask:0xf bound_ctrl:1
	v_add_f32_dpp v195, v195, v195 row_half_mirror row_mask:0xf bank_mask:0xf bound_ctrl:1
	v_fmac_f32_e32 v186, v66, v36
	v_fmac_f32_e32 v187, v66, v37
	v_add_f32_dpp v194, v194, v194 row_mirror row_mask:0xf bank_mask:0xf bound_ctrl:1
	v_add_f32_dpp v195, v195, v195 row_mirror row_mask:0xf bank_mask:0xf bound_ctrl:1
	v_fmac_f32_e32 v188, v66, v38
	v_fmac_f32_e32 v189, v66, v39
	v_fmac_f32_e32 v190, v67, v36
	v_fmac_f32_e32 v191, v67, v37
	v_fmac_f32_e32 v192, v67, v38
	v_fmac_f32_e32 v193, v67, v39
	v_fmac_f32_e32 v186, v194, v32
	v_fmac_f32_e32 v187, v194, v33
	v_fmac_f32_e32 v188, v194, v34
	v_fmac_f32_e32 v189, v194, v35
	v_fmac_f32_e32 v190, v195, v32
	v_fmac_f32_e32 v191, v195, v33
	v_fmac_f32_e32 v192, v195, v34
	v_fmac_f32_e32 v193, v195, v35
	ds_read_b128 v[28:31], v152 offset:12800
	ds_read_b128 v[32:35], v152 offset:20992
	ds_read_b128 v[36:39], v152 offset:29184
	ds_read_b128 v[40:43], v152 offset:37376
	ds_read_b64 v[66:67], v69 offset:4608
	s_waitcnt lgkmcnt(11)
	v_mul_f32_e32 v194, v186, v48
	v_mul_f32_e32 v195, v190, v48
	v_mul_f32_e32 v238, v186, v60
	v_mul_f32_e32 v239, v190, v60
	v_fmac_f32_e32 v194, v187, v49
	v_fmac_f32_e32 v195, v191, v49
	v_fmac_f32_e32 v238, v187, v61
	v_fmac_f32_e32 v239, v191, v61
	v_fmac_f32_e32 v194, v188, v50
	v_fmac_f32_e32 v195, v192, v50
	v_fmac_f32_e32 v238, v188, v62
	v_fmac_f32_e32 v239, v192, v62
	v_fmac_f32_e32 v194, v189, v51
	v_fmac_f32_e32 v195, v193, v51
	v_fmac_f32_e32 v238, v189, v63
	v_fmac_f32_e32 v239, v193, v63
	v_add_f32_dpp v194, v194, v194 quad_perm:[1,0,3,2] row_mask:0xf bank_mask:0xf bound_ctrl:1
	v_add_f32_dpp v195, v195, v195 quad_perm:[1,0,3,2] row_mask:0xf bank_mask:0xf bound_ctrl:1
	v_add_f32_dpp v238, v238, v238 quad_perm:[1,0,3,2] row_mask:0xf bank_mask:0xf bound_ctrl:1
	v_add_f32_dpp v239, v239, v239 quad_perm:[1,0,3,2] row_mask:0xf bank_mask:0xf bound_ctrl:1
	v_add_f32_dpp v194, v194, v194 quad_perm:[2,3,0,1] row_mask:0xf bank_mask:0xf bound_ctrl:1
	v_add_f32_dpp v195, v195, v195 quad_perm:[2,3,0,1] row_mask:0xf bank_mask:0xf bound_ctrl:1
	v_add_f32_dpp v238, v238, v238 quad_perm:[2,3,0,1] row_mask:0xf bank_mask:0xf bound_ctrl:1
	v_add_f32_dpp v239, v239, v239 quad_perm:[2,3,0,1] row_mask:0xf bank_mask:0xf bound_ctrl:1
	v_add_f32_dpp v194, v194, v194 row_half_mirror row_mask:0xf bank_mask:0xf bound_ctrl:1
	v_add_f32_dpp v195, v195, v195 row_half_mirror row_mask:0xf bank_mask:0xf bound_ctrl:1
	v_fmac_f32_e32 v186, v130, v56
	v_fmac_f32_e32 v187, v130, v57
	v_add_f32_dpp v194, v194, v194 row_mirror row_mask:0xf bank_mask:0xf bound_ctrl:1
	v_add_f32_dpp v195, v195, v195 row_mirror row_mask:0xf bank_mask:0xf bound_ctrl:1
	v_fmac_f32_e32 v188, v130, v58
	v_fmac_f32_e32 v189, v130, v59
	v_fmac_f32_e32 v190, v131, v56
	v_fmac_f32_e32 v191, v131, v57
	v_fmac_f32_e32 v192, v131, v58
	v_fmac_f32_e32 v193, v131, v59
	v_fmac_f32_e32 v186, v194, v52
	v_fmac_f32_e32 v187, v194, v53
	v_fmac_f32_e32 v188, v194, v54
	v_fmac_f32_e32 v189, v194, v55
	v_fmac_f32_e32 v190, v195, v52
	v_fmac_f32_e32 v191, v195, v53
	v_fmac_f32_e32 v192, v195, v54
	v_fmac_f32_e32 v193, v195, v55
	s_mov_b64 exec, s[10:11]
	ds_write2st64_b64 v196, v[132:133], v[238:239] offset0:42 offset1:40
	s_mov_b64 exec, -1
	ds_read_b128 v[48:51], v152 offset:12544
	ds_read_b128 v[52:55], v152 offset:20736
	ds_read_b128 v[56:59], v152 offset:28928
	ds_read_b128 v[60:63], v152 offset:37120
	ds_read_b64 v[130:131], v69 offset:4352
	s_waitcnt lgkmcnt(11)
	v_mul_f32_e32 v194, v186, v8
	v_mul_f32_e32 v195, v190, v8
	v_mul_f32_e32 v132, v186, v20
	v_mul_f32_e32 v133, v190, v20
	v_fmac_f32_e32 v194, v187, v9
	v_fmac_f32_e32 v195, v191, v9
	v_fmac_f32_e32 v132, v187, v21
	v_fmac_f32_e32 v133, v191, v21
	v_fmac_f32_e32 v194, v188, v10
	v_fmac_f32_e32 v195, v192, v10
	v_fmac_f32_e32 v132, v188, v22
	v_fmac_f32_e32 v133, v192, v22
	v_fmac_f32_e32 v194, v189, v11
	v_fmac_f32_e32 v195, v193, v11
	v_fmac_f32_e32 v132, v189, v23
	v_fmac_f32_e32 v133, v193, v23
	v_add_f32_dpp v194, v194, v194 quad_perm:[1,0,3,2] row_mask:0xf bank_mask:0xf bound_ctrl:1
	v_add_f32_dpp v195, v195, v195 quad_perm:[1,0,3,2] row_mask:0xf bank_mask:0xf bound_ctrl:1
	v_add_f32_dpp v132, v132, v132 quad_perm:[1,0,3,2] row_mask:0xf bank_mask:0xf bound_ctrl:1
	v_add_f32_dpp v133, v133, v133 quad_perm:[1,0,3,2] row_mask:0xf bank_mask:0xf bound_ctrl:1
	v_add_f32_dpp v194, v194, v194 quad_perm:[2,3,0,1] row_mask:0xf bank_mask:0xf bound_ctrl:1
	v_add_f32_dpp v195, v195, v195 quad_perm:[2,3,0,1] row_mask:0xf bank_mask:0xf bound_ctrl:1
	v_add_f32_dpp v132, v132, v132 quad_perm:[2,3,0,1] row_mask:0xf bank_mask:0xf bound_ctrl:1
	v_add_f32_dpp v133, v133, v133 quad_perm:[2,3,0,1] row_mask:0xf bank_mask:0xf bound_ctrl:1
	v_add_f32_dpp v194, v194, v194 row_half_mirror row_mask:0xf bank_mask:0xf bound_ctrl:1
	v_add_f32_dpp v195, v195, v195 row_half_mirror row_mask:0xf bank_mask:0xf bound_ctrl:1
	v_fmac_f32_e32 v186, v64, v16
	v_fmac_f32_e32 v187, v64, v17
	v_add_f32_dpp v194, v194, v194 row_mirror row_mask:0xf bank_mask:0xf bound_ctrl:1
	v_add_f32_dpp v195, v195, v195 row_mirror row_mask:0xf bank_mask:0xf bound_ctrl:1
	v_fmac_f32_e32 v188, v64, v18
	v_fmac_f32_e32 v189, v64, v19
	v_fmac_f32_e32 v190, v65, v16
	v_fmac_f32_e32 v191, v65, v17
	v_fmac_f32_e32 v192, v65, v18
	v_fmac_f32_e32 v193, v65, v19
	v_fmac_f32_e32 v186, v194, v12
	v_fmac_f32_e32 v187, v194, v13
	v_fmac_f32_e32 v188, v194, v14
	v_fmac_f32_e32 v189, v194, v15
	v_fmac_f32_e32 v190, v195, v12
	v_fmac_f32_e32 v191, v195, v13
	v_fmac_f32_e32 v192, v195, v14
	v_fmac_f32_e32 v193, v195, v15
	ds_read_b128 v[8:11], v152 offset:12288
	ds_read_b128 v[12:15], v152 offset:20480
	ds_read_b128 v[16:19], v152 offset:28672
	ds_read_b128 v[20:23], v152 offset:36864
	ds_read_b64 v[64:65], v69 offset:4096
	s_waitcnt lgkmcnt(11)
	v_mul_f32_e32 v194, v186, v28
	v_mul_f32_e32 v195, v190, v28
	v_mul_f32_e32 v238, v186, v40
	v_mul_f32_e32 v239, v190, v40
	v_fmac_f32_e32 v194, v187, v29
	v_fmac_f32_e32 v195, v191, v29
	v_fmac_f32_e32 v238, v187, v41
	v_fmac_f32_e32 v239, v191, v41
	v_fmac_f32_e32 v194, v188, v30
	v_fmac_f32_e32 v195, v192, v30
	v_fmac_f32_e32 v238, v188, v42
	v_fmac_f32_e32 v239, v192, v42
	v_fmac_f32_e32 v194, v189, v31
	v_fmac_f32_e32 v195, v193, v31
	v_fmac_f32_e32 v238, v189, v43
	v_fmac_f32_e32 v239, v193, v43
	v_add_f32_dpp v194, v194, v194 quad_perm:[1,0,3,2] row_mask:0xf bank_mask:0xf bound_ctrl:1
	v_add_f32_dpp v195, v195, v195 quad_perm:[1,0,3,2] row_mask:0xf bank_mask:0xf bound_ctrl:1
	v_add_f32_dpp v238, v238, v238 quad_perm:[1,0,3,2] row_mask:0xf bank_mask:0xf bound_ctrl:1
	v_add_f32_dpp v239, v239, v239 quad_perm:[1,0,3,2] row_mask:0xf bank_mask:0xf bound_ctrl:1
	v_add_f32_dpp v194, v194, v194 quad_perm:[2,3,0,1] row_mask:0xf bank_mask:0xf bound_ctrl:1
	v_add_f32_dpp v195, v195, v195 quad_perm:[2,3,0,1] row_mask:0xf bank_mask:0xf bound_ctrl:1
	v_add_f32_dpp v238, v238, v238 quad_perm:[2,3,0,1] row_mask:0xf bank_mask:0xf bound_ctrl:1
	v_add_f32_dpp v239, v239, v239 quad_perm:[2,3,0,1] row_mask:0xf bank_mask:0xf bound_ctrl:1
	v_add_f32_dpp v194, v194, v194 row_half_mirror row_mask:0xf bank_mask:0xf bound_ctrl:1
	v_add_f32_dpp v195, v195, v195 row_half_mirror row_mask:0xf bank_mask:0xf bound_ctrl:1
	v_fmac_f32_e32 v186, v66, v36
	v_fmac_f32_e32 v187, v66, v37
	v_add_f32_dpp v194, v194, v194 row_mirror row_mask:0xf bank_mask:0xf bound_ctrl:1
	v_add_f32_dpp v195, v195, v195 row_mirror row_mask:0xf bank_mask:0xf bound_ctrl:1
	v_fmac_f32_e32 v188, v66, v38
	v_fmac_f32_e32 v189, v66, v39
	v_fmac_f32_e32 v190, v67, v36
	v_fmac_f32_e32 v191, v67, v37
	v_fmac_f32_e32 v192, v67, v38
	v_fmac_f32_e32 v193, v67, v39
	v_fmac_f32_e32 v186, v194, v32
	v_fmac_f32_e32 v187, v194, v33
	v_fmac_f32_e32 v188, v194, v34
	v_fmac_f32_e32 v189, v194, v35
	v_fmac_f32_e32 v190, v195, v32
	v_fmac_f32_e32 v191, v195, v33
	v_fmac_f32_e32 v192, v195, v34
	v_fmac_f32_e32 v193, v195, v35
	s_mov_b64 exec, s[10:11]
	ds_write2st64_b64 v196, v[132:133], v[238:239] offset0:38 offset1:36
	s_mov_b64 exec, -1
	ds_read_b128 v[28:31], v152 offset:12032
	ds_read_b128 v[32:35], v152 offset:20224
	ds_read_b128 v[36:39], v152 offset:28416
	ds_read_b128 v[40:43], v152 offset:36608
	ds_read_b64 v[66:67], v69 offset:3840
	s_waitcnt lgkmcnt(11)
	v_mul_f32_e32 v194, v186, v48
	v_mul_f32_e32 v195, v190, v48
	v_mul_f32_e32 v132, v186, v60
	v_mul_f32_e32 v133, v190, v60
	v_fmac_f32_e32 v194, v187, v49
	v_fmac_f32_e32 v195, v191, v49
	v_fmac_f32_e32 v132, v187, v61
	v_fmac_f32_e32 v133, v191, v61
	v_fmac_f32_e32 v194, v188, v50
	v_fmac_f32_e32 v195, v192, v50
	v_fmac_f32_e32 v132, v188, v62
	v_fmac_f32_e32 v133, v192, v62
	v_fmac_f32_e32 v194, v189, v51
	v_fmac_f32_e32 v195, v193, v51
	v_fmac_f32_e32 v132, v189, v63
	v_fmac_f32_e32 v133, v193, v63
	v_add_f32_dpp v194, v194, v194 quad_perm:[1,0,3,2] row_mask:0xf bank_mask:0xf bound_ctrl:1
	v_add_f32_dpp v195, v195, v195 quad_perm:[1,0,3,2] row_mask:0xf bank_mask:0xf bound_ctrl:1
	v_add_f32_dpp v132, v132, v132 quad_perm:[1,0,3,2] row_mask:0xf bank_mask:0xf bound_ctrl:1
	v_add_f32_dpp v133, v133, v133 quad_perm:[1,0,3,2] row_mask:0xf bank_mask:0xf bound_ctrl:1
	v_add_f32_dpp v194, v194, v194 quad_perm:[2,3,0,1] row_mask:0xf bank_mask:0xf bound_ctrl:1
	v_add_f32_dpp v195, v195, v195 quad_perm:[2,3,0,1] row_mask:0xf bank_mask:0xf bound_ctrl:1
	v_add_f32_dpp v132, v132, v132 quad_perm:[2,3,0,1] row_mask:0xf bank_mask:0xf bound_ctrl:1
	v_add_f32_dpp v133, v133, v133 quad_perm:[2,3,0,1] row_mask:0xf bank_mask:0xf bound_ctrl:1
	v_add_f32_dpp v194, v194, v194 row_half_mirror row_mask:0xf bank_mask:0xf bound_ctrl:1
	v_add_f32_dpp v195, v195, v195 row_half_mirror row_mask:0xf bank_mask:0xf bound_ctrl:1
	v_fmac_f32_e32 v186, v130, v56
	v_fmac_f32_e32 v187, v130, v57
	v_add_f32_dpp v194, v194, v194 row_mirror row_mask:0xf bank_mask:0xf bound_ctrl:1
	v_add_f32_dpp v195, v195, v195 row_mirror row_mask:0xf bank_mask:0xf bound_ctrl:1
	v_fmac_f32_e32 v188, v130, v58
	v_fmac_f32_e32 v189, v130, v59
	v_fmac_f32_e32 v190, v131, v56
	v_fmac_f32_e32 v191, v131, v57
	v_fmac_f32_e32 v192, v131, v58
	v_fmac_f32_e32 v193, v131, v59
	v_fmac_f32_e32 v186, v194, v52
	v_fmac_f32_e32 v187, v194, v53
	v_fmac_f32_e32 v188, v194, v54
	v_fmac_f32_e32 v189, v194, v55
	v_fmac_f32_e32 v190, v195, v52
	v_fmac_f32_e32 v191, v195, v53
	v_fmac_f32_e32 v192, v195, v54
	v_fmac_f32_e32 v193, v195, v55
	ds_read_b128 v[48:51], v152 offset:11776
	ds_read_b128 v[52:55], v152 offset:19968
	ds_read_b128 v[56:59], v152 offset:28160
	ds_read_b128 v[60:63], v152 offset:36352
	ds_read_b64 v[130:131], v69 offset:3584
	s_waitcnt lgkmcnt(11)
	v_mul_f32_e32 v194, v186, v8
	v_mul_f32_e32 v195, v190, v8
	v_mul_f32_e32 v238, v186, v20
	v_mul_f32_e32 v239, v190, v20
	v_fmac_f32_e32 v194, v187, v9
	v_fmac_f32_e32 v195, v191, v9
	v_fmac_f32_e32 v238, v187, v21
	v_fmac_f32_e32 v239, v191, v21
	v_fmac_f32_e32 v194, v188, v10
	v_fmac_f32_e32 v195, v192, v10
	v_fmac_f32_e32 v238, v188, v22
	v_fmac_f32_e32 v239, v192, v22
	v_fmac_f32_e32 v194, v189, v11
	v_fmac_f32_e32 v195, v193, v11
	v_fmac_f32_e32 v238, v189, v23
	v_fmac_f32_e32 v239, v193, v23
	v_add_f32_dpp v194, v194, v194 quad_perm:[1,0,3,2] row_mask:0xf bank_mask:0xf bound_ctrl:1
	v_add_f32_dpp v195, v195, v195 quad_perm:[1,0,3,2] row_mask:0xf bank_mask:0xf bound_ctrl:1
	v_add_f32_dpp v238, v238, v238 quad_perm:[1,0,3,2] row_mask:0xf bank_mask:0xf bound_ctrl:1
	v_add_f32_dpp v239, v239, v239 quad_perm:[1,0,3,2] row_mask:0xf bank_mask:0xf bound_ctrl:1
	v_add_f32_dpp v194, v194, v194 quad_perm:[2,3,0,1] row_mask:0xf bank_mask:0xf bound_ctrl:1
	v_add_f32_dpp v195, v195, v195 quad_perm:[2,3,0,1] row_mask:0xf bank_mask:0xf bound_ctrl:1
	v_add_f32_dpp v238, v238, v238 quad_perm:[2,3,0,1] row_mask:0xf bank_mask:0xf bound_ctrl:1
	v_add_f32_dpp v239, v239, v239 quad_perm:[2,3,0,1] row_mask:0xf bank_mask:0xf bound_ctrl:1
	v_add_f32_dpp v194, v194, v194 row_half_mirror row_mask:0xf bank_mask:0xf bound_ctrl:1
	v_add_f32_dpp v195, v195, v195 row_half_mirror row_mask:0xf bank_mask:0xf bound_ctrl:1
	v_fmac_f32_e32 v186, v64, v16
	v_fmac_f32_e32 v187, v64, v17
	v_add_f32_dpp v194, v194, v194 row_mirror row_mask:0xf bank_mask:0xf bound_ctrl:1
	v_add_f32_dpp v195, v195, v195 row_mirror row_mask:0xf bank_mask:0xf bound_ctrl:1
	v_fmac_f32_e32 v188, v64, v18
	v_fmac_f32_e32 v189, v64, v19
	v_fmac_f32_e32 v190, v65, v16
	v_fmac_f32_e32 v191, v65, v17
	v_fmac_f32_e32 v192, v65, v18
	v_fmac_f32_e32 v193, v65, v19
	v_fmac_f32_e32 v186, v194, v12
	v_fmac_f32_e32 v187, v194, v13
	v_fmac_f32_e32 v188, v194, v14
	v_fmac_f32_e32 v189, v194, v15
	v_fmac_f32_e32 v190, v195, v12
	v_fmac_f32_e32 v191, v195, v13
	v_fmac_f32_e32 v192, v195, v14
	v_fmac_f32_e32 v193, v195, v15
	s_mov_b64 exec, s[10:11]
	ds_write2st64_b64 v196, v[132:133], v[238:239] offset0:34 offset1:32
	s_mov_b64 exec, -1
	ds_read_b128 v[8:11], v152 offset:11520
	ds_read_b128 v[12:15], v152 offset:19712
	ds_read_b128 v[16:19], v152 offset:27904
	ds_read_b128 v[20:23], v152 offset:36096
	ds_read_b64 v[64:65], v69 offset:3328
	s_waitcnt lgkmcnt(11)
	v_mul_f32_e32 v194, v186, v28
	v_mul_f32_e32 v195, v190, v28
	v_mul_f32_e32 v132, v186, v40
	v_mul_f32_e32 v133, v190, v40
	v_fmac_f32_e32 v194, v187, v29
	v_fmac_f32_e32 v195, v191, v29
	v_fmac_f32_e32 v132, v187, v41
	v_fmac_f32_e32 v133, v191, v41
	v_fmac_f32_e32 v194, v188, v30
	v_fmac_f32_e32 v195, v192, v30
	v_fmac_f32_e32 v132, v188, v42
	v_fmac_f32_e32 v133, v192, v42
	v_fmac_f32_e32 v194, v189, v31
	v_fmac_f32_e32 v195, v193, v31
	v_fmac_f32_e32 v132, v189, v43
	v_fmac_f32_e32 v133, v193, v43
	v_add_f32_dpp v194, v194, v194 quad_perm:[1,0,3,2] row_mask:0xf bank_mask:0xf bound_ctrl:1
	v_add_f32_dpp v195, v195, v195 quad_perm:[1,0,3,2] row_mask:0xf bank_mask:0xf bound_ctrl:1
	v_add_f32_dpp v132, v132, v132 quad_perm:[1,0,3,2] row_mask:0xf bank_mask:0xf bound_ctrl:1
	v_add_f32_dpp v133, v133, v133 quad_perm:[1,0,3,2] row_mask:0xf bank_mask:0xf bound_ctrl:1
	v_add_f32_dpp v194, v194, v194 quad_perm:[2,3,0,1] row_mask:0xf bank_mask:0xf bound_ctrl:1
	v_add_f32_dpp v195, v195, v195 quad_perm:[2,3,0,1] row_mask:0xf bank_mask:0xf bound_ctrl:1
	v_add_f32_dpp v132, v132, v132 quad_perm:[2,3,0,1] row_mask:0xf bank_mask:0xf bound_ctrl:1
	v_add_f32_dpp v133, v133, v133 quad_perm:[2,3,0,1] row_mask:0xf bank_mask:0xf bound_ctrl:1
	v_add_f32_dpp v194, v194, v194 row_half_mirror row_mask:0xf bank_mask:0xf bound_ctrl:1
	v_add_f32_dpp v195, v195, v195 row_half_mirror row_mask:0xf bank_mask:0xf bound_ctrl:1
	v_fmac_f32_e32 v186, v66, v36
	v_fmac_f32_e32 v187, v66, v37
	v_add_f32_dpp v194, v194, v194 row_mirror row_mask:0xf bank_mask:0xf bound_ctrl:1
	v_add_f32_dpp v195, v195, v195 row_mirror row_mask:0xf bank_mask:0xf bound_ctrl:1
	v_fmac_f32_e32 v188, v66, v38
	v_fmac_f32_e32 v189, v66, v39
	v_fmac_f32_e32 v190, v67, v36
	v_fmac_f32_e32 v191, v67, v37
	v_fmac_f32_e32 v192, v67, v38
	v_fmac_f32_e32 v193, v67, v39
	v_fmac_f32_e32 v186, v194, v32
	v_fmac_f32_e32 v187, v194, v33
	v_fmac_f32_e32 v188, v194, v34
	v_fmac_f32_e32 v189, v194, v35
	v_fmac_f32_e32 v190, v195, v32
	v_fmac_f32_e32 v191, v195, v33
	v_fmac_f32_e32 v192, v195, v34
	v_fmac_f32_e32 v193, v195, v35
	ds_read_b128 v[28:31], v152 offset:11264
	ds_read_b128 v[32:35], v152 offset:19456
	ds_read_b128 v[36:39], v152 offset:27648
	ds_read_b128 v[40:43], v152 offset:35840
	ds_read_b64 v[66:67], v69 offset:3072
	s_waitcnt lgkmcnt(11)
	v_mul_f32_e32 v194, v186, v48
	v_mul_f32_e32 v195, v190, v48
	v_mul_f32_e32 v238, v186, v60
	v_mul_f32_e32 v239, v190, v60
	v_fmac_f32_e32 v194, v187, v49
	v_fmac_f32_e32 v195, v191, v49
	v_fmac_f32_e32 v238, v187, v61
	v_fmac_f32_e32 v239, v191, v61
	v_fmac_f32_e32 v194, v188, v50
	v_fmac_f32_e32 v195, v192, v50
	v_fmac_f32_e32 v238, v188, v62
	v_fmac_f32_e32 v239, v192, v62
	v_fmac_f32_e32 v194, v189, v51
	v_fmac_f32_e32 v195, v193, v51
	v_fmac_f32_e32 v238, v189, v63
	v_fmac_f32_e32 v239, v193, v63
	v_add_f32_dpp v194, v194, v194 quad_perm:[1,0,3,2] row_mask:0xf bank_mask:0xf bound_ctrl:1
	v_add_f32_dpp v195, v195, v195 quad_perm:[1,0,3,2] row_mask:0xf bank_mask:0xf bound_ctrl:1
	v_add_f32_dpp v238, v238, v238 quad_perm:[1,0,3,2] row_mask:0xf bank_mask:0xf bound_ctrl:1
	v_add_f32_dpp v239, v239, v239 quad_perm:[1,0,3,2] row_mask:0xf bank_mask:0xf bound_ctrl:1
	v_add_f32_dpp v194, v194, v194 quad_perm:[2,3,0,1] row_mask:0xf bank_mask:0xf bound_ctrl:1
	v_add_f32_dpp v195, v195, v195 quad_perm:[2,3,0,1] row_mask:0xf bank_mask:0xf bound_ctrl:1
	v_add_f32_dpp v238, v238, v238 quad_perm:[2,3,0,1] row_mask:0xf bank_mask:0xf bound_ctrl:1
	v_add_f32_dpp v239, v239, v239 quad_perm:[2,3,0,1] row_mask:0xf bank_mask:0xf bound_ctrl:1
	v_add_f32_dpp v194, v194, v194 row_half_mirror row_mask:0xf bank_mask:0xf bound_ctrl:1
	v_add_f32_dpp v195, v195, v195 row_half_mirror row_mask:0xf bank_mask:0xf bound_ctrl:1
	v_fmac_f32_e32 v186, v130, v56
	v_fmac_f32_e32 v187, v130, v57
	v_add_f32_dpp v194, v194, v194 row_mirror row_mask:0xf bank_mask:0xf bound_ctrl:1
	v_add_f32_dpp v195, v195, v195 row_mirror row_mask:0xf bank_mask:0xf bound_ctrl:1
	v_fmac_f32_e32 v188, v130, v58
	v_fmac_f32_e32 v189, v130, v59
	v_fmac_f32_e32 v190, v131, v56
	v_fmac_f32_e32 v191, v131, v57
	v_fmac_f32_e32 v192, v131, v58
	v_fmac_f32_e32 v193, v131, v59
	v_fmac_f32_e32 v186, v194, v52
	v_fmac_f32_e32 v187, v194, v53
	v_fmac_f32_e32 v188, v194, v54
	v_fmac_f32_e32 v189, v194, v55
	v_fmac_f32_e32 v190, v195, v52
	v_fmac_f32_e32 v191, v195, v53
	v_fmac_f32_e32 v192, v195, v54
	v_fmac_f32_e32 v193, v195, v55
	s_mov_b64 exec, s[10:11]
	ds_write2st64_b64 v196, v[132:133], v[238:239] offset0:30 offset1:28
	s_mov_b64 exec, -1
	ds_read_b128 v[48:51], v152 offset:11008
	ds_read_b128 v[52:55], v152 offset:19200
	ds_read_b128 v[56:59], v152 offset:27392
	ds_read_b128 v[60:63], v152 offset:35584
	ds_read_b64 v[130:131], v69 offset:2816
	s_waitcnt lgkmcnt(11)
	v_mul_f32_e32 v194, v186, v8
	v_mul_f32_e32 v195, v190, v8
	v_mul_f32_e32 v132, v186, v20
	v_mul_f32_e32 v133, v190, v20
	v_fmac_f32_e32 v194, v187, v9
	v_fmac_f32_e32 v195, v191, v9
	v_fmac_f32_e32 v132, v187, v21
	v_fmac_f32_e32 v133, v191, v21
	v_fmac_f32_e32 v194, v188, v10
	v_fmac_f32_e32 v195, v192, v10
	v_fmac_f32_e32 v132, v188, v22
	v_fmac_f32_e32 v133, v192, v22
	v_fmac_f32_e32 v194, v189, v11
	v_fmac_f32_e32 v195, v193, v11
	v_fmac_f32_e32 v132, v189, v23
	v_fmac_f32_e32 v133, v193, v23
	v_add_f32_dpp v194, v194, v194 quad_perm:[1,0,3,2] row_mask:0xf bank_mask:0xf bound_ctrl:1
	v_add_f32_dpp v195, v195, v195 quad_perm:[1,0,3,2] row_mask:0xf bank_mask:0xf bound_ctrl:1
	v_add_f32_dpp v132, v132, v132 quad_perm:[1,0,3,2] row_mask:0xf bank_mask:0xf bound_ctrl:1
	v_add_f32_dpp v133, v133, v133 quad_perm:[1,0,3,2] row_mask:0xf bank_mask:0xf bound_ctrl:1
	v_add_f32_dpp v194, v194, v194 quad_perm:[2,3,0,1] row_mask:0xf bank_mask:0xf bound_ctrl:1
	v_add_f32_dpp v195, v195, v195 quad_perm:[2,3,0,1] row_mask:0xf bank_mask:0xf bound_ctrl:1
	v_add_f32_dpp v132, v132, v132 quad_perm:[2,3,0,1] row_mask:0xf bank_mask:0xf bound_ctrl:1
	v_add_f32_dpp v133, v133, v133 quad_perm:[2,3,0,1] row_mask:0xf bank_mask:0xf bound_ctrl:1
	v_add_f32_dpp v194, v194, v194 row_half_mirror row_mask:0xf bank_mask:0xf bound_ctrl:1
	v_add_f32_dpp v195, v195, v195 row_half_mirror row_mask:0xf bank_mask:0xf bound_ctrl:1
	v_fmac_f32_e32 v186, v64, v16
	v_fmac_f32_e32 v187, v64, v17
	v_add_f32_dpp v194, v194, v194 row_mirror row_mask:0xf bank_mask:0xf bound_ctrl:1
	v_add_f32_dpp v195, v195, v195 row_mirror row_mask:0xf bank_mask:0xf bound_ctrl:1
	v_fmac_f32_e32 v188, v64, v18
	v_fmac_f32_e32 v189, v64, v19
	v_fmac_f32_e32 v190, v65, v16
	v_fmac_f32_e32 v191, v65, v17
	v_fmac_f32_e32 v192, v65, v18
	v_fmac_f32_e32 v193, v65, v19
	v_fmac_f32_e32 v186, v194, v12
	v_fmac_f32_e32 v187, v194, v13
	v_fmac_f32_e32 v188, v194, v14
	v_fmac_f32_e32 v189, v194, v15
	v_fmac_f32_e32 v190, v195, v12
	v_fmac_f32_e32 v191, v195, v13
	v_fmac_f32_e32 v192, v195, v14
	v_fmac_f32_e32 v193, v195, v15
	ds_read_b128 v[8:11], v152 offset:10752
	ds_read_b128 v[12:15], v152 offset:18944
	ds_read_b128 v[16:19], v152 offset:27136
	ds_read_b128 v[20:23], v152 offset:35328
	ds_read_b64 v[64:65], v69 offset:2560
	s_waitcnt lgkmcnt(11)
	v_mul_f32_e32 v194, v186, v28
	v_mul_f32_e32 v195, v190, v28
	v_mul_f32_e32 v238, v186, v40
	v_mul_f32_e32 v239, v190, v40
	v_fmac_f32_e32 v194, v187, v29
	v_fmac_f32_e32 v195, v191, v29
	v_fmac_f32_e32 v238, v187, v41
	v_fmac_f32_e32 v239, v191, v41
	v_fmac_f32_e32 v194, v188, v30
	v_fmac_f32_e32 v195, v192, v30
	v_fmac_f32_e32 v238, v188, v42
	v_fmac_f32_e32 v239, v192, v42
	v_fmac_f32_e32 v194, v189, v31
	v_fmac_f32_e32 v195, v193, v31
	v_fmac_f32_e32 v238, v189, v43
	v_fmac_f32_e32 v239, v193, v43
	v_add_f32_dpp v194, v194, v194 quad_perm:[1,0,3,2] row_mask:0xf bank_mask:0xf bound_ctrl:1
	v_add_f32_dpp v195, v195, v195 quad_perm:[1,0,3,2] row_mask:0xf bank_mask:0xf bound_ctrl:1
	v_add_f32_dpp v238, v238, v238 quad_perm:[1,0,3,2] row_mask:0xf bank_mask:0xf bound_ctrl:1
	v_add_f32_dpp v239, v239, v239 quad_perm:[1,0,3,2] row_mask:0xf bank_mask:0xf bound_ctrl:1
	v_add_f32_dpp v194, v194, v194 quad_perm:[2,3,0,1] row_mask:0xf bank_mask:0xf bound_ctrl:1
	v_add_f32_dpp v195, v195, v195 quad_perm:[2,3,0,1] row_mask:0xf bank_mask:0xf bound_ctrl:1
	v_add_f32_dpp v238, v238, v238 quad_perm:[2,3,0,1] row_mask:0xf bank_mask:0xf bound_ctrl:1
	v_add_f32_dpp v239, v239, v239 quad_perm:[2,3,0,1] row_mask:0xf bank_mask:0xf bound_ctrl:1
	v_add_f32_dpp v194, v194, v194 row_half_mirror row_mask:0xf bank_mask:0xf bound_ctrl:1
	v_add_f32_dpp v195, v195, v195 row_half_mirror row_mask:0xf bank_mask:0xf bound_ctrl:1
	v_fmac_f32_e32 v186, v66, v36
	v_fmac_f32_e32 v187, v66, v37
	v_add_f32_dpp v194, v194, v194 row_mirror row_mask:0xf bank_mask:0xf bound_ctrl:1
	v_add_f32_dpp v195, v195, v195 row_mirror row_mask:0xf bank_mask:0xf bound_ctrl:1
	v_fmac_f32_e32 v188, v66, v38
	v_fmac_f32_e32 v189, v66, v39
	v_fmac_f32_e32 v190, v67, v36
	v_fmac_f32_e32 v191, v67, v37
	v_fmac_f32_e32 v192, v67, v38
	v_fmac_f32_e32 v193, v67, v39
	v_fmac_f32_e32 v186, v194, v32
	v_fmac_f32_e32 v187, v194, v33
	v_fmac_f32_e32 v188, v194, v34
	v_fmac_f32_e32 v189, v194, v35
	v_fmac_f32_e32 v190, v195, v32
	v_fmac_f32_e32 v191, v195, v33
	v_fmac_f32_e32 v192, v195, v34
	v_fmac_f32_e32 v193, v195, v35
	s_mov_b64 exec, s[10:11]
	ds_write2st64_b64 v196, v[132:133], v[238:239] offset0:26 offset1:24
	s_mov_b64 exec, -1
	ds_read_b128 v[28:31], v152 offset:10496
	ds_read_b128 v[32:35], v152 offset:18688
	ds_read_b128 v[36:39], v152 offset:26880
	ds_read_b128 v[40:43], v152 offset:35072
	ds_read_b64 v[66:67], v69 offset:2304
	s_waitcnt lgkmcnt(11)
	v_mul_f32_e32 v194, v186, v48
	v_mul_f32_e32 v195, v190, v48
	v_mul_f32_e32 v132, v186, v60
	v_mul_f32_e32 v133, v190, v60
	v_fmac_f32_e32 v194, v187, v49
	v_fmac_f32_e32 v195, v191, v49
	v_fmac_f32_e32 v132, v187, v61
	v_fmac_f32_e32 v133, v191, v61
	v_fmac_f32_e32 v194, v188, v50
	v_fmac_f32_e32 v195, v192, v50
	v_fmac_f32_e32 v132, v188, v62
	v_fmac_f32_e32 v133, v192, v62
	v_fmac_f32_e32 v194, v189, v51
	v_fmac_f32_e32 v195, v193, v51
	v_fmac_f32_e32 v132, v189, v63
	v_fmac_f32_e32 v133, v193, v63
	v_add_f32_dpp v194, v194, v194 quad_perm:[1,0,3,2] row_mask:0xf bank_mask:0xf bound_ctrl:1
	v_add_f32_dpp v195, v195, v195 quad_perm:[1,0,3,2] row_mask:0xf bank_mask:0xf bound_ctrl:1
	v_add_f32_dpp v132, v132, v132 quad_perm:[1,0,3,2] row_mask:0xf bank_mask:0xf bound_ctrl:1
	v_add_f32_dpp v133, v133, v133 quad_perm:[1,0,3,2] row_mask:0xf bank_mask:0xf bound_ctrl:1
	v_add_f32_dpp v194, v194, v194 quad_perm:[2,3,0,1] row_mask:0xf bank_mask:0xf bound_ctrl:1
	v_add_f32_dpp v195, v195, v195 quad_perm:[2,3,0,1] row_mask:0xf bank_mask:0xf bound_ctrl:1
	v_add_f32_dpp v132, v132, v132 quad_perm:[2,3,0,1] row_mask:0xf bank_mask:0xf bound_ctrl:1
	v_add_f32_dpp v133, v133, v133 quad_perm:[2,3,0,1] row_mask:0xf bank_mask:0xf bound_ctrl:1
	v_add_f32_dpp v194, v194, v194 row_half_mirror row_mask:0xf bank_mask:0xf bound_ctrl:1
	v_add_f32_dpp v195, v195, v195 row_half_mirror row_mask:0xf bank_mask:0xf bound_ctrl:1
	v_fmac_f32_e32 v186, v130, v56
	v_fmac_f32_e32 v187, v130, v57
	v_add_f32_dpp v194, v194, v194 row_mirror row_mask:0xf bank_mask:0xf bound_ctrl:1
	v_add_f32_dpp v195, v195, v195 row_mirror row_mask:0xf bank_mask:0xf bound_ctrl:1
	v_fmac_f32_e32 v188, v130, v58
	v_fmac_f32_e32 v189, v130, v59
	v_fmac_f32_e32 v190, v131, v56
	v_fmac_f32_e32 v191, v131, v57
	v_fmac_f32_e32 v192, v131, v58
	v_fmac_f32_e32 v193, v131, v59
	v_fmac_f32_e32 v186, v194, v52
	v_fmac_f32_e32 v187, v194, v53
	v_fmac_f32_e32 v188, v194, v54
	v_fmac_f32_e32 v189, v194, v55
	v_fmac_f32_e32 v190, v195, v52
	v_fmac_f32_e32 v191, v195, v53
	v_fmac_f32_e32 v192, v195, v54
	v_fmac_f32_e32 v193, v195, v55
	ds_read_b128 v[48:51], v152 offset:10240
	ds_read_b128 v[52:55], v152 offset:18432
	ds_read_b128 v[56:59], v152 offset:26624
	ds_read_b128 v[60:63], v152 offset:34816
	ds_read_b64 v[130:131], v69 offset:2048
	s_waitcnt lgkmcnt(11)
	v_mul_f32_e32 v194, v186, v8
	v_mul_f32_e32 v195, v190, v8
	v_mul_f32_e32 v238, v186, v20
	v_mul_f32_e32 v239, v190, v20
	v_fmac_f32_e32 v194, v187, v9
	v_fmac_f32_e32 v195, v191, v9
	v_fmac_f32_e32 v238, v187, v21
	v_fmac_f32_e32 v239, v191, v21
	v_fmac_f32_e32 v194, v188, v10
	v_fmac_f32_e32 v195, v192, v10
	v_fmac_f32_e32 v238, v188, v22
	v_fmac_f32_e32 v239, v192, v22
	v_fmac_f32_e32 v194, v189, v11
	v_fmac_f32_e32 v195, v193, v11
	v_fmac_f32_e32 v238, v189, v23
	v_fmac_f32_e32 v239, v193, v23
	v_add_f32_dpp v194, v194, v194 quad_perm:[1,0,3,2] row_mask:0xf bank_mask:0xf bound_ctrl:1
	v_add_f32_dpp v195, v195, v195 quad_perm:[1,0,3,2] row_mask:0xf bank_mask:0xf bound_ctrl:1
	v_add_f32_dpp v238, v238, v238 quad_perm:[1,0,3,2] row_mask:0xf bank_mask:0xf bound_ctrl:1
	v_add_f32_dpp v239, v239, v239 quad_perm:[1,0,3,2] row_mask:0xf bank_mask:0xf bound_ctrl:1
	v_add_f32_dpp v194, v194, v194 quad_perm:[2,3,0,1] row_mask:0xf bank_mask:0xf bound_ctrl:1
	v_add_f32_dpp v195, v195, v195 quad_perm:[2,3,0,1] row_mask:0xf bank_mask:0xf bound_ctrl:1
	v_add_f32_dpp v238, v238, v238 quad_perm:[2,3,0,1] row_mask:0xf bank_mask:0xf bound_ctrl:1
	v_add_f32_dpp v239, v239, v239 quad_perm:[2,3,0,1] row_mask:0xf bank_mask:0xf bound_ctrl:1
	v_add_f32_dpp v194, v194, v194 row_half_mirror row_mask:0xf bank_mask:0xf bound_ctrl:1
	v_add_f32_dpp v195, v195, v195 row_half_mirror row_mask:0xf bank_mask:0xf bound_ctrl:1
	v_fmac_f32_e32 v186, v64, v16
	v_fmac_f32_e32 v187, v64, v17
	v_add_f32_dpp v194, v194, v194 row_mirror row_mask:0xf bank_mask:0xf bound_ctrl:1
	v_add_f32_dpp v195, v195, v195 row_mirror row_mask:0xf bank_mask:0xf bound_ctrl:1
	v_fmac_f32_e32 v188, v64, v18
	v_fmac_f32_e32 v189, v64, v19
	v_fmac_f32_e32 v190, v65, v16
	v_fmac_f32_e32 v191, v65, v17
	v_fmac_f32_e32 v192, v65, v18
	v_fmac_f32_e32 v193, v65, v19
	v_fmac_f32_e32 v186, v194, v12
	v_fmac_f32_e32 v187, v194, v13
	v_fmac_f32_e32 v188, v194, v14
	v_fmac_f32_e32 v189, v194, v15
	v_fmac_f32_e32 v190, v195, v12
	v_fmac_f32_e32 v191, v195, v13
	v_fmac_f32_e32 v192, v195, v14
	v_fmac_f32_e32 v193, v195, v15
	s_mov_b64 exec, s[10:11]
	ds_write2st64_b64 v196, v[132:133], v[238:239] offset0:22 offset1:20
	s_mov_b64 exec, -1
	ds_read_b128 v[8:11], v152 offset:9984
	ds_read_b128 v[12:15], v152 offset:18176
	ds_read_b128 v[16:19], v152 offset:26368
	ds_read_b128 v[20:23], v152 offset:34560
	ds_read_b64 v[64:65], v69 offset:1792
	s_waitcnt lgkmcnt(11)
	v_mul_f32_e32 v194, v186, v28
	v_mul_f32_e32 v195, v190, v28
	v_mul_f32_e32 v132, v186, v40
	v_mul_f32_e32 v133, v190, v40
	v_fmac_f32_e32 v194, v187, v29
	v_fmac_f32_e32 v195, v191, v29
	v_fmac_f32_e32 v132, v187, v41
	v_fmac_f32_e32 v133, v191, v41
	v_fmac_f32_e32 v194, v188, v30
	v_fmac_f32_e32 v195, v192, v30
	v_fmac_f32_e32 v132, v188, v42
	v_fmac_f32_e32 v133, v192, v42
	v_fmac_f32_e32 v194, v189, v31
	v_fmac_f32_e32 v195, v193, v31
	v_fmac_f32_e32 v132, v189, v43
	v_fmac_f32_e32 v133, v193, v43
	v_add_f32_dpp v194, v194, v194 quad_perm:[1,0,3,2] row_mask:0xf bank_mask:0xf bound_ctrl:1
	v_add_f32_dpp v195, v195, v195 quad_perm:[1,0,3,2] row_mask:0xf bank_mask:0xf bound_ctrl:1
	v_add_f32_dpp v132, v132, v132 quad_perm:[1,0,3,2] row_mask:0xf bank_mask:0xf bound_ctrl:1
	v_add_f32_dpp v133, v133, v133 quad_perm:[1,0,3,2] row_mask:0xf bank_mask:0xf bound_ctrl:1
	v_add_f32_dpp v194, v194, v194 quad_perm:[2,3,0,1] row_mask:0xf bank_mask:0xf bound_ctrl:1
	v_add_f32_dpp v195, v195, v195 quad_perm:[2,3,0,1] row_mask:0xf bank_mask:0xf bound_ctrl:1
	v_add_f32_dpp v132, v132, v132 quad_perm:[2,3,0,1] row_mask:0xf bank_mask:0xf bound_ctrl:1
	v_add_f32_dpp v133, v133, v133 quad_perm:[2,3,0,1] row_mask:0xf bank_mask:0xf bound_ctrl:1
	v_add_f32_dpp v194, v194, v194 row_half_mirror row_mask:0xf bank_mask:0xf bound_ctrl:1
	v_add_f32_dpp v195, v195, v195 row_half_mirror row_mask:0xf bank_mask:0xf bound_ctrl:1
	v_fmac_f32_e32 v186, v66, v36
	v_fmac_f32_e32 v187, v66, v37
	v_add_f32_dpp v194, v194, v194 row_mirror row_mask:0xf bank_mask:0xf bound_ctrl:1
	v_add_f32_dpp v195, v195, v195 row_mirror row_mask:0xf bank_mask:0xf bound_ctrl:1
	v_fmac_f32_e32 v188, v66, v38
	v_fmac_f32_e32 v189, v66, v39
	v_fmac_f32_e32 v190, v67, v36
	v_fmac_f32_e32 v191, v67, v37
	v_fmac_f32_e32 v192, v67, v38
	v_fmac_f32_e32 v193, v67, v39
	v_fmac_f32_e32 v186, v194, v32
	v_fmac_f32_e32 v187, v194, v33
	v_fmac_f32_e32 v188, v194, v34
	v_fmac_f32_e32 v189, v194, v35
	v_fmac_f32_e32 v190, v195, v32
	v_fmac_f32_e32 v191, v195, v33
	v_fmac_f32_e32 v192, v195, v34
	v_fmac_f32_e32 v193, v195, v35
	ds_read_b128 v[28:31], v152 offset:9728
	ds_read_b128 v[32:35], v152 offset:17920
	ds_read_b128 v[36:39], v152 offset:26112
	ds_read_b128 v[40:43], v152 offset:34304
	ds_read_b64 v[66:67], v69 offset:1536
	s_waitcnt lgkmcnt(11)
	v_mul_f32_e32 v194, v186, v48
	v_mul_f32_e32 v195, v190, v48
	v_mul_f32_e32 v238, v186, v60
	v_mul_f32_e32 v239, v190, v60
	v_fmac_f32_e32 v194, v187, v49
	v_fmac_f32_e32 v195, v191, v49
	v_fmac_f32_e32 v238, v187, v61
	v_fmac_f32_e32 v239, v191, v61
	v_fmac_f32_e32 v194, v188, v50
	v_fmac_f32_e32 v195, v192, v50
	v_fmac_f32_e32 v238, v188, v62
	v_fmac_f32_e32 v239, v192, v62
	v_fmac_f32_e32 v194, v189, v51
	v_fmac_f32_e32 v195, v193, v51
	v_fmac_f32_e32 v238, v189, v63
	v_fmac_f32_e32 v239, v193, v63
	v_add_f32_dpp v194, v194, v194 quad_perm:[1,0,3,2] row_mask:0xf bank_mask:0xf bound_ctrl:1
	v_add_f32_dpp v195, v195, v195 quad_perm:[1,0,3,2] row_mask:0xf bank_mask:0xf bound_ctrl:1
	v_add_f32_dpp v238, v238, v238 quad_perm:[1,0,3,2] row_mask:0xf bank_mask:0xf bound_ctrl:1
	v_add_f32_dpp v239, v239, v239 quad_perm:[1,0,3,2] row_mask:0xf bank_mask:0xf bound_ctrl:1
	v_add_f32_dpp v194, v194, v194 quad_perm:[2,3,0,1] row_mask:0xf bank_mask:0xf bound_ctrl:1
	v_add_f32_dpp v195, v195, v195 quad_perm:[2,3,0,1] row_mask:0xf bank_mask:0xf bound_ctrl:1
	v_add_f32_dpp v238, v238, v238 quad_perm:[2,3,0,1] row_mask:0xf bank_mask:0xf bound_ctrl:1
	v_add_f32_dpp v239, v239, v239 quad_perm:[2,3,0,1] row_mask:0xf bank_mask:0xf bound_ctrl:1
	v_add_f32_dpp v194, v194, v194 row_half_mirror row_mask:0xf bank_mask:0xf bound_ctrl:1
	v_add_f32_dpp v195, v195, v195 row_half_mirror row_mask:0xf bank_mask:0xf bound_ctrl:1
	v_fmac_f32_e32 v186, v130, v56
	v_fmac_f32_e32 v187, v130, v57
	v_add_f32_dpp v194, v194, v194 row_mirror row_mask:0xf bank_mask:0xf bound_ctrl:1
	v_add_f32_dpp v195, v195, v195 row_mirror row_mask:0xf bank_mask:0xf bound_ctrl:1
	v_fmac_f32_e32 v188, v130, v58
	v_fmac_f32_e32 v189, v130, v59
	v_fmac_f32_e32 v190, v131, v56
	v_fmac_f32_e32 v191, v131, v57
	v_fmac_f32_e32 v192, v131, v58
	v_fmac_f32_e32 v193, v131, v59
	v_fmac_f32_e32 v186, v194, v52
	v_fmac_f32_e32 v187, v194, v53
	v_fmac_f32_e32 v188, v194, v54
	v_fmac_f32_e32 v189, v194, v55
	v_fmac_f32_e32 v190, v195, v52
	v_fmac_f32_e32 v191, v195, v53
	v_fmac_f32_e32 v192, v195, v54
	v_fmac_f32_e32 v193, v195, v55
	s_mov_b64 exec, s[10:11]
	ds_write2st64_b64 v196, v[132:133], v[238:239] offset0:18 offset1:16
	s_mov_b64 exec, -1
	ds_read_b128 v[48:51], v152 offset:9472
	ds_read_b128 v[52:55], v152 offset:17664
	ds_read_b128 v[56:59], v152 offset:25856
	ds_read_b128 v[60:63], v152 offset:34048
	ds_read_b64 v[130:131], v69 offset:1280
	s_waitcnt lgkmcnt(11)
	v_mul_f32_e32 v194, v186, v8
	v_mul_f32_e32 v195, v190, v8
	v_mul_f32_e32 v132, v186, v20
	v_mul_f32_e32 v133, v190, v20
	v_fmac_f32_e32 v194, v187, v9
	v_fmac_f32_e32 v195, v191, v9
	v_fmac_f32_e32 v132, v187, v21
	v_fmac_f32_e32 v133, v191, v21
	v_fmac_f32_e32 v194, v188, v10
	v_fmac_f32_e32 v195, v192, v10
	v_fmac_f32_e32 v132, v188, v22
	v_fmac_f32_e32 v133, v192, v22
	v_fmac_f32_e32 v194, v189, v11
	v_fmac_f32_e32 v195, v193, v11
	v_fmac_f32_e32 v132, v189, v23
	v_fmac_f32_e32 v133, v193, v23
	v_add_f32_dpp v194, v194, v194 quad_perm:[1,0,3,2] row_mask:0xf bank_mask:0xf bound_ctrl:1
	v_add_f32_dpp v195, v195, v195 quad_perm:[1,0,3,2] row_mask:0xf bank_mask:0xf bound_ctrl:1
	v_add_f32_dpp v132, v132, v132 quad_perm:[1,0,3,2] row_mask:0xf bank_mask:0xf bound_ctrl:1
	v_add_f32_dpp v133, v133, v133 quad_perm:[1,0,3,2] row_mask:0xf bank_mask:0xf bound_ctrl:1
	v_add_f32_dpp v194, v194, v194 quad_perm:[2,3,0,1] row_mask:0xf bank_mask:0xf bound_ctrl:1
	v_add_f32_dpp v195, v195, v195 quad_perm:[2,3,0,1] row_mask:0xf bank_mask:0xf bound_ctrl:1
	v_add_f32_dpp v132, v132, v132 quad_perm:[2,3,0,1] row_mask:0xf bank_mask:0xf bound_ctrl:1
	v_add_f32_dpp v133, v133, v133 quad_perm:[2,3,0,1] row_mask:0xf bank_mask:0xf bound_ctrl:1
	v_add_f32_dpp v194, v194, v194 row_half_mirror row_mask:0xf bank_mask:0xf bound_ctrl:1
	v_add_f32_dpp v195, v195, v195 row_half_mirror row_mask:0xf bank_mask:0xf bound_ctrl:1
	v_fmac_f32_e32 v186, v64, v16
	v_fmac_f32_e32 v187, v64, v17
	v_add_f32_dpp v194, v194, v194 row_mirror row_mask:0xf bank_mask:0xf bound_ctrl:1
	v_add_f32_dpp v195, v195, v195 row_mirror row_mask:0xf bank_mask:0xf bound_ctrl:1
	v_fmac_f32_e32 v188, v64, v18
	v_fmac_f32_e32 v189, v64, v19
	v_fmac_f32_e32 v190, v65, v16
	v_fmac_f32_e32 v191, v65, v17
	v_fmac_f32_e32 v192, v65, v18
	v_fmac_f32_e32 v193, v65, v19
	v_fmac_f32_e32 v186, v194, v12
	v_fmac_f32_e32 v187, v194, v13
	v_fmac_f32_e32 v188, v194, v14
	v_fmac_f32_e32 v189, v194, v15
	v_fmac_f32_e32 v190, v195, v12
	v_fmac_f32_e32 v191, v195, v13
	v_fmac_f32_e32 v192, v195, v14
	v_fmac_f32_e32 v193, v195, v15
	ds_read_b128 v[8:11], v152 offset:9216
	ds_read_b128 v[12:15], v152 offset:17408
	ds_read_b128 v[16:19], v152 offset:25600
	ds_read_b128 v[20:23], v152 offset:33792
	ds_read_b64 v[64:65], v69 offset:1024
	s_waitcnt lgkmcnt(11)
	v_mul_f32_e32 v194, v186, v28
	v_mul_f32_e32 v195, v190, v28
	v_mul_f32_e32 v238, v186, v40
	v_mul_f32_e32 v239, v190, v40
	v_fmac_f32_e32 v194, v187, v29
	v_fmac_f32_e32 v195, v191, v29
	v_fmac_f32_e32 v238, v187, v41
	v_fmac_f32_e32 v239, v191, v41
	v_fmac_f32_e32 v194, v188, v30
	v_fmac_f32_e32 v195, v192, v30
	v_fmac_f32_e32 v238, v188, v42
	v_fmac_f32_e32 v239, v192, v42
	v_fmac_f32_e32 v194, v189, v31
	v_fmac_f32_e32 v195, v193, v31
	v_fmac_f32_e32 v238, v189, v43
	v_fmac_f32_e32 v239, v193, v43
	v_add_f32_dpp v194, v194, v194 quad_perm:[1,0,3,2] row_mask:0xf bank_mask:0xf bound_ctrl:1
	v_add_f32_dpp v195, v195, v195 quad_perm:[1,0,3,2] row_mask:0xf bank_mask:0xf bound_ctrl:1
	v_add_f32_dpp v238, v238, v238 quad_perm:[1,0,3,2] row_mask:0xf bank_mask:0xf bound_ctrl:1
	v_add_f32_dpp v239, v239, v239 quad_perm:[1,0,3,2] row_mask:0xf bank_mask:0xf bound_ctrl:1
	v_add_f32_dpp v194, v194, v194 quad_perm:[2,3,0,1] row_mask:0xf bank_mask:0xf bound_ctrl:1
	v_add_f32_dpp v195, v195, v195 quad_perm:[2,3,0,1] row_mask:0xf bank_mask:0xf bound_ctrl:1
	v_add_f32_dpp v238, v238, v238 quad_perm:[2,3,0,1] row_mask:0xf bank_mask:0xf bound_ctrl:1
	v_add_f32_dpp v239, v239, v239 quad_perm:[2,3,0,1] row_mask:0xf bank_mask:0xf bound_ctrl:1
	v_add_f32_dpp v194, v194, v194 row_half_mirror row_mask:0xf bank_mask:0xf bound_ctrl:1
	v_add_f32_dpp v195, v195, v195 row_half_mirror row_mask:0xf bank_mask:0xf bound_ctrl:1
	v_fmac_f32_e32 v186, v66, v36
	v_fmac_f32_e32 v187, v66, v37
	v_add_f32_dpp v194, v194, v194 row_mirror row_mask:0xf bank_mask:0xf bound_ctrl:1
	v_add_f32_dpp v195, v195, v195 row_mirror row_mask:0xf bank_mask:0xf bound_ctrl:1
	v_fmac_f32_e32 v188, v66, v38
	v_fmac_f32_e32 v189, v66, v39
	v_fmac_f32_e32 v190, v67, v36
	v_fmac_f32_e32 v191, v67, v37
	v_fmac_f32_e32 v192, v67, v38
	v_fmac_f32_e32 v193, v67, v39
	v_fmac_f32_e32 v186, v194, v32
	v_fmac_f32_e32 v187, v194, v33
	v_fmac_f32_e32 v188, v194, v34
	v_fmac_f32_e32 v189, v194, v35
	v_fmac_f32_e32 v190, v195, v32
	v_fmac_f32_e32 v191, v195, v33
	v_fmac_f32_e32 v192, v195, v34
	v_fmac_f32_e32 v193, v195, v35
	s_mov_b64 exec, s[10:11]
	ds_write2st64_b64 v196, v[132:133], v[238:239] offset0:14 offset1:12
	s_mov_b64 exec, -1
	ds_read_b128 v[28:31], v152 offset:8960
	ds_read_b128 v[32:35], v152 offset:17152
	ds_read_b128 v[36:39], v152 offset:25344
	ds_read_b128 v[40:43], v152 offset:33536
	ds_read_b64 v[66:67], v69 offset:768
	s_waitcnt lgkmcnt(11)
	v_mul_f32_e32 v194, v186, v48
	v_mul_f32_e32 v195, v190, v48
	v_mul_f32_e32 v132, v186, v60
	v_mul_f32_e32 v133, v190, v60
	v_fmac_f32_e32 v194, v187, v49
	v_fmac_f32_e32 v195, v191, v49
	v_fmac_f32_e32 v132, v187, v61
	v_fmac_f32_e32 v133, v191, v61
	v_fmac_f32_e32 v194, v188, v50
	v_fmac_f32_e32 v195, v192, v50
	v_fmac_f32_e32 v132, v188, v62
	v_fmac_f32_e32 v133, v192, v62
	v_fmac_f32_e32 v194, v189, v51
	v_fmac_f32_e32 v195, v193, v51
	v_fmac_f32_e32 v132, v189, v63
	v_fmac_f32_e32 v133, v193, v63
	v_add_f32_dpp v194, v194, v194 quad_perm:[1,0,3,2] row_mask:0xf bank_mask:0xf bound_ctrl:1
	v_add_f32_dpp v195, v195, v195 quad_perm:[1,0,3,2] row_mask:0xf bank_mask:0xf bound_ctrl:1
	v_add_f32_dpp v132, v132, v132 quad_perm:[1,0,3,2] row_mask:0xf bank_mask:0xf bound_ctrl:1
	v_add_f32_dpp v133, v133, v133 quad_perm:[1,0,3,2] row_mask:0xf bank_mask:0xf bound_ctrl:1
	v_add_f32_dpp v194, v194, v194 quad_perm:[2,3,0,1] row_mask:0xf bank_mask:0xf bound_ctrl:1
	v_add_f32_dpp v195, v195, v195 quad_perm:[2,3,0,1] row_mask:0xf bank_mask:0xf bound_ctrl:1
	v_add_f32_dpp v132, v132, v132 quad_perm:[2,3,0,1] row_mask:0xf bank_mask:0xf bound_ctrl:1
	v_add_f32_dpp v133, v133, v133 quad_perm:[2,3,0,1] row_mask:0xf bank_mask:0xf bound_ctrl:1
	v_add_f32_dpp v194, v194, v194 row_half_mirror row_mask:0xf bank_mask:0xf bound_ctrl:1
	v_add_f32_dpp v195, v195, v195 row_half_mirror row_mask:0xf bank_mask:0xf bound_ctrl:1
	v_fmac_f32_e32 v186, v130, v56
	v_fmac_f32_e32 v187, v130, v57
	v_add_f32_dpp v194, v194, v194 row_mirror row_mask:0xf bank_mask:0xf bound_ctrl:1
	v_add_f32_dpp v195, v195, v195 row_mirror row_mask:0xf bank_mask:0xf bound_ctrl:1
	v_fmac_f32_e32 v188, v130, v58
	v_fmac_f32_e32 v189, v130, v59
	v_fmac_f32_e32 v190, v131, v56
	v_fmac_f32_e32 v191, v131, v57
	v_fmac_f32_e32 v192, v131, v58
	v_fmac_f32_e32 v193, v131, v59
	v_fmac_f32_e32 v186, v194, v52
	v_fmac_f32_e32 v187, v194, v53
	v_fmac_f32_e32 v188, v194, v54
	v_fmac_f32_e32 v189, v194, v55
	v_fmac_f32_e32 v190, v195, v52
	v_fmac_f32_e32 v191, v195, v53
	v_fmac_f32_e32 v192, v195, v54
	v_fmac_f32_e32 v193, v195, v55
	ds_read_b128 v[48:51], v152 offset:8704
	ds_read_b128 v[52:55], v152 offset:16896
	ds_read_b128 v[56:59], v152 offset:25088
	ds_read_b128 v[60:63], v152 offset:33280
	ds_read_b64 v[130:131], v69 offset:512
	s_waitcnt lgkmcnt(11)
	v_mul_f32_e32 v194, v186, v8
	v_mul_f32_e32 v195, v190, v8
	v_mul_f32_e32 v238, v186, v20
	v_mul_f32_e32 v239, v190, v20
	v_fmac_f32_e32 v194, v187, v9
	v_fmac_f32_e32 v195, v191, v9
	v_fmac_f32_e32 v238, v187, v21
	v_fmac_f32_e32 v239, v191, v21
	v_fmac_f32_e32 v194, v188, v10
	v_fmac_f32_e32 v195, v192, v10
	v_fmac_f32_e32 v238, v188, v22
	v_fmac_f32_e32 v239, v192, v22
	v_fmac_f32_e32 v194, v189, v11
	v_fmac_f32_e32 v195, v193, v11
	v_fmac_f32_e32 v238, v189, v23
	v_fmac_f32_e32 v239, v193, v23
	v_add_f32_dpp v194, v194, v194 quad_perm:[1,0,3,2] row_mask:0xf bank_mask:0xf bound_ctrl:1
	v_add_f32_dpp v195, v195, v195 quad_perm:[1,0,3,2] row_mask:0xf bank_mask:0xf bound_ctrl:1
	v_add_f32_dpp v238, v238, v238 quad_perm:[1,0,3,2] row_mask:0xf bank_mask:0xf bound_ctrl:1
	v_add_f32_dpp v239, v239, v239 quad_perm:[1,0,3,2] row_mask:0xf bank_mask:0xf bound_ctrl:1
	v_add_f32_dpp v194, v194, v194 quad_perm:[2,3,0,1] row_mask:0xf bank_mask:0xf bound_ctrl:1
	v_add_f32_dpp v195, v195, v195 quad_perm:[2,3,0,1] row_mask:0xf bank_mask:0xf bound_ctrl:1
	v_add_f32_dpp v238, v238, v238 quad_perm:[2,3,0,1] row_mask:0xf bank_mask:0xf bound_ctrl:1
	v_add_f32_dpp v239, v239, v239 quad_perm:[2,3,0,1] row_mask:0xf bank_mask:0xf bound_ctrl:1
	v_add_f32_dpp v194, v194, v194 row_half_mirror row_mask:0xf bank_mask:0xf bound_ctrl:1
	v_add_f32_dpp v195, v195, v195 row_half_mirror row_mask:0xf bank_mask:0xf bound_ctrl:1
	v_fmac_f32_e32 v186, v64, v16
	v_fmac_f32_e32 v187, v64, v17
	v_add_f32_dpp v194, v194, v194 row_mirror row_mask:0xf bank_mask:0xf bound_ctrl:1
	v_add_f32_dpp v195, v195, v195 row_mirror row_mask:0xf bank_mask:0xf bound_ctrl:1
	v_fmac_f32_e32 v188, v64, v18
	v_fmac_f32_e32 v189, v64, v19
	v_fmac_f32_e32 v190, v65, v16
	v_fmac_f32_e32 v191, v65, v17
	v_fmac_f32_e32 v192, v65, v18
	v_fmac_f32_e32 v193, v65, v19
	v_fmac_f32_e32 v186, v194, v12
	v_fmac_f32_e32 v187, v194, v13
	v_fmac_f32_e32 v188, v194, v14
	v_fmac_f32_e32 v189, v194, v15
	v_fmac_f32_e32 v190, v195, v12
	v_fmac_f32_e32 v191, v195, v13
	v_fmac_f32_e32 v192, v195, v14
	v_fmac_f32_e32 v193, v195, v15
	s_mov_b64 exec, s[10:11]
	ds_write2st64_b64 v196, v[132:133], v[238:239] offset0:10 offset1:8
	s_mov_b64 exec, -1
	ds_read_b128 v[8:11], v152 offset:8448
	ds_read_b128 v[12:15], v152 offset:16640
	ds_read_b128 v[16:19], v152 offset:24832
	ds_read_b128 v[20:23], v152 offset:33024
	ds_read_b64 v[64:65], v69 offset:256
	s_waitcnt lgkmcnt(11)
	v_mul_f32_e32 v194, v186, v28
	v_mul_f32_e32 v195, v190, v28
	v_mul_f32_e32 v132, v186, v40
	v_mul_f32_e32 v133, v190, v40
	v_fmac_f32_e32 v194, v187, v29
	v_fmac_f32_e32 v195, v191, v29
	v_fmac_f32_e32 v132, v187, v41
	v_fmac_f32_e32 v133, v191, v41
	v_fmac_f32_e32 v194, v188, v30
	v_fmac_f32_e32 v195, v192, v30
	v_fmac_f32_e32 v132, v188, v42
	v_fmac_f32_e32 v133, v192, v42
	v_fmac_f32_e32 v194, v189, v31
	v_fmac_f32_e32 v195, v193, v31
	v_fmac_f32_e32 v132, v189, v43
	v_fmac_f32_e32 v133, v193, v43
	v_add_f32_dpp v194, v194, v194 quad_perm:[1,0,3,2] row_mask:0xf bank_mask:0xf bound_ctrl:1
	v_add_f32_dpp v195, v195, v195 quad_perm:[1,0,3,2] row_mask:0xf bank_mask:0xf bound_ctrl:1
	v_add_f32_dpp v132, v132, v132 quad_perm:[1,0,3,2] row_mask:0xf bank_mask:0xf bound_ctrl:1
	v_add_f32_dpp v133, v133, v133 quad_perm:[1,0,3,2] row_mask:0xf bank_mask:0xf bound_ctrl:1
	v_add_f32_dpp v194, v194, v194 quad_perm:[2,3,0,1] row_mask:0xf bank_mask:0xf bound_ctrl:1
	v_add_f32_dpp v195, v195, v195 quad_perm:[2,3,0,1] row_mask:0xf bank_mask:0xf bound_ctrl:1
	v_add_f32_dpp v132, v132, v132 quad_perm:[2,3,0,1] row_mask:0xf bank_mask:0xf bound_ctrl:1
	v_add_f32_dpp v133, v133, v133 quad_perm:[2,3,0,1] row_mask:0xf bank_mask:0xf bound_ctrl:1
	v_add_f32_dpp v194, v194, v194 row_half_mirror row_mask:0xf bank_mask:0xf bound_ctrl:1
	v_add_f32_dpp v195, v195, v195 row_half_mirror row_mask:0xf bank_mask:0xf bound_ctrl:1
	v_fmac_f32_e32 v186, v66, v36
	v_fmac_f32_e32 v187, v66, v37
	v_add_f32_dpp v194, v194, v194 row_mirror row_mask:0xf bank_mask:0xf bound_ctrl:1
	v_add_f32_dpp v195, v195, v195 row_mirror row_mask:0xf bank_mask:0xf bound_ctrl:1
	v_fmac_f32_e32 v188, v66, v38
	v_fmac_f32_e32 v189, v66, v39
	v_fmac_f32_e32 v190, v67, v36
	v_fmac_f32_e32 v191, v67, v37
	v_fmac_f32_e32 v192, v67, v38
	v_fmac_f32_e32 v193, v67, v39
	v_fmac_f32_e32 v186, v194, v32
	v_fmac_f32_e32 v187, v194, v33
	v_fmac_f32_e32 v188, v194, v34
	v_fmac_f32_e32 v189, v194, v35
	v_fmac_f32_e32 v190, v195, v32
	v_fmac_f32_e32 v191, v195, v33
	v_fmac_f32_e32 v192, v195, v34
	v_fmac_f32_e32 v193, v195, v35
	ds_read_b128 v[28:31], v152 offset:8192
	ds_read_b128 v[32:35], v152 offset:16384
	ds_read_b128 v[36:39], v152 offset:24576
	ds_read_b128 v[40:43], v152 offset:32768
	ds_read_b64 v[66:67], v69
	s_waitcnt lgkmcnt(11)
	v_mul_f32_e32 v194, v186, v48
	v_mul_f32_e32 v195, v190, v48
	v_mul_f32_e32 v238, v186, v60
	v_mul_f32_e32 v239, v190, v60
	v_fmac_f32_e32 v194, v187, v49
	v_fmac_f32_e32 v195, v191, v49
	v_fmac_f32_e32 v238, v187, v61
	v_fmac_f32_e32 v239, v191, v61
	v_fmac_f32_e32 v194, v188, v50
	v_fmac_f32_e32 v195, v192, v50
	v_fmac_f32_e32 v238, v188, v62
	v_fmac_f32_e32 v239, v192, v62
	v_fmac_f32_e32 v194, v189, v51
	v_fmac_f32_e32 v195, v193, v51
	v_fmac_f32_e32 v238, v189, v63
	v_fmac_f32_e32 v239, v193, v63
	v_add_f32_dpp v194, v194, v194 quad_perm:[1,0,3,2] row_mask:0xf bank_mask:0xf bound_ctrl:1
	v_add_f32_dpp v195, v195, v195 quad_perm:[1,0,3,2] row_mask:0xf bank_mask:0xf bound_ctrl:1
	v_add_f32_dpp v238, v238, v238 quad_perm:[1,0,3,2] row_mask:0xf bank_mask:0xf bound_ctrl:1
	v_add_f32_dpp v239, v239, v239 quad_perm:[1,0,3,2] row_mask:0xf bank_mask:0xf bound_ctrl:1
	v_add_f32_dpp v194, v194, v194 quad_perm:[2,3,0,1] row_mask:0xf bank_mask:0xf bound_ctrl:1
	v_add_f32_dpp v195, v195, v195 quad_perm:[2,3,0,1] row_mask:0xf bank_mask:0xf bound_ctrl:1
	v_add_f32_dpp v238, v238, v238 quad_perm:[2,3,0,1] row_mask:0xf bank_mask:0xf bound_ctrl:1
	v_add_f32_dpp v239, v239, v239 quad_perm:[2,3,0,1] row_mask:0xf bank_mask:0xf bound_ctrl:1
	v_add_f32_dpp v194, v194, v194 row_half_mirror row_mask:0xf bank_mask:0xf bound_ctrl:1
	v_add_f32_dpp v195, v195, v195 row_half_mirror row_mask:0xf bank_mask:0xf bound_ctrl:1
	v_fmac_f32_e32 v186, v130, v56
	v_fmac_f32_e32 v187, v130, v57
	v_add_f32_dpp v194, v194, v194 row_mirror row_mask:0xf bank_mask:0xf bound_ctrl:1
	v_add_f32_dpp v195, v195, v195 row_mirror row_mask:0xf bank_mask:0xf bound_ctrl:1
	v_fmac_f32_e32 v188, v130, v58
	v_fmac_f32_e32 v189, v130, v59
	v_fmac_f32_e32 v190, v131, v56
	v_fmac_f32_e32 v191, v131, v57
	v_fmac_f32_e32 v192, v131, v58
	v_fmac_f32_e32 v193, v131, v59
	v_fmac_f32_e32 v186, v194, v52
	v_fmac_f32_e32 v187, v194, v53
	v_fmac_f32_e32 v188, v194, v54
	v_fmac_f32_e32 v189, v194, v55
	v_fmac_f32_e32 v190, v195, v52
	v_fmac_f32_e32 v191, v195, v53
	v_fmac_f32_e32 v192, v195, v54
	v_fmac_f32_e32 v193, v195, v55
	s_mov_b64 exec, s[10:11]
	ds_write2st64_b64 v196, v[132:133], v[238:239] offset0:6 offset1:4
	s_mov_b64 exec, -1
	s_waitcnt lgkmcnt(6)
	v_mul_f32_e32 v194, v186, v8
	v_mul_f32_e32 v195, v190, v8
	v_mul_f32_e32 v132, v186, v20
	v_mul_f32_e32 v133, v190, v20
	v_fmac_f32_e32 v194, v187, v9
	v_fmac_f32_e32 v195, v191, v9
	v_fmac_f32_e32 v132, v187, v21
	v_fmac_f32_e32 v133, v191, v21
	v_fmac_f32_e32 v194, v188, v10
	v_fmac_f32_e32 v195, v192, v10
	v_fmac_f32_e32 v132, v188, v22
	v_fmac_f32_e32 v133, v192, v22
	v_fmac_f32_e32 v194, v189, v11
	v_fmac_f32_e32 v195, v193, v11
	v_fmac_f32_e32 v132, v189, v23
	v_fmac_f32_e32 v133, v193, v23
	v_add_f32_dpp v194, v194, v194 quad_perm:[1,0,3,2] row_mask:0xf bank_mask:0xf bound_ctrl:1
	v_add_f32_dpp v195, v195, v195 quad_perm:[1,0,3,2] row_mask:0xf bank_mask:0xf bound_ctrl:1
	v_add_f32_dpp v132, v132, v132 quad_perm:[1,0,3,2] row_mask:0xf bank_mask:0xf bound_ctrl:1
	v_add_f32_dpp v133, v133, v133 quad_perm:[1,0,3,2] row_mask:0xf bank_mask:0xf bound_ctrl:1
	v_add_f32_dpp v194, v194, v194 quad_perm:[2,3,0,1] row_mask:0xf bank_mask:0xf bound_ctrl:1
	v_add_f32_dpp v195, v195, v195 quad_perm:[2,3,0,1] row_mask:0xf bank_mask:0xf bound_ctrl:1
	v_add_f32_dpp v132, v132, v132 quad_perm:[2,3,0,1] row_mask:0xf bank_mask:0xf bound_ctrl:1
	v_add_f32_dpp v133, v133, v133 quad_perm:[2,3,0,1] row_mask:0xf bank_mask:0xf bound_ctrl:1
	v_add_f32_dpp v194, v194, v194 row_half_mirror row_mask:0xf bank_mask:0xf bound_ctrl:1
	v_add_f32_dpp v195, v195, v195 row_half_mirror row_mask:0xf bank_mask:0xf bound_ctrl:1
	v_fmac_f32_e32 v186, v64, v16
	v_fmac_f32_e32 v187, v64, v17
	v_add_f32_dpp v194, v194, v194 row_mirror row_mask:0xf bank_mask:0xf bound_ctrl:1
	v_add_f32_dpp v195, v195, v195 row_mirror row_mask:0xf bank_mask:0xf bound_ctrl:1
	v_fmac_f32_e32 v188, v64, v18
	v_fmac_f32_e32 v189, v64, v19
	v_fmac_f32_e32 v190, v65, v16
	v_fmac_f32_e32 v191, v65, v17
	v_fmac_f32_e32 v192, v65, v18
	v_fmac_f32_e32 v193, v65, v19
	v_fmac_f32_e32 v186, v194, v12
	v_fmac_f32_e32 v187, v194, v13
	v_fmac_f32_e32 v188, v194, v14
	v_fmac_f32_e32 v189, v194, v15
	v_fmac_f32_e32 v190, v195, v12
	v_fmac_f32_e32 v191, v195, v13
	v_fmac_f32_e32 v192, v195, v14
	v_fmac_f32_e32 v193, v195, v15
	s_waitcnt lgkmcnt(1)
	v_mul_f32_e32 v194, v186, v28
	v_mul_f32_e32 v195, v190, v28
	v_mul_f32_e32 v238, v186, v40
	v_mul_f32_e32 v239, v190, v40
	v_fmac_f32_e32 v194, v187, v29
	v_fmac_f32_e32 v195, v191, v29
	v_fmac_f32_e32 v238, v187, v41
	v_fmac_f32_e32 v239, v191, v41
	v_fmac_f32_e32 v194, v188, v30
	v_fmac_f32_e32 v195, v192, v30
	v_fmac_f32_e32 v238, v188, v42
	v_fmac_f32_e32 v239, v192, v42
	v_fmac_f32_e32 v194, v189, v31
	v_fmac_f32_e32 v195, v193, v31
	v_fmac_f32_e32 v238, v189, v43
	v_fmac_f32_e32 v239, v193, v43
	v_add_f32_dpp v194, v194, v194 quad_perm:[1,0,3,2] row_mask:0xf bank_mask:0xf bound_ctrl:1
	v_add_f32_dpp v195, v195, v195 quad_perm:[1,0,3,2] row_mask:0xf bank_mask:0xf bound_ctrl:1
	v_add_f32_dpp v238, v238, v238 quad_perm:[1,0,3,2] row_mask:0xf bank_mask:0xf bound_ctrl:1
	v_add_f32_dpp v239, v239, v239 quad_perm:[1,0,3,2] row_mask:0xf bank_mask:0xf bound_ctrl:1
	v_add_f32_dpp v194, v194, v194 quad_perm:[2,3,0,1] row_mask:0xf bank_mask:0xf bound_ctrl:1
	v_add_f32_dpp v195, v195, v195 quad_perm:[2,3,0,1] row_mask:0xf bank_mask:0xf bound_ctrl:1
	v_add_f32_dpp v238, v238, v238 quad_perm:[2,3,0,1] row_mask:0xf bank_mask:0xf bound_ctrl:1
	v_add_f32_dpp v239, v239, v239 quad_perm:[2,3,0,1] row_mask:0xf bank_mask:0xf bound_ctrl:1
	v_add_f32_dpp v194, v194, v194 row_half_mirror row_mask:0xf bank_mask:0xf bound_ctrl:1
	v_add_f32_dpp v195, v195, v195 row_half_mirror row_mask:0xf bank_mask:0xf bound_ctrl:1
	v_fmac_f32_e32 v186, v66, v36
	v_fmac_f32_e32 v187, v66, v37
	v_add_f32_dpp v194, v194, v194 row_mirror row_mask:0xf bank_mask:0xf bound_ctrl:1
	v_add_f32_dpp v195, v195, v195 row_mirror row_mask:0xf bank_mask:0xf bound_ctrl:1
	v_fmac_f32_e32 v188, v66, v38
	v_fmac_f32_e32 v189, v66, v39
	v_fmac_f32_e32 v190, v67, v36
	v_fmac_f32_e32 v191, v67, v37
	v_fmac_f32_e32 v192, v67, v38
	v_fmac_f32_e32 v193, v67, v39
	v_fmac_f32_e32 v186, v194, v32
	v_fmac_f32_e32 v187, v194, v33
	v_fmac_f32_e32 v188, v194, v34
	v_fmac_f32_e32 v189, v194, v35
	v_fmac_f32_e32 v190, v195, v32
	v_fmac_f32_e32 v191, v195, v33
	v_fmac_f32_e32 v192, v195, v34
	v_fmac_f32_e32 v193, v195, v35
	s_mov_b64 exec, s[10:11]
	ds_write2st64_b64 v196, v[132:133], v[238:239] offset0:2 offset1:0
	s_mov_b64 exec, -1
	ds_read_b128 v[4:7], v152 offset:57344
	s_waitcnt lgkmcnt(0)
	v_mul_f32_e32 v186, v186, v4
	v_mul_f32_e32 v187, v187, v5
	v_mul_f32_e32 v188, v188, v6
	v_mul_f32_e32 v189, v189, v7
	v_mul_f32_e32 v190, v190, v4
	v_mul_f32_e32 v191, v191, v5
	v_mul_f32_e32 v192, v192, v6
	v_mul_f32_e32 v193, v193, v7
	s_branch .LBB0_100

.LBB0_182:
	s_or_b64 exec, exec, s[10:11]
	s_waitcnt lgkmcnt(0)
	s_barrier
	v_lshrrev_b32_e32 v244, 4, v134
	v_lshl_add_u32 v244, v244, 9, v159
	ds_read_b128 v[4:7], v244
	ds_read_b128 v[8:11], v244 offset:256
	ds_read_b128 v[200:203], v244 offset:512
	ds_read_b128 v[204:207], v244 offset:768
	s_cmp_eq_u32 s34, 64
	s_mov_b32 s68, s34
	s_waitcnt lgkmcnt(0)
	v_pk_add_f32 v[4:5], v[4:5], v[200:201]
	v_pk_add_f32 v[6:7], v[6:7], v[202:203]
	v_pk_add_f32 v[8:9], v[8:9], v[204:205]
	v_pk_add_f32 v[10:11], v[10:11], v[206:207]
	v_pk_add_f32 v[10:11], v[6:7], v[10:11]
	v_pk_add_f32 v[8:9], v[4:5], v[8:9]
	ds_read_b128 v[4:7], v158
	s_waitcnt lgkmcnt(0)
	v_pk_add_f32 v[6:7], v[10:11], v[6:7]
	v_pk_add_f32 v[4:5], v[8:9], v[4:5]
	s_nop 0
	v_cvt_pk_bf16_f32 v4, v4, v5
	v_cvt_pk_bf16_f32 v5, v6, v7
	v_lshlrev_b64 v[6:7], 11, v[124:125]
	v_lshl_add_u64 v[6:7], v[104:105], 0, v[6:7]
	global_store_dwordx2 v[6:7], v[4:5], off
	s_cbranch_scc1 .LBB0_225

.LBB0_213:
	s_or_b64 exec, exec, s[10:11]
	s_waitcnt lgkmcnt(0)
	s_barrier
	v_mbcnt_lo_u32_b32 v193, -1, 0
	v_mbcnt_hi_u32_b32 v193, -1, v193
	v_lshlrev_b32_e32 v193, 3, v193
	v_add_u32_e32 v193, 0xe000, v193
	v_cndmask_b32_e64 v192, v193, v146, s[8:9]
	v_mbcnt_lo_u32_b32 v193, -1, 0
	v_mbcnt_hi_u32_b32 v193, -1, v193
	v_and_b32_e32 v193, 12, v193
	v_lshlrev_b32_e32 v193, 6, v193
	v_add_u32_e32 v192, 0x10000, v181
	v_add_u32_e32 v192, v193, v192
	s_mov_b32 s10, 0x11111111
	s_mov_b32 s11, 0x11111111
	ds_read_b128 v[8:11], v151 offset:8192
	ds_read_b128 v[12:15], v151 offset:16384
	ds_read_b128 v[16:19], v151 offset:24576
	ds_read_b128 v[20:23], v151 offset:32768
	ds_read_b64 v[64:65], v181
	ds_read_b128 v[28:31], v151 offset:8448
	ds_read_b128 v[32:35], v151 offset:16640
	ds_read_b128 v[36:39], v151 offset:24832
	ds_read_b128 v[40:43], v151 offset:33024
	ds_read_b64 v[66:67], v181 offset:256
	ds_read_b128 v[48:51], v151 offset:8704
	ds_read_b128 v[52:55], v151 offset:16896
	ds_read_b128 v[56:59], v151 offset:25088
	ds_read_b128 v[60:63], v151 offset:33280
	ds_read_b64 v[126:127], v181 offset:512
	s_waitcnt lgkmcnt(10)
	v_mul_f32_e32 v190, v182, v8
	v_mul_f32_e32 v191, v186, v8
	v_mul_f32_e32 v128, v182, v20
	v_mul_f32_e32 v129, v186, v20
	v_fmac_f32_e32 v190, v183, v9
	v_fmac_f32_e32 v191, v187, v9
	v_fmac_f32_e32 v128, v183, v21
	v_fmac_f32_e32 v129, v187, v21
	v_fmac_f32_e32 v190, v184, v10
	v_fmac_f32_e32 v191, v188, v10
	v_fmac_f32_e32 v128, v184, v22
	v_fmac_f32_e32 v129, v188, v22
	v_fmac_f32_e32 v190, v185, v11
	v_fmac_f32_e32 v191, v189, v11
	v_fmac_f32_e32 v128, v185, v23
	v_fmac_f32_e32 v129, v189, v23
	v_add_f32_dpp v190, v190, v190 quad_perm:[1,0,3,2] row_mask:0xf bank_mask:0xf bound_ctrl:1
	v_add_f32_dpp v191, v191, v191 quad_perm:[1,0,3,2] row_mask:0xf bank_mask:0xf bound_ctrl:1
	v_add_f32_dpp v128, v128, v128 quad_perm:[1,0,3,2] row_mask:0xf bank_mask:0xf bound_ctrl:1
	v_add_f32_dpp v129, v129, v129 quad_perm:[1,0,3,2] row_mask:0xf bank_mask:0xf bound_ctrl:1
	v_add_f32_dpp v190, v190, v190 quad_perm:[2,3,0,1] row_mask:0xf bank_mask:0xf bound_ctrl:1
	v_add_f32_dpp v191, v191, v191 quad_perm:[2,3,0,1] row_mask:0xf bank_mask:0xf bound_ctrl:1
	v_add_f32_dpp v128, v128, v128 quad_perm:[2,3,0,1] row_mask:0xf bank_mask:0xf bound_ctrl:1
	v_add_f32_dpp v129, v129, v129 quad_perm:[2,3,0,1] row_mask:0xf bank_mask:0xf bound_ctrl:1
	v_add_f32_dpp v190, v190, v190 row_half_mirror row_mask:0xf bank_mask:0xf bound_ctrl:1
	v_add_f32_dpp v191, v191, v191 row_half_mirror row_mask:0xf bank_mask:0xf bound_ctrl:1
	v_fmac_f32_e32 v182, v64, v16
	v_fmac_f32_e32 v183, v64, v17
	v_add_f32_dpp v190, v190, v190 row_mirror row_mask:0xf bank_mask:0xf bound_ctrl:1
	v_add_f32_dpp v191, v191, v191 row_mirror row_mask:0xf bank_mask:0xf bound_ctrl:1
	v_fmac_f32_e32 v184, v64, v18
	v_fmac_f32_e32 v185, v64, v19
	v_fmac_f32_e32 v186, v65, v16
	v_fmac_f32_e32 v187, v65, v17
	v_fmac_f32_e32 v188, v65, v18
	v_fmac_f32_e32 v189, v65, v19
	v_fmac_f32_e32 v182, v190, v12
	v_fmac_f32_e32 v183, v190, v13
	v_fmac_f32_e32 v184, v190, v14
	v_fmac_f32_e32 v185, v190, v15
	v_fmac_f32_e32 v186, v191, v12
	v_fmac_f32_e32 v187, v191, v13
	v_fmac_f32_e32 v188, v191, v14
	v_fmac_f32_e32 v189, v191, v15
	ds_read_b128 v[8:11], v151 offset:8960
	ds_read_b128 v[12:15], v151 offset:17152
	ds_read_b128 v[16:19], v151 offset:25344
	ds_read_b128 v[20:23], v151 offset:33536
	ds_read_b64 v[64:65], v181 offset:768
	s_waitcnt lgkmcnt(10)
	v_mul_f32_e32 v190, v182, v28
	v_mul_f32_e32 v191, v186, v28
	v_mul_f32_e32 v238, v182, v40
	v_mul_f32_e32 v239, v186, v40
	v_fmac_f32_e32 v190, v183, v29
	v_fmac_f32_e32 v191, v187, v29
	v_fmac_f32_e32 v238, v183, v41
	v_fmac_f32_e32 v239, v187, v41
	v_fmac_f32_e32 v190, v184, v30
	v_fmac_f32_e32 v191, v188, v30
	v_fmac_f32_e32 v238, v184, v42
	v_fmac_f32_e32 v239, v188, v42
	v_fmac_f32_e32 v190, v185, v31
	v_fmac_f32_e32 v191, v189, v31
	v_fmac_f32_e32 v238, v185, v43
	v_fmac_f32_e32 v239, v189, v43
	v_add_f32_dpp v190, v190, v190 quad_perm:[1,0,3,2] row_mask:0xf bank_mask:0xf bound_ctrl:1
	v_add_f32_dpp v191, v191, v191 quad_perm:[1,0,3,2] row_mask:0xf bank_mask:0xf bound_ctrl:1
	v_add_f32_dpp v238, v238, v238 quad_perm:[1,0,3,2] row_mask:0xf bank_mask:0xf bound_ctrl:1
	v_add_f32_dpp v239, v239, v239 quad_perm:[1,0,3,2] row_mask:0xf bank_mask:0xf bound_ctrl:1
	v_add_f32_dpp v190, v190, v190 quad_perm:[2,3,0,1] row_mask:0xf bank_mask:0xf bound_ctrl:1
	v_add_f32_dpp v191, v191, v191 quad_perm:[2,3,0,1] row_mask:0xf bank_mask:0xf bound_ctrl:1
	v_add_f32_dpp v238, v238, v238 quad_perm:[2,3,0,1] row_mask:0xf bank_mask:0xf bound_ctrl:1
	v_add_f32_dpp v239, v239, v239 quad_perm:[2,3,0,1] row_mask:0xf bank_mask:0xf bound_ctrl:1
	v_add_f32_dpp v190, v190, v190 row_half_mirror row_mask:0xf bank_mask:0xf bound_ctrl:1
	v_add_f32_dpp v191, v191, v191 row_half_mirror row_mask:0xf bank_mask:0xf bound_ctrl:1
	v_fmac_f32_e32 v182, v66, v36
	v_fmac_f32_e32 v183, v66, v37
	v_add_f32_dpp v190, v190, v190 row_mirror row_mask:0xf bank_mask:0xf bound_ctrl:1
	v_add_f32_dpp v191, v191, v191 row_mirror row_mask:0xf bank_mask:0xf bound_ctrl:1
	v_fmac_f32_e32 v184, v66, v38
	v_fmac_f32_e32 v185, v66, v39
	v_fmac_f32_e32 v186, v67, v36
	v_fmac_f32_e32 v187, v67, v37
	v_fmac_f32_e32 v188, v67, v38
	v_fmac_f32_e32 v189, v67, v39
	v_fmac_f32_e32 v182, v190, v32
	v_fmac_f32_e32 v183, v190, v33
	v_fmac_f32_e32 v184, v190, v34
	v_fmac_f32_e32 v185, v190, v35
	v_fmac_f32_e32 v186, v191, v32
	v_fmac_f32_e32 v187, v191, v33
	v_fmac_f32_e32 v188, v191, v34
	v_fmac_f32_e32 v189, v191, v35
	s_mov_b64 exec, s[10:11]
	ds_write2st64_b64 v192, v[128:129], v[238:239] offset0:0 offset1:2
	s_mov_b64 exec, -1
	ds_read_b128 v[28:31], v151 offset:9216
	ds_read_b128 v[32:35], v151 offset:17408
	ds_read_b128 v[36:39], v151 offset:25600
	ds_read_b128 v[40:43], v151 offset:33792
	ds_read_b64 v[66:67], v181 offset:1024
	s_waitcnt lgkmcnt(11)
	v_mul_f32_e32 v190, v182, v48
	v_mul_f32_e32 v191, v186, v48
	v_mul_f32_e32 v128, v182, v60
	v_mul_f32_e32 v129, v186, v60
	v_fmac_f32_e32 v190, v183, v49
	v_fmac_f32_e32 v191, v187, v49
	v_fmac_f32_e32 v128, v183, v61
	v_fmac_f32_e32 v129, v187, v61
	v_fmac_f32_e32 v190, v184, v50
	v_fmac_f32_e32 v191, v188, v50
	v_fmac_f32_e32 v128, v184, v62
	v_fmac_f32_e32 v129, v188, v62
	v_fmac_f32_e32 v190, v185, v51
	v_fmac_f32_e32 v191, v189, v51
	v_fmac_f32_e32 v128, v185, v63
	v_fmac_f32_e32 v129, v189, v63
	v_add_f32_dpp v190, v190, v190 quad_perm:[1,0,3,2] row_mask:0xf bank_mask:0xf bound_ctrl:1
	v_add_f32_dpp v191, v191, v191 quad_perm:[1,0,3,2] row_mask:0xf bank_mask:0xf bound_ctrl:1
	v_add_f32_dpp v128, v128, v128 quad_perm:[1,0,3,2] row_mask:0xf bank_mask:0xf bound_ctrl:1
	v_add_f32_dpp v129, v129, v129 quad_perm:[1,0,3,2] row_mask:0xf bank_mask:0xf bound_ctrl:1
	v_add_f32_dpp v190, v190, v190 quad_perm:[2,3,0,1] row_mask:0xf bank_mask:0xf bound_ctrl:1
	v_add_f32_dpp v191, v191, v191 quad_perm:[2,3,0,1] row_mask:0xf bank_mask:0xf bound_ctrl:1
	v_add_f32_dpp v128, v128, v128 quad_perm:[2,3,0,1] row_mask:0xf bank_mask:0xf bound_ctrl:1
	v_add_f32_dpp v129, v129, v129 quad_perm:[2,3,0,1] row_mask:0xf bank_mask:0xf bound_ctrl:1
	v_add_f32_dpp v190, v190, v190 row_half_mirror row_mask:0xf bank_mask:0xf bound_ctrl:1
	v_add_f32_dpp v191, v191, v191 row_half_mirror row_mask:0xf bank_mask:0xf bound_ctrl:1
	v_fmac_f32_e32 v182, v126, v56
	v_fmac_f32_e32 v183, v126, v57
	v_add_f32_dpp v190, v190, v190 row_mirror row_mask:0xf bank_mask:0xf bound_ctrl:1
	v_add_f32_dpp v191, v191, v191 row_mirror row_mask:0xf bank_mask:0xf bound_ctrl:1
	v_fmac_f32_e32 v184, v126, v58
	v_fmac_f32_e32 v185, v126, v59
	v_fmac_f32_e32 v186, v127, v56
	v_fmac_f32_e32 v187, v127, v57
	v_fmac_f32_e32 v188, v127, v58
	v_fmac_f32_e32 v189, v127, v59
	v_fmac_f32_e32 v182, v190, v52
	v_fmac_f32_e32 v183, v190, v53
	v_fmac_f32_e32 v184, v190, v54
	v_fmac_f32_e32 v185, v190, v55
	v_fmac_f32_e32 v186, v191, v52
	v_fmac_f32_e32 v187, v191, v53
	v_fmac_f32_e32 v188, v191, v54
	v_fmac_f32_e32 v189, v191, v55
	ds_read_b128 v[48:51], v151 offset:9472
	ds_read_b128 v[52:55], v151 offset:17664
	ds_read_b128 v[56:59], v151 offset:25856
	ds_read_b128 v[60:63], v151 offset:34048
	ds_read_b64 v[126:127], v181 offset:1280
	s_waitcnt lgkmcnt(11)
	v_mul_f32_e32 v190, v182, v8
	v_mul_f32_e32 v191, v186, v8
	v_mul_f32_e32 v238, v182, v20
	v_mul_f32_e32 v239, v186, v20
	v_fmac_f32_e32 v190, v183, v9
	v_fmac_f32_e32 v191, v187, v9
	v_fmac_f32_e32 v238, v183, v21
	v_fmac_f32_e32 v239, v187, v21
	v_fmac_f32_e32 v190, v184, v10
	v_fmac_f32_e32 v191, v188, v10
	v_fmac_f32_e32 v238, v184, v22
	v_fmac_f32_e32 v239, v188, v22
	v_fmac_f32_e32 v190, v185, v11
	v_fmac_f32_e32 v191, v189, v11
	v_fmac_f32_e32 v238, v185, v23
	v_fmac_f32_e32 v239, v189, v23
	v_add_f32_dpp v190, v190, v190 quad_perm:[1,0,3,2] row_mask:0xf bank_mask:0xf bound_ctrl:1
	v_add_f32_dpp v191, v191, v191 quad_perm:[1,0,3,2] row_mask:0xf bank_mask:0xf bound_ctrl:1
	v_add_f32_dpp v238, v238, v238 quad_perm:[1,0,3,2] row_mask:0xf bank_mask:0xf bound_ctrl:1
	v_add_f32_dpp v239, v239, v239 quad_perm:[1,0,3,2] row_mask:0xf bank_mask:0xf bound_ctrl:1
	v_add_f32_dpp v190, v190, v190 quad_perm:[2,3,0,1] row_mask:0xf bank_mask:0xf bound_ctrl:1
	v_add_f32_dpp v191, v191, v191 quad_perm:[2,3,0,1] row_mask:0xf bank_mask:0xf bound_ctrl:1
	v_add_f32_dpp v238, v238, v238 quad_perm:[2,3,0,1] row_mask:0xf bank_mask:0xf bound_ctrl:1
	v_add_f32_dpp v239, v239, v239 quad_perm:[2,3,0,1] row_mask:0xf bank_mask:0xf bound_ctrl:1
	v_add_f32_dpp v190, v190, v190 row_half_mirror row_mask:0xf bank_mask:0xf bound_ctrl:1
	v_add_f32_dpp v191, v191, v191 row_half_mirror row_mask:0xf bank_mask:0xf bound_ctrl:1
	v_fmac_f32_e32 v182, v64, v16
	v_fmac_f32_e32 v183, v64, v17
	v_add_f32_dpp v190, v190, v190 row_mirror row_mask:0xf bank_mask:0xf bound_ctrl:1
	v_add_f32_dpp v191, v191, v191 row_mirror row_mask:0xf bank_mask:0xf bound_ctrl:1
	v_fmac_f32_e32 v184, v64, v18
	v_fmac_f32_e32 v185, v64, v19
	v_fmac_f32_e32 v186, v65, v16
	v_fmac_f32_e32 v187, v65, v17
	v_fmac_f32_e32 v188, v65, v18
	v_fmac_f32_e32 v189, v65, v19
	v_fmac_f32_e32 v182, v190, v12
	v_fmac_f32_e32 v183, v190, v13
	v_fmac_f32_e32 v184, v190, v14
	v_fmac_f32_e32 v185, v190, v15
	v_fmac_f32_e32 v186, v191, v12
	v_fmac_f32_e32 v187, v191, v13
	v_fmac_f32_e32 v188, v191, v14
	v_fmac_f32_e32 v189, v191, v15
	s_mov_b64 exec, s[10:11]
	ds_write2st64_b64 v192, v[128:129], v[238:239] offset0:4 offset1:6
	s_mov_b64 exec, -1
	ds_read_b128 v[8:11], v151 offset:9728
	ds_read_b128 v[12:15], v151 offset:17920
	ds_read_b128 v[16:19], v151 offset:26112
	ds_read_b128 v[20:23], v151 offset:34304
	ds_read_b64 v[64:65], v181 offset:1536
	s_waitcnt lgkmcnt(11)
	v_mul_f32_e32 v190, v182, v28
	v_mul_f32_e32 v191, v186, v28
	v_mul_f32_e32 v128, v182, v40
	v_mul_f32_e32 v129, v186, v40
	v_fmac_f32_e32 v190, v183, v29
	v_fmac_f32_e32 v191, v187, v29
	v_fmac_f32_e32 v128, v183, v41
	v_fmac_f32_e32 v129, v187, v41
	v_fmac_f32_e32 v190, v184, v30
	v_fmac_f32_e32 v191, v188, v30
	v_fmac_f32_e32 v128, v184, v42
	v_fmac_f32_e32 v129, v188, v42
	v_fmac_f32_e32 v190, v185, v31
	v_fmac_f32_e32 v191, v189, v31
	v_fmac_f32_e32 v128, v185, v43
	v_fmac_f32_e32 v129, v189, v43
	v_add_f32_dpp v190, v190, v190 quad_perm:[1,0,3,2] row_mask:0xf bank_mask:0xf bound_ctrl:1
	v_add_f32_dpp v191, v191, v191 quad_perm:[1,0,3,2] row_mask:0xf bank_mask:0xf bound_ctrl:1
	v_add_f32_dpp v128, v128, v128 quad_perm:[1,0,3,2] row_mask:0xf bank_mask:0xf bound_ctrl:1
	v_add_f32_dpp v129, v129, v129 quad_perm:[1,0,3,2] row_mask:0xf bank_mask:0xf bound_ctrl:1
	v_add_f32_dpp v190, v190, v190 quad_perm:[2,3,0,1] row_mask:0xf bank_mask:0xf bound_ctrl:1
	v_add_f32_dpp v191, v191, v191 quad_perm:[2,3,0,1] row_mask:0xf bank_mask:0xf bound_ctrl:1
	v_add_f32_dpp v128, v128, v128 quad_perm:[2,3,0,1] row_mask:0xf bank_mask:0xf bound_ctrl:1
	v_add_f32_dpp v129, v129, v129 quad_perm:[2,3,0,1] row_mask:0xf bank_mask:0xf bound_ctrl:1
	v_add_f32_dpp v190, v190, v190 row_half_mirror row_mask:0xf bank_mask:0xf bound_ctrl:1
	v_add_f32_dpp v191, v191, v191 row_half_mirror row_mask:0xf bank_mask:0xf bound_ctrl:1
	v_fmac_f32_e32 v182, v66, v36
	v_fmac_f32_e32 v183, v66, v37
	v_add_f32_dpp v190, v190, v190 row_mirror row_mask:0xf bank_mask:0xf bound_ctrl:1
	v_add_f32_dpp v191, v191, v191 row_mirror row_mask:0xf bank_mask:0xf bound_ctrl:1
	v_fmac_f32_e32 v184, v66, v38
	v_fmac_f32_e32 v185, v66, v39
	v_fmac_f32_e32 v186, v67, v36
	v_fmac_f32_e32 v187, v67, v37
	v_fmac_f32_e32 v188, v67, v38
	v_fmac_f32_e32 v189, v67, v39
	v_fmac_f32_e32 v182, v190, v32
	v_fmac_f32_e32 v183, v190, v33
	v_fmac_f32_e32 v184, v190, v34
	v_fmac_f32_e32 v185, v190, v35
	v_fmac_f32_e32 v186, v191, v32
	v_fmac_f32_e32 v187, v191, v33
	v_fmac_f32_e32 v188, v191, v34
	v_fmac_f32_e32 v189, v191, v35
	ds_read_b128 v[28:31], v151 offset:9984
	ds_read_b128 v[32:35], v151 offset:18176
	ds_read_b128 v[36:39], v151 offset:26368
	ds_read_b128 v[40:43], v151 offset:34560
	ds_read_b64 v[66:67], v181 offset:1792
	s_waitcnt lgkmcnt(11)
	v_mul_f32_e32 v190, v182, v48
	v_mul_f32_e32 v191, v186, v48
	v_mul_f32_e32 v238, v182, v60
	v_mul_f32_e32 v239, v186, v60
	v_fmac_f32_e32 v190, v183, v49
	v_fmac_f32_e32 v191, v187, v49
	v_fmac_f32_e32 v238, v183, v61
	v_fmac_f32_e32 v239, v187, v61
	v_fmac_f32_e32 v190, v184, v50
	v_fmac_f32_e32 v191, v188, v50
	v_fmac_f32_e32 v238, v184, v62
	v_fmac_f32_e32 v239, v188, v62
	v_fmac_f32_e32 v190, v185, v51
	v_fmac_f32_e32 v191, v189, v51
	v_fmac_f32_e32 v238, v185, v63
	v_fmac_f32_e32 v239, v189, v63
	v_add_f32_dpp v190, v190, v190 quad_perm:[1,0,3,2] row_mask:0xf bank_mask:0xf bound_ctrl:1
	v_add_f32_dpp v191, v191, v191 quad_perm:[1,0,3,2] row_mask:0xf bank_mask:0xf bound_ctrl:1
	v_add_f32_dpp v238, v238, v238 quad_perm:[1,0,3,2] row_mask:0xf bank_mask:0xf bound_ctrl:1
	v_add_f32_dpp v239, v239, v239 quad_perm:[1,0,3,2] row_mask:0xf bank_mask:0xf bound_ctrl:1
	v_add_f32_dpp v190, v190, v190 quad_perm:[2,3,0,1] row_mask:0xf bank_mask:0xf bound_ctrl:1
	v_add_f32_dpp v191, v191, v191 quad_perm:[2,3,0,1] row_mask:0xf bank_mask:0xf bound_ctrl:1
	v_add_f32_dpp v238, v238, v238 quad_perm:[2,3,0,1] row_mask:0xf bank_mask:0xf bound_ctrl:1
	v_add_f32_dpp v239, v239, v239 quad_perm:[2,3,0,1] row_mask:0xf bank_mask:0xf bound_ctrl:1
	v_add_f32_dpp v190, v190, v190 row_half_mirror row_mask:0xf bank_mask:0xf bound_ctrl:1
	v_add_f32_dpp v191, v191, v191 row_half_mirror row_mask:0xf bank_mask:0xf bound_ctrl:1
	v_fmac_f32_e32 v182, v126, v56
	v_fmac_f32_e32 v183, v126, v57
	v_add_f32_dpp v190, v190, v190 row_mirror row_mask:0xf bank_mask:0xf bound_ctrl:1
	v_add_f32_dpp v191, v191, v191 row_mirror row_mask:0xf bank_mask:0xf bound_ctrl:1
	v_fmac_f32_e32 v184, v126, v58
	v_fmac_f32_e32 v185, v126, v59
	v_fmac_f32_e32 v186, v127, v56
	v_fmac_f32_e32 v187, v127, v57
	v_fmac_f32_e32 v188, v127, v58
	v_fmac_f32_e32 v189, v127, v59
	v_fmac_f32_e32 v182, v190, v52
	v_fmac_f32_e32 v183, v190, v53
	v_fmac_f32_e32 v184, v190, v54
	v_fmac_f32_e32 v185, v190, v55
	v_fmac_f32_e32 v186, v191, v52
	v_fmac_f32_e32 v187, v191, v53
	v_fmac_f32_e32 v188, v191, v54
	v_fmac_f32_e32 v189, v191, v55
	s_mov_b64 exec, s[10:11]
	ds_write2st64_b64 v192, v[128:129], v[238:239] offset0:8 offset1:10
	s_mov_b64 exec, -1
	ds_read_b128 v[48:51], v151 offset:10240
	ds_read_b128 v[52:55], v151 offset:18432
	ds_read_b128 v[56:59], v151 offset:26624
	ds_read_b128 v[60:63], v151 offset:34816
	ds_read_b64 v[126:127], v181 offset:2048
	s_waitcnt lgkmcnt(11)
	v_mul_f32_e32 v190, v182, v8
	v_mul_f32_e32 v191, v186, v8
	v_mul_f32_e32 v128, v182, v20
	v_mul_f32_e32 v129, v186, v20
	v_fmac_f32_e32 v190, v183, v9
	v_fmac_f32_e32 v191, v187, v9
	v_fmac_f32_e32 v128, v183, v21
	v_fmac_f32_e32 v129, v187, v21
	v_fmac_f32_e32 v190, v184, v10
	v_fmac_f32_e32 v191, v188, v10
	v_fmac_f32_e32 v128, v184, v22
	v_fmac_f32_e32 v129, v188, v22
	v_fmac_f32_e32 v190, v185, v11
	v_fmac_f32_e32 v191, v189, v11
	v_fmac_f32_e32 v128, v185, v23
	v_fmac_f32_e32 v129, v189, v23
	v_add_f32_dpp v190, v190, v190 quad_perm:[1,0,3,2] row_mask:0xf bank_mask:0xf bound_ctrl:1
	v_add_f32_dpp v191, v191, v191 quad_perm:[1,0,3,2] row_mask:0xf bank_mask:0xf bound_ctrl:1
	v_add_f32_dpp v128, v128, v128 quad_perm:[1,0,3,2] row_mask:0xf bank_mask:0xf bound_ctrl:1
	v_add_f32_dpp v129, v129, v129 quad_perm:[1,0,3,2] row_mask:0xf bank_mask:0xf bound_ctrl:1
	v_add_f32_dpp v190, v190, v190 quad_perm:[2,3,0,1] row_mask:0xf bank_mask:0xf bound_ctrl:1
	v_add_f32_dpp v191, v191, v191 quad_perm:[2,3,0,1] row_mask:0xf bank_mask:0xf bound_ctrl:1
	v_add_f32_dpp v128, v128, v128 quad_perm:[2,3,0,1] row_mask:0xf bank_mask:0xf bound_ctrl:1
	v_add_f32_dpp v129, v129, v129 quad_perm:[2,3,0,1] row_mask:0xf bank_mask:0xf bound_ctrl:1
	v_add_f32_dpp v190, v190, v190 row_half_mirror row_mask:0xf bank_mask:0xf bound_ctrl:1
	v_add_f32_dpp v191, v191, v191 row_half_mirror row_mask:0xf bank_mask:0xf bound_ctrl:1
	v_fmac_f32_e32 v182, v64, v16
	v_fmac_f32_e32 v183, v64, v17
	v_add_f32_dpp v190, v190, v190 row_mirror row_mask:0xf bank_mask:0xf bound_ctrl:1
	v_add_f32_dpp v191, v191, v191 row_mirror row_mask:0xf bank_mask:0xf bound_ctrl:1
	v_fmac_f32_e32 v184, v64, v18
	v_fmac_f32_e32 v185, v64, v19
	v_fmac_f32_e32 v186, v65, v16
	v_fmac_f32_e32 v187, v65, v17
	v_fmac_f32_e32 v188, v65, v18
	v_fmac_f32_e32 v189, v65, v19
	v_fmac_f32_e32 v182, v190, v12
	v_fmac_f32_e32 v183, v190, v13
	v_fmac_f32_e32 v184, v190, v14
	v_fmac_f32_e32 v185, v190, v15
	v_fmac_f32_e32 v186, v191, v12
	v_fmac_f32_e32 v187, v191, v13
	v_fmac_f32_e32 v188, v191, v14
	v_fmac_f32_e32 v189, v191, v15
	ds_read_b128 v[8:11], v151 offset:10496
	ds_read_b128 v[12:15], v151 offset:18688
	ds_read_b128 v[16:19], v151 offset:26880
	ds_read_b128 v[20:23], v151 offset:35072
	ds_read_b64 v[64:65], v181 offset:2304
	s_waitcnt lgkmcnt(11)
	v_mul_f32_e32 v190, v182, v28
	v_mul_f32_e32 v191, v186, v28
	v_mul_f32_e32 v238, v182, v40
	v_mul_f32_e32 v239, v186, v40
	v_fmac_f32_e32 v190, v183, v29
	v_fmac_f32_e32 v191, v187, v29
	v_fmac_f32_e32 v238, v183, v41
	v_fmac_f32_e32 v239, v187, v41
	v_fmac_f32_e32 v190, v184, v30
	v_fmac_f32_e32 v191, v188, v30
	v_fmac_f32_e32 v238, v184, v42
	v_fmac_f32_e32 v239, v188, v42
	v_fmac_f32_e32 v190, v185, v31
	v_fmac_f32_e32 v191, v189, v31
	v_fmac_f32_e32 v238, v185, v43
	v_fmac_f32_e32 v239, v189, v43
	v_add_f32_dpp v190, v190, v190 quad_perm:[1,0,3,2] row_mask:0xf bank_mask:0xf bound_ctrl:1
	v_add_f32_dpp v191, v191, v191 quad_perm:[1,0,3,2] row_mask:0xf bank_mask:0xf bound_ctrl:1
	v_add_f32_dpp v238, v238, v238 quad_perm:[1,0,3,2] row_mask:0xf bank_mask:0xf bound_ctrl:1
	v_add_f32_dpp v239, v239, v239 quad_perm:[1,0,3,2] row_mask:0xf bank_mask:0xf bound_ctrl:1
	v_add_f32_dpp v190, v190, v190 quad_perm:[2,3,0,1] row_mask:0xf bank_mask:0xf bound_ctrl:1
	v_add_f32_dpp v191, v191, v191 quad_perm:[2,3,0,1] row_mask:0xf bank_mask:0xf bound_ctrl:1
	v_add_f32_dpp v238, v238, v238 quad_perm:[2,3,0,1] row_mask:0xf bank_mask:0xf bound_ctrl:1
	v_add_f32_dpp v239, v239, v239 quad_perm:[2,3,0,1] row_mask:0xf bank_mask:0xf bound_ctrl:1
	v_add_f32_dpp v190, v190, v190 row_half_mirror row_mask:0xf bank_mask:0xf bound_ctrl:1
	v_add_f32_dpp v191, v191, v191 row_half_mirror row_mask:0xf bank_mask:0xf bound_ctrl:1
	v_fmac_f32_e32 v182, v66, v36
	v_fmac_f32_e32 v183, v66, v37
	v_add_f32_dpp v190, v190, v190 row_mirror row_mask:0xf bank_mask:0xf bound_ctrl:1
	v_add_f32_dpp v191, v191, v191 row_mirror row_mask:0xf bank_mask:0xf bound_ctrl:1
	v_fmac_f32_e32 v184, v66, v38
	v_fmac_f32_e32 v185, v66, v39
	v_fmac_f32_e32 v186, v67, v36
	v_fmac_f32_e32 v187, v67, v37
	v_fmac_f32_e32 v188, v67, v38
	v_fmac_f32_e32 v189, v67, v39
	v_fmac_f32_e32 v182, v190, v32
	v_fmac_f32_e32 v183, v190, v33
	v_fmac_f32_e32 v184, v190, v34
	v_fmac_f32_e32 v185, v190, v35
	v_fmac_f32_e32 v186, v191, v32
	v_fmac_f32_e32 v187, v191, v33
	v_fmac_f32_e32 v188, v191, v34
	v_fmac_f32_e32 v189, v191, v35
	s_mov_b64 exec, s[10:11]
	ds_write2st64_b64 v192, v[128:129], v[238:239] offset0:12 offset1:14
	s_mov_b64 exec, -1
	ds_read_b128 v[28:31], v151 offset:10752
	ds_read_b128 v[32:35], v151 offset:18944
	ds_read_b128 v[36:39], v151 offset:27136
	ds_read_b128 v[40:43], v151 offset:35328
	ds_read_b64 v[66:67], v181 offset:2560
	s_waitcnt lgkmcnt(11)
	v_mul_f32_e32 v190, v182, v48
	v_mul_f32_e32 v191, v186, v48
	v_mul_f32_e32 v128, v182, v60
	v_mul_f32_e32 v129, v186, v60
	v_fmac_f32_e32 v190, v183, v49
	v_fmac_f32_e32 v191, v187, v49
	v_fmac_f32_e32 v128, v183, v61
	v_fmac_f32_e32 v129, v187, v61
	v_fmac_f32_e32 v190, v184, v50
	v_fmac_f32_e32 v191, v188, v50
	v_fmac_f32_e32 v128, v184, v62
	v_fmac_f32_e32 v129, v188, v62
	v_fmac_f32_e32 v190, v185, v51
	v_fmac_f32_e32 v191, v189, v51
	v_fmac_f32_e32 v128, v185, v63
	v_fmac_f32_e32 v129, v189, v63
	v_add_f32_dpp v190, v190, v190 quad_perm:[1,0,3,2] row_mask:0xf bank_mask:0xf bound_ctrl:1
	v_add_f32_dpp v191, v191, v191 quad_perm:[1,0,3,2] row_mask:0xf bank_mask:0xf bound_ctrl:1
	v_add_f32_dpp v128, v128, v128 quad_perm:[1,0,3,2] row_mask:0xf bank_mask:0xf bound_ctrl:1
	v_add_f32_dpp v129, v129, v129 quad_perm:[1,0,3,2] row_mask:0xf bank_mask:0xf bound_ctrl:1
	v_add_f32_dpp v190, v190, v190 quad_perm:[2,3,0,1] row_mask:0xf bank_mask:0xf bound_ctrl:1
	v_add_f32_dpp v191, v191, v191 quad_perm:[2,3,0,1] row_mask:0xf bank_mask:0xf bound_ctrl:1
	v_add_f32_dpp v128, v128, v128 quad_perm:[2,3,0,1] row_mask:0xf bank_mask:0xf bound_ctrl:1
	v_add_f32_dpp v129, v129, v129 quad_perm:[2,3,0,1] row_mask:0xf bank_mask:0xf bound_ctrl:1
	v_add_f32_dpp v190, v190, v190 row_half_mirror row_mask:0xf bank_mask:0xf bound_ctrl:1
	v_add_f32_dpp v191, v191, v191 row_half_mirror row_mask:0xf bank_mask:0xf bound_ctrl:1
	v_fmac_f32_e32 v182, v126, v56
	v_fmac_f32_e32 v183, v126, v57
	v_add_f32_dpp v190, v190, v190 row_mirror row_mask:0xf bank_mask:0xf bound_ctrl:1
	v_add_f32_dpp v191, v191, v191 row_mirror row_mask:0xf bank_mask:0xf bound_ctrl:1
	v_fmac_f32_e32 v184, v126, v58
	v_fmac_f32_e32 v185, v126, v59
	v_fmac_f32_e32 v186, v127, v56
	v_fmac_f32_e32 v187, v127, v57
	v_fmac_f32_e32 v188, v127, v58
	v_fmac_f32_e32 v189, v127, v59
	v_fmac_f32_e32 v182, v190, v52
	v_fmac_f32_e32 v183, v190, v53
	v_fmac_f32_e32 v184, v190, v54
	v_fmac_f32_e32 v185, v190, v55
	v_fmac_f32_e32 v186, v191, v52
	v_fmac_f32_e32 v187, v191, v53
	v_fmac_f32_e32 v188, v191, v54
	v_fmac_f32_e32 v189, v191, v55
	ds_read_b128 v[48:51], v151 offset:11008
	ds_read_b128 v[52:55], v151 offset:19200
	ds_read_b128 v[56:59], v151 offset:27392
	ds_read_b128 v[60:63], v151 offset:35584
	ds_read_b64 v[126:127], v181 offset:2816
	s_waitcnt lgkmcnt(11)
	v_mul_f32_e32 v190, v182, v8
	v_mul_f32_e32 v191, v186, v8
	v_mul_f32_e32 v238, v182, v20
	v_mul_f32_e32 v239, v186, v20
	v_fmac_f32_e32 v190, v183, v9
	v_fmac_f32_e32 v191, v187, v9
	v_fmac_f32_e32 v238, v183, v21
	v_fmac_f32_e32 v239, v187, v21
	v_fmac_f32_e32 v190, v184, v10
	v_fmac_f32_e32 v191, v188, v10
	v_fmac_f32_e32 v238, v184, v22
	v_fmac_f32_e32 v239, v188, v22
	v_fmac_f32_e32 v190, v185, v11
	v_fmac_f32_e32 v191, v189, v11
	v_fmac_f32_e32 v238, v185, v23
	v_fmac_f32_e32 v239, v189, v23
	v_add_f32_dpp v190, v190, v190 quad_perm:[1,0,3,2] row_mask:0xf bank_mask:0xf bound_ctrl:1
	v_add_f32_dpp v191, v191, v191 quad_perm:[1,0,3,2] row_mask:0xf bank_mask:0xf bound_ctrl:1
	v_add_f32_dpp v238, v238, v238 quad_perm:[1,0,3,2] row_mask:0xf bank_mask:0xf bound_ctrl:1
	v_add_f32_dpp v239, v239, v239 quad_perm:[1,0,3,2] row_mask:0xf bank_mask:0xf bound_ctrl:1
	v_add_f32_dpp v190, v190, v190 quad_perm:[2,3,0,1] row_mask:0xf bank_mask:0xf bound_ctrl:1
	v_add_f32_dpp v191, v191, v191 quad_perm:[2,3,0,1] row_mask:0xf bank_mask:0xf bound_ctrl:1
	v_add_f32_dpp v238, v238, v238 quad_perm:[2,3,0,1] row_mask:0xf bank_mask:0xf bound_ctrl:1
	v_add_f32_dpp v239, v239, v239 quad_perm:[2,3,0,1] row_mask:0xf bank_mask:0xf bound_ctrl:1
	v_add_f32_dpp v190, v190, v190 row_half_mirror row_mask:0xf bank_mask:0xf bound_ctrl:1
	v_add_f32_dpp v191, v191, v191 row_half_mirror row_mask:0xf bank_mask:0xf bound_ctrl:1
	v_fmac_f32_e32 v182, v64, v16
	v_fmac_f32_e32 v183, v64, v17
	v_add_f32_dpp v190, v190, v190 row_mirror row_mask:0xf bank_mask:0xf bound_ctrl:1
	v_add_f32_dpp v191, v191, v191 row_mirror row_mask:0xf bank_mask:0xf bound_ctrl:1
	v_fmac_f32_e32 v184, v64, v18
	v_fmac_f32_e32 v185, v64, v19
	v_fmac_f32_e32 v186, v65, v16
	v_fmac_f32_e32 v187, v65, v17
	v_fmac_f32_e32 v188, v65, v18
	v_fmac_f32_e32 v189, v65, v19
	v_fmac_f32_e32 v182, v190, v12
	v_fmac_f32_e32 v183, v190, v13
	v_fmac_f32_e32 v184, v190, v14
	v_fmac_f32_e32 v185, v190, v15
	v_fmac_f32_e32 v186, v191, v12
	v_fmac_f32_e32 v187, v191, v13
	v_fmac_f32_e32 v188, v191, v14
	v_fmac_f32_e32 v189, v191, v15
	s_mov_b64 exec, s[10:11]
	ds_write2st64_b64 v192, v[128:129], v[238:239] offset0:16 offset1:18
	s_mov_b64 exec, -1
	ds_read_b128 v[8:11], v151 offset:11264
	ds_read_b128 v[12:15], v151 offset:19456
	ds_read_b128 v[16:19], v151 offset:27648
	ds_read_b128 v[20:23], v151 offset:35840
	ds_read_b64 v[64:65], v181 offset:3072
	s_waitcnt lgkmcnt(11)
	v_mul_f32_e32 v190, v182, v28
	v_mul_f32_e32 v191, v186, v28
	v_mul_f32_e32 v128, v182, v40
	v_mul_f32_e32 v129, v186, v40
	v_fmac_f32_e32 v190, v183, v29
	v_fmac_f32_e32 v191, v187, v29
	v_fmac_f32_e32 v128, v183, v41
	v_fmac_f32_e32 v129, v187, v41
	v_fmac_f32_e32 v190, v184, v30
	v_fmac_f32_e32 v191, v188, v30
	v_fmac_f32_e32 v128, v184, v42
	v_fmac_f32_e32 v129, v188, v42
	v_fmac_f32_e32 v190, v185, v31
	v_fmac_f32_e32 v191, v189, v31
	v_fmac_f32_e32 v128, v185, v43
	v_fmac_f32_e32 v129, v189, v43
	v_add_f32_dpp v190, v190, v190 quad_perm:[1,0,3,2] row_mask:0xf bank_mask:0xf bound_ctrl:1
	v_add_f32_dpp v191, v191, v191 quad_perm:[1,0,3,2] row_mask:0xf bank_mask:0xf bound_ctrl:1
	v_add_f32_dpp v128, v128, v128 quad_perm:[1,0,3,2] row_mask:0xf bank_mask:0xf bound_ctrl:1
	v_add_f32_dpp v129, v129, v129 quad_perm:[1,0,3,2] row_mask:0xf bank_mask:0xf bound_ctrl:1
	v_add_f32_dpp v190, v190, v190 quad_perm:[2,3,0,1] row_mask:0xf bank_mask:0xf bound_ctrl:1
	v_add_f32_dpp v191, v191, v191 quad_perm:[2,3,0,1] row_mask:0xf bank_mask:0xf bound_ctrl:1
	v_add_f32_dpp v128, v128, v128 quad_perm:[2,3,0,1] row_mask:0xf bank_mask:0xf bound_ctrl:1
	v_add_f32_dpp v129, v129, v129 quad_perm:[2,3,0,1] row_mask:0xf bank_mask:0xf bound_ctrl:1
	v_add_f32_dpp v190, v190, v190 row_half_mirror row_mask:0xf bank_mask:0xf bound_ctrl:1
	v_add_f32_dpp v191, v191, v191 row_half_mirror row_mask:0xf bank_mask:0xf bound_ctrl:1
	v_fmac_f32_e32 v182, v66, v36
	v_fmac_f32_e32 v183, v66, v37
	v_add_f32_dpp v190, v190, v190 row_mirror row_mask:0xf bank_mask:0xf bound_ctrl:1
	v_add_f32_dpp v191, v191, v191 row_mirror row_mask:0xf bank_mask:0xf bound_ctrl:1
	v_fmac_f32_e32 v184, v66, v38
	v_fmac_f32_e32 v185, v66, v39
	v_fmac_f32_e32 v186, v67, v36
	v_fmac_f32_e32 v187, v67, v37
	v_fmac_f32_e32 v188, v67, v38
	v_fmac_f32_e32 v189, v67, v39
	v_fmac_f32_e32 v182, v190, v32
	v_fmac_f32_e32 v183, v190, v33
	v_fmac_f32_e32 v184, v190, v34
	v_fmac_f32_e32 v185, v190, v35
	v_fmac_f32_e32 v186, v191, v32
	v_fmac_f32_e32 v187, v191, v33
	v_fmac_f32_e32 v188, v191, v34
	v_fmac_f32_e32 v189, v191, v35
	ds_read_b128 v[28:31], v151 offset:11520
	ds_read_b128 v[32:35], v151 offset:19712
	ds_read_b128 v[36:39], v151 offset:27904
	ds_read_b128 v[40:43], v151 offset:36096
	ds_read_b64 v[66:67], v181 offset:3328
	s_waitcnt lgkmcnt(11)
	v_mul_f32_e32 v190, v182, v48
	v_mul_f32_e32 v191, v186, v48
	v_mul_f32_e32 v238, v182, v60
	v_mul_f32_e32 v239, v186, v60
	v_fmac_f32_e32 v190, v183, v49
	v_fmac_f32_e32 v191, v187, v49
	v_fmac_f32_e32 v238, v183, v61
	v_fmac_f32_e32 v239, v187, v61
	v_fmac_f32_e32 v190, v184, v50
	v_fmac_f32_e32 v191, v188, v50
	v_fmac_f32_e32 v238, v184, v62
	v_fmac_f32_e32 v239, v188, v62
	v_fmac_f32_e32 v190, v185, v51
	v_fmac_f32_e32 v191, v189, v51
	v_fmac_f32_e32 v238, v185, v63
	v_fmac_f32_e32 v239, v189, v63
	v_add_f32_dpp v190, v190, v190 quad_perm:[1,0,3,2] row_mask:0xf bank_mask:0xf bound_ctrl:1
	v_add_f32_dpp v191, v191, v191 quad_perm:[1,0,3,2] row_mask:0xf bank_mask:0xf bound_ctrl:1
	v_add_f32_dpp v238, v238, v238 quad_perm:[1,0,3,2] row_mask:0xf bank_mask:0xf bound_ctrl:1
	v_add_f32_dpp v239, v239, v239 quad_perm:[1,0,3,2] row_mask:0xf bank_mask:0xf bound_ctrl:1
	v_add_f32_dpp v190, v190, v190 quad_perm:[2,3,0,1] row_mask:0xf bank_mask:0xf bound_ctrl:1
	v_add_f32_dpp v191, v191, v191 quad_perm:[2,3,0,1] row_mask:0xf bank_mask:0xf bound_ctrl:1
	v_add_f32_dpp v238, v238, v238 quad_perm:[2,3,0,1] row_mask:0xf bank_mask:0xf bound_ctrl:1
	v_add_f32_dpp v239, v239, v239 quad_perm:[2,3,0,1] row_mask:0xf bank_mask:0xf bound_ctrl:1
	v_add_f32_dpp v190, v190, v190 row_half_mirror row_mask:0xf bank_mask:0xf bound_ctrl:1
	v_add_f32_dpp v191, v191, v191 row_half_mirror row_mask:0xf bank_mask:0xf bound_ctrl:1
	v_fmac_f32_e32 v182, v126, v56
	v_fmac_f32_e32 v183, v126, v57
	v_add_f32_dpp v190, v190, v190 row_mirror row_mask:0xf bank_mask:0xf bound_ctrl:1
	v_add_f32_dpp v191, v191, v191 row_mirror row_mask:0xf bank_mask:0xf bound_ctrl:1
	v_fmac_f32_e32 v184, v126, v58
	v_fmac_f32_e32 v185, v126, v59
	v_fmac_f32_e32 v186, v127, v56
	v_fmac_f32_e32 v187, v127, v57
	v_fmac_f32_e32 v188, v127, v58
	v_fmac_f32_e32 v189, v127, v59
	v_fmac_f32_e32 v182, v190, v52
	v_fmac_f32_e32 v183, v190, v53
	v_fmac_f32_e32 v184, v190, v54
	v_fmac_f32_e32 v185, v190, v55
	v_fmac_f32_e32 v186, v191, v52
	v_fmac_f32_e32 v187, v191, v53
	v_fmac_f32_e32 v188, v191, v54
	v_fmac_f32_e32 v189, v191, v55
	s_mov_b64 exec, s[10:11]
	ds_write2st64_b64 v192, v[128:129], v[238:239] offset0:20 offset1:22
	s_mov_b64 exec, -1
	ds_read_b128 v[48:51], v151 offset:11776
	ds_read_b128 v[52:55], v151 offset:19968
	ds_read_b128 v[56:59], v151 offset:28160
	ds_read_b128 v[60:63], v151 offset:36352
	ds_read_b64 v[126:127], v181 offset:3584
	s_waitcnt lgkmcnt(11)
	v_mul_f32_e32 v190, v182, v8
	v_mul_f32_e32 v191, v186, v8
	v_mul_f32_e32 v128, v182, v20
	v_mul_f32_e32 v129, v186, v20
	v_fmac_f32_e32 v190, v183, v9
	v_fmac_f32_e32 v191, v187, v9
	v_fmac_f32_e32 v128, v183, v21
	v_fmac_f32_e32 v129, v187, v21
	v_fmac_f32_e32 v190, v184, v10
	v_fmac_f32_e32 v191, v188, v10
	v_fmac_f32_e32 v128, v184, v22
	v_fmac_f32_e32 v129, v188, v22
	v_fmac_f32_e32 v190, v185, v11
	v_fmac_f32_e32 v191, v189, v11
	v_fmac_f32_e32 v128, v185, v23
	v_fmac_f32_e32 v129, v189, v23
	v_add_f32_dpp v190, v190, v190 quad_perm:[1,0,3,2] row_mask:0xf bank_mask:0xf bound_ctrl:1
	v_add_f32_dpp v191, v191, v191 quad_perm:[1,0,3,2] row_mask:0xf bank_mask:0xf bound_ctrl:1
	v_add_f32_dpp v128, v128, v128 quad_perm:[1,0,3,2] row_mask:0xf bank_mask:0xf bound_ctrl:1
	v_add_f32_dpp v129, v129, v129 quad_perm:[1,0,3,2] row_mask:0xf bank_mask:0xf bound_ctrl:1
	v_add_f32_dpp v190, v190, v190 quad_perm:[2,3,0,1] row_mask:0xf bank_mask:0xf bound_ctrl:1
	v_add_f32_dpp v191, v191, v191 quad_perm:[2,3,0,1] row_mask:0xf bank_mask:0xf bound_ctrl:1
	v_add_f32_dpp v128, v128, v128 quad_perm:[2,3,0,1] row_mask:0xf bank_mask:0xf bound_ctrl:1
	v_add_f32_dpp v129, v129, v129 quad_perm:[2,3,0,1] row_mask:0xf bank_mask:0xf bound_ctrl:1
	v_add_f32_dpp v190, v190, v190 row_half_mirror row_mask:0xf bank_mask:0xf bound_ctrl:1
	v_add_f32_dpp v191, v191, v191 row_half_mirror row_mask:0xf bank_mask:0xf bound_ctrl:1
	v_fmac_f32_e32 v182, v64, v16
	v_fmac_f32_e32 v183, v64, v17
	v_add_f32_dpp v190, v190, v190 row_mirror row_mask:0xf bank_mask:0xf bound_ctrl:1
	v_add_f32_dpp v191, v191, v191 row_mirror row_mask:0xf bank_mask:0xf bound_ctrl:1
	v_fmac_f32_e32 v184, v64, v18
	v_fmac_f32_e32 v185, v64, v19
	v_fmac_f32_e32 v186, v65, v16
	v_fmac_f32_e32 v187, v65, v17
	v_fmac_f32_e32 v188, v65, v18
	v_fmac_f32_e32 v189, v65, v19
	v_fmac_f32_e32 v182, v190, v12
	v_fmac_f32_e32 v183, v190, v13
	v_fmac_f32_e32 v184, v190, v14
	v_fmac_f32_e32 v185, v190, v15
	v_fmac_f32_e32 v186, v191, v12
	v_fmac_f32_e32 v187, v191, v13
	v_fmac_f32_e32 v188, v191, v14
	v_fmac_f32_e32 v189, v191, v15
	ds_read_b128 v[8:11], v151 offset:12032
	ds_read_b128 v[12:15], v151 offset:20224
	ds_read_b128 v[16:19], v151 offset:28416
	ds_read_b128 v[20:23], v151 offset:36608
	ds_read_b64 v[64:65], v181 offset:3840
	s_waitcnt lgkmcnt(11)
	v_mul_f32_e32 v190, v182, v28
	v_mul_f32_e32 v191, v186, v28
	v_mul_f32_e32 v238, v182, v40
	v_mul_f32_e32 v239, v186, v40
	v_fmac_f32_e32 v190, v183, v29
	v_fmac_f32_e32 v191, v187, v29
	v_fmac_f32_e32 v238, v183, v41
	v_fmac_f32_e32 v239, v187, v41
	v_fmac_f32_e32 v190, v184, v30
	v_fmac_f32_e32 v191, v188, v30
	v_fmac_f32_e32 v238, v184, v42
	v_fmac_f32_e32 v239, v188, v42
	v_fmac_f32_e32 v190, v185, v31
	v_fmac_f32_e32 v191, v189, v31
	v_fmac_f32_e32 v238, v185, v43
	v_fmac_f32_e32 v239, v189, v43
	v_add_f32_dpp v190, v190, v190 quad_perm:[1,0,3,2] row_mask:0xf bank_mask:0xf bound_ctrl:1
	v_add_f32_dpp v191, v191, v191 quad_perm:[1,0,3,2] row_mask:0xf bank_mask:0xf bound_ctrl:1
	v_add_f32_dpp v238, v238, v238 quad_perm:[1,0,3,2] row_mask:0xf bank_mask:0xf bound_ctrl:1
	v_add_f32_dpp v239, v239, v239 quad_perm:[1,0,3,2] row_mask:0xf bank_mask:0xf bound_ctrl:1
	v_add_f32_dpp v190, v190, v190 quad_perm:[2,3,0,1] row_mask:0xf bank_mask:0xf bound_ctrl:1
	v_add_f32_dpp v191, v191, v191 quad_perm:[2,3,0,1] row_mask:0xf bank_mask:0xf bound_ctrl:1
	v_add_f32_dpp v238, v238, v238 quad_perm:[2,3,0,1] row_mask:0xf bank_mask:0xf bound_ctrl:1
	v_add_f32_dpp v239, v239, v239 quad_perm:[2,3,0,1] row_mask:0xf bank_mask:0xf bound_ctrl:1
	v_add_f32_dpp v190, v190, v190 row_half_mirror row_mask:0xf bank_mask:0xf bound_ctrl:1
	v_add_f32_dpp v191, v191, v191 row_half_mirror row_mask:0xf bank_mask:0xf bound_ctrl:1
	v_fmac_f32_e32 v182, v66, v36
	v_fmac_f32_e32 v183, v66, v37
	v_add_f32_dpp v190, v190, v190 row_mirror row_mask:0xf bank_mask:0xf bound_ctrl:1
	v_add_f32_dpp v191, v191, v191 row_mirror row_mask:0xf bank_mask:0xf bound_ctrl:1
	v_fmac_f32_e32 v184, v66, v38
	v_fmac_f32_e32 v185, v66, v39
	v_fmac_f32_e32 v186, v67, v36
	v_fmac_f32_e32 v187, v67, v37
	v_fmac_f32_e32 v188, v67, v38
	v_fmac_f32_e32 v189, v67, v39
	v_fmac_f32_e32 v182, v190, v32
	v_fmac_f32_e32 v183, v190, v33
	v_fmac_f32_e32 v184, v190, v34
	v_fmac_f32_e32 v185, v190, v35
	v_fmac_f32_e32 v186, v191, v32
	v_fmac_f32_e32 v187, v191, v33
	v_fmac_f32_e32 v188, v191, v34
	v_fmac_f32_e32 v189, v191, v35
	s_mov_b64 exec, s[10:11]
	ds_write2st64_b64 v192, v[128:129], v[238:239] offset0:24 offset1:26
	s_mov_b64 exec, -1
	ds_read_b128 v[28:31], v151 offset:12288
	ds_read_b128 v[32:35], v151 offset:20480
	ds_read_b128 v[36:39], v151 offset:28672
	ds_read_b128 v[40:43], v151 offset:36864
	ds_read_b64 v[66:67], v181 offset:4096
	s_waitcnt lgkmcnt(11)
	v_mul_f32_e32 v190, v182, v48
	v_mul_f32_e32 v191, v186, v48
	v_mul_f32_e32 v128, v182, v60
	v_mul_f32_e32 v129, v186, v60
	v_fmac_f32_e32 v190, v183, v49
	v_fmac_f32_e32 v191, v187, v49
	v_fmac_f32_e32 v128, v183, v61
	v_fmac_f32_e32 v129, v187, v61
	v_fmac_f32_e32 v190, v184, v50
	v_fmac_f32_e32 v191, v188, v50
	v_fmac_f32_e32 v128, v184, v62
	v_fmac_f32_e32 v129, v188, v62
	v_fmac_f32_e32 v190, v185, v51
	v_fmac_f32_e32 v191, v189, v51
	v_fmac_f32_e32 v128, v185, v63
	v_fmac_f32_e32 v129, v189, v63
	v_add_f32_dpp v190, v190, v190 quad_perm:[1,0,3,2] row_mask:0xf bank_mask:0xf bound_ctrl:1
	v_add_f32_dpp v191, v191, v191 quad_perm:[1,0,3,2] row_mask:0xf bank_mask:0xf bound_ctrl:1
	v_add_f32_dpp v128, v128, v128 quad_perm:[1,0,3,2] row_mask:0xf bank_mask:0xf bound_ctrl:1
	v_add_f32_dpp v129, v129, v129 quad_perm:[1,0,3,2] row_mask:0xf bank_mask:0xf bound_ctrl:1
	v_add_f32_dpp v190, v190, v190 quad_perm:[2,3,0,1] row_mask:0xf bank_mask:0xf bound_ctrl:1
	v_add_f32_dpp v191, v191, v191 quad_perm:[2,3,0,1] row_mask:0xf bank_mask:0xf bound_ctrl:1
	v_add_f32_dpp v128, v128, v128 quad_perm:[2,3,0,1] row_mask:0xf bank_mask:0xf bound_ctrl:1
	v_add_f32_dpp v129, v129, v129 quad_perm:[2,3,0,1] row_mask:0xf bank_mask:0xf bound_ctrl:1
	v_add_f32_dpp v190, v190, v190 row_half_mirror row_mask:0xf bank_mask:0xf bound_ctrl:1
	v_add_f32_dpp v191, v191, v191 row_half_mirror row_mask:0xf bank_mask:0xf bound_ctrl:1
	v_fmac_f32_e32 v182, v126, v56
	v_fmac_f32_e32 v183, v126, v57
	v_add_f32_dpp v190, v190, v190 row_mirror row_mask:0xf bank_mask:0xf bound_ctrl:1
	v_add_f32_dpp v191, v191, v191 row_mirror row_mask:0xf bank_mask:0xf bound_ctrl:1
	v_fmac_f32_e32 v184, v126, v58
	v_fmac_f32_e32 v185, v126, v59
	v_fmac_f32_e32 v186, v127, v56
	v_fmac_f32_e32 v187, v127, v57
	v_fmac_f32_e32 v188, v127, v58
	v_fmac_f32_e32 v189, v127, v59
	v_fmac_f32_e32 v182, v190, v52
	v_fmac_f32_e32 v183, v190, v53
	v_fmac_f32_e32 v184, v190, v54
	v_fmac_f32_e32 v185, v190, v55
	v_fmac_f32_e32 v186, v191, v52
	v_fmac_f32_e32 v187, v191, v53
	v_fmac_f32_e32 v188, v191, v54
	v_fmac_f32_e32 v189, v191, v55
	ds_read_b128 v[48:51], v151 offset:12544
	ds_read_b128 v[52:55], v151 offset:20736
	ds_read_b128 v[56:59], v151 offset:28928
	ds_read_b128 v[60:63], v151 offset:37120
	ds_read_b64 v[126:127], v181 offset:4352
	s_waitcnt lgkmcnt(11)
	v_mul_f32_e32 v190, v182, v8
	v_mul_f32_e32 v191, v186, v8
	v_mul_f32_e32 v238, v182, v20
	v_mul_f32_e32 v239, v186, v20
	v_fmac_f32_e32 v190, v183, v9
	v_fmac_f32_e32 v191, v187, v9
	v_fmac_f32_e32 v238, v183, v21
	v_fmac_f32_e32 v239, v187, v21
	v_fmac_f32_e32 v190, v184, v10
	v_fmac_f32_e32 v191, v188, v10
	v_fmac_f32_e32 v238, v184, v22
	v_fmac_f32_e32 v239, v188, v22
	v_fmac_f32_e32 v190, v185, v11
	v_fmac_f32_e32 v191, v189, v11
	v_fmac_f32_e32 v238, v185, v23
	v_fmac_f32_e32 v239, v189, v23
	v_add_f32_dpp v190, v190, v190 quad_perm:[1,0,3,2] row_mask:0xf bank_mask:0xf bound_ctrl:1
	v_add_f32_dpp v191, v191, v191 quad_perm:[1,0,3,2] row_mask:0xf bank_mask:0xf bound_ctrl:1
	v_add_f32_dpp v238, v238, v238 quad_perm:[1,0,3,2] row_mask:0xf bank_mask:0xf bound_ctrl:1
	v_add_f32_dpp v239, v239, v239 quad_perm:[1,0,3,2] row_mask:0xf bank_mask:0xf bound_ctrl:1
	v_add_f32_dpp v190, v190, v190 quad_perm:[2,3,0,1] row_mask:0xf bank_mask:0xf bound_ctrl:1
	v_add_f32_dpp v191, v191, v191 quad_perm:[2,3,0,1] row_mask:0xf bank_mask:0xf bound_ctrl:1
	v_add_f32_dpp v238, v238, v238 quad_perm:[2,3,0,1] row_mask:0xf bank_mask:0xf bound_ctrl:1
	v_add_f32_dpp v239, v239, v239 quad_perm:[2,3,0,1] row_mask:0xf bank_mask:0xf bound_ctrl:1
	v_add_f32_dpp v190, v190, v190 row_half_mirror row_mask:0xf bank_mask:0xf bound_ctrl:1
	v_add_f32_dpp v191, v191, v191 row_half_mirror row_mask:0xf bank_mask:0xf bound_ctrl:1
	v_fmac_f32_e32 v182, v64, v16
	v_fmac_f32_e32 v183, v64, v17
	v_add_f32_dpp v190, v190, v190 row_mirror row_mask:0xf bank_mask:0xf bound_ctrl:1
	v_add_f32_dpp v191, v191, v191 row_mirror row_mask:0xf bank_mask:0xf bound_ctrl:1
	v_fmac_f32_e32 v184, v64, v18
	v_fmac_f32_e32 v185, v64, v19
	v_fmac_f32_e32 v186, v65, v16
	v_fmac_f32_e32 v187, v65, v17
	v_fmac_f32_e32 v188, v65, v18
	v_fmac_f32_e32 v189, v65, v19
	v_fmac_f32_e32 v182, v190, v12
	v_fmac_f32_e32 v183, v190, v13
	v_fmac_f32_e32 v184, v190, v14
	v_fmac_f32_e32 v185, v190, v15
	v_fmac_f32_e32 v186, v191, v12
	v_fmac_f32_e32 v187, v191, v13
	v_fmac_f32_e32 v188, v191, v14
	v_fmac_f32_e32 v189, v191, v15
	s_mov_b64 exec, s[10:11]
	ds_write2st64_b64 v192, v[128:129], v[238:239] offset0:28 offset1:30
	s_mov_b64 exec, -1
	ds_read_b128 v[8:11], v151 offset:12800
	ds_read_b128 v[12:15], v151 offset:20992
	ds_read_b128 v[16:19], v151 offset:29184
	ds_read_b128 v[20:23], v151 offset:37376
	ds_read_b64 v[64:65], v181 offset:4608
	s_waitcnt lgkmcnt(11)
	v_mul_f32_e32 v190, v182, v28
	v_mul_f32_e32 v191, v186, v28
	v_mul_f32_e32 v128, v182, v40
	v_mul_f32_e32 v129, v186, v40
	v_fmac_f32_e32 v190, v183, v29
	v_fmac_f32_e32 v191, v187, v29
	v_fmac_f32_e32 v128, v183, v41
	v_fmac_f32_e32 v129, v187, v41
	v_fmac_f32_e32 v190, v184, v30
	v_fmac_f32_e32 v191, v188, v30
	v_fmac_f32_e32 v128, v184, v42
	v_fmac_f32_e32 v129, v188, v42
	v_fmac_f32_e32 v190, v185, v31
	v_fmac_f32_e32 v191, v189, v31
	v_fmac_f32_e32 v128, v185, v43
	v_fmac_f32_e32 v129, v189, v43
	v_add_f32_dpp v190, v190, v190 quad_perm:[1,0,3,2] row_mask:0xf bank_mask:0xf bound_ctrl:1
	v_add_f32_dpp v191, v191, v191 quad_perm:[1,0,3,2] row_mask:0xf bank_mask:0xf bound_ctrl:1
	v_add_f32_dpp v128, v128, v128 quad_perm:[1,0,3,2] row_mask:0xf bank_mask:0xf bound_ctrl:1
	v_add_f32_dpp v129, v129, v129 quad_perm:[1,0,3,2] row_mask:0xf bank_mask:0xf bound_ctrl:1
	v_add_f32_dpp v190, v190, v190 quad_perm:[2,3,0,1] row_mask:0xf bank_mask:0xf bound_ctrl:1
	v_add_f32_dpp v191, v191, v191 quad_perm:[2,3,0,1] row_mask:0xf bank_mask:0xf bound_ctrl:1
	v_add_f32_dpp v128, v128, v128 quad_perm:[2,3,0,1] row_mask:0xf bank_mask:0xf bound_ctrl:1
	v_add_f32_dpp v129, v129, v129 quad_perm:[2,3,0,1] row_mask:0xf bank_mask:0xf bound_ctrl:1
	v_add_f32_dpp v190, v190, v190 row_half_mirror row_mask:0xf bank_mask:0xf bound_ctrl:1
	v_add_f32_dpp v191, v191, v191 row_half_mirror row_mask:0xf bank_mask:0xf bound_ctrl:1
	v_fmac_f32_e32 v182, v66, v36
	v_fmac_f32_e32 v183, v66, v37
	v_add_f32_dpp v190, v190, v190 row_mirror row_mask:0xf bank_mask:0xf bound_ctrl:1
	v_add_f32_dpp v191, v191, v191 row_mirror row_mask:0xf bank_mask:0xf bound_ctrl:1
	v_fmac_f32_e32 v184, v66, v38
	v_fmac_f32_e32 v185, v66, v39
	v_fmac_f32_e32 v186, v67, v36
	v_fmac_f32_e32 v187, v67, v37
	v_fmac_f32_e32 v188, v67, v38
	v_fmac_f32_e32 v189, v67, v39
	v_fmac_f32_e32 v182, v190, v32
	v_fmac_f32_e32 v183, v190, v33
	v_fmac_f32_e32 v184, v190, v34
	v_fmac_f32_e32 v185, v190, v35
	v_fmac_f32_e32 v186, v191, v32
	v_fmac_f32_e32 v187, v191, v33
	v_fmac_f32_e32 v188, v191, v34
	v_fmac_f32_e32 v189, v191, v35
	ds_read_b128 v[28:31], v151 offset:13056
	ds_read_b128 v[32:35], v151 offset:21248
	ds_read_b128 v[36:39], v151 offset:29440
	ds_read_b128 v[40:43], v151 offset:37632
	ds_read_b64 v[66:67], v181 offset:4864
	s_waitcnt lgkmcnt(11)
	v_mul_f32_e32 v190, v182, v48
	v_mul_f32_e32 v191, v186, v48
	v_mul_f32_e32 v238, v182, v60
	v_mul_f32_e32 v239, v186, v60
	v_fmac_f32_e32 v190, v183, v49
	v_fmac_f32_e32 v191, v187, v49
	v_fmac_f32_e32 v238, v183, v61
	v_fmac_f32_e32 v239, v187, v61
	v_fmac_f32_e32 v190, v184, v50
	v_fmac_f32_e32 v191, v188, v50
	v_fmac_f32_e32 v238, v184, v62
	v_fmac_f32_e32 v239, v188, v62
	v_fmac_f32_e32 v190, v185, v51
	v_fmac_f32_e32 v191, v189, v51
	v_fmac_f32_e32 v238, v185, v63
	v_fmac_f32_e32 v239, v189, v63
	v_add_f32_dpp v190, v190, v190 quad_perm:[1,0,3,2] row_mask:0xf bank_mask:0xf bound_ctrl:1
	v_add_f32_dpp v191, v191, v191 quad_perm:[1,0,3,2] row_mask:0xf bank_mask:0xf bound_ctrl:1
	v_add_f32_dpp v238, v238, v238 quad_perm:[1,0,3,2] row_mask:0xf bank_mask:0xf bound_ctrl:1
	v_add_f32_dpp v239, v239, v239 quad_perm:[1,0,3,2] row_mask:0xf bank_mask:0xf bound_ctrl:1
	v_add_f32_dpp v190, v190, v190 quad_perm:[2,3,0,1] row_mask:0xf bank_mask:0xf bound_ctrl:1
	v_add_f32_dpp v191, v191, v191 quad_perm:[2,3,0,1] row_mask:0xf bank_mask:0xf bound_ctrl:1
	v_add_f32_dpp v238, v238, v238 quad_perm:[2,3,0,1] row_mask:0xf bank_mask:0xf bound_ctrl:1
	v_add_f32_dpp v239, v239, v239 quad_perm:[2,3,0,1] row_mask:0xf bank_mask:0xf bound_ctrl:1
	v_add_f32_dpp v190, v190, v190 row_half_mirror row_mask:0xf bank_mask:0xf bound_ctrl:1
	v_add_f32_dpp v191, v191, v191 row_half_mirror row_mask:0xf bank_mask:0xf bound_ctrl:1
	v_fmac_f32_e32 v182, v126, v56
	v_fmac_f32_e32 v183, v126, v57
	v_add_f32_dpp v190, v190, v190 row_mirror row_mask:0xf bank_mask:0xf bound_ctrl:1
	v_add_f32_dpp v191, v191, v191 row_mirror row_mask:0xf bank_mask:0xf bound_ctrl:1
	v_fmac_f32_e32 v184, v126, v58
	v_fmac_f32_e32 v185, v126, v59
	v_fmac_f32_e32 v186, v127, v56
	v_fmac_f32_e32 v187, v127, v57
	v_fmac_f32_e32 v188, v127, v58
	v_fmac_f32_e32 v189, v127, v59
	v_fmac_f32_e32 v182, v190, v52
	v_fmac_f32_e32 v183, v190, v53
	v_fmac_f32_e32 v184, v190, v54
	v_fmac_f32_e32 v185, v190, v55
	v_fmac_f32_e32 v186, v191, v52
	v_fmac_f32_e32 v187, v191, v53
	v_fmac_f32_e32 v188, v191, v54
	v_fmac_f32_e32 v189, v191, v55
	s_mov_b64 exec, s[10:11]
	ds_write2st64_b64 v192, v[128:129], v[238:239] offset0:32 offset1:34
	s_mov_b64 exec, -1
	ds_read_b128 v[48:51], v151 offset:13312
	ds_read_b128 v[52:55], v151 offset:21504
	ds_read_b128 v[56:59], v151 offset:29696
	ds_read_b128 v[60:63], v151 offset:37888
	ds_read_b64 v[126:127], v181 offset:5120
	s_waitcnt lgkmcnt(11)
	v_mul_f32_e32 v190, v182, v8
	v_mul_f32_e32 v191, v186, v8
	v_mul_f32_e32 v128, v182, v20
	v_mul_f32_e32 v129, v186, v20
	v_fmac_f32_e32 v190, v183, v9
	v_fmac_f32_e32 v191, v187, v9
	v_fmac_f32_e32 v128, v183, v21
	v_fmac_f32_e32 v129, v187, v21
	v_fmac_f32_e32 v190, v184, v10
	v_fmac_f32_e32 v191, v188, v10
	v_fmac_f32_e32 v128, v184, v22
	v_fmac_f32_e32 v129, v188, v22
	v_fmac_f32_e32 v190, v185, v11
	v_fmac_f32_e32 v191, v189, v11
	v_fmac_f32_e32 v128, v185, v23
	v_fmac_f32_e32 v129, v189, v23
	v_add_f32_dpp v190, v190, v190 quad_perm:[1,0,3,2] row_mask:0xf bank_mask:0xf bound_ctrl:1
	v_add_f32_dpp v191, v191, v191 quad_perm:[1,0,3,2] row_mask:0xf bank_mask:0xf bound_ctrl:1
	v_add_f32_dpp v128, v128, v128 quad_perm:[1,0,3,2] row_mask:0xf bank_mask:0xf bound_ctrl:1
	v_add_f32_dpp v129, v129, v129 quad_perm:[1,0,3,2] row_mask:0xf bank_mask:0xf bound_ctrl:1
	v_add_f32_dpp v190, v190, v190 quad_perm:[2,3,0,1] row_mask:0xf bank_mask:0xf bound_ctrl:1
	v_add_f32_dpp v191, v191, v191 quad_perm:[2,3,0,1] row_mask:0xf bank_mask:0xf bound_ctrl:1
	v_add_f32_dpp v128, v128, v128 quad_perm:[2,3,0,1] row_mask:0xf bank_mask:0xf bound_ctrl:1
	v_add_f32_dpp v129, v129, v129 quad_perm:[2,3,0,1] row_mask:0xf bank_mask:0xf bound_ctrl:1
	v_add_f32_dpp v190, v190, v190 row_half_mirror row_mask:0xf bank_mask:0xf bound_ctrl:1
	v_add_f32_dpp v191, v191, v191 row_half_mirror row_mask:0xf bank_mask:0xf bound_ctrl:1
	v_fmac_f32_e32 v182, v64, v16
	v_fmac_f32_e32 v183, v64, v17
	v_add_f32_dpp v190, v190, v190 row_mirror row_mask:0xf bank_mask:0xf bound_ctrl:1
	v_add_f32_dpp v191, v191, v191 row_mirror row_mask:0xf bank_mask:0xf bound_ctrl:1
	v_fmac_f32_e32 v184, v64, v18
	v_fmac_f32_e32 v185, v64, v19
	v_fmac_f32_e32 v186, v65, v16
	v_fmac_f32_e32 v187, v65, v17
	v_fmac_f32_e32 v188, v65, v18
	v_fmac_f32_e32 v189, v65, v19
	v_fmac_f32_e32 v182, v190, v12
	v_fmac_f32_e32 v183, v190, v13
	v_fmac_f32_e32 v184, v190, v14
	v_fmac_f32_e32 v185, v190, v15
	v_fmac_f32_e32 v186, v191, v12
	v_fmac_f32_e32 v187, v191, v13
	v_fmac_f32_e32 v188, v191, v14
	v_fmac_f32_e32 v189, v191, v15
	ds_read_b128 v[8:11], v151 offset:13568
	ds_read_b128 v[12:15], v151 offset:21760
	ds_read_b128 v[16:19], v151 offset:29952
	ds_read_b128 v[20:23], v151 offset:38144
	ds_read_b64 v[64:65], v181 offset:5376
	s_waitcnt lgkmcnt(11)
	v_mul_f32_e32 v190, v182, v28
	v_mul_f32_e32 v191, v186, v28
	v_mul_f32_e32 v238, v182, v40
	v_mul_f32_e32 v239, v186, v40
	v_fmac_f32_e32 v190, v183, v29
	v_fmac_f32_e32 v191, v187, v29
	v_fmac_f32_e32 v238, v183, v41
	v_fmac_f32_e32 v239, v187, v41
	v_fmac_f32_e32 v190, v184, v30
	v_fmac_f32_e32 v191, v188, v30
	v_fmac_f32_e32 v238, v184, v42
	v_fmac_f32_e32 v239, v188, v42
	v_fmac_f32_e32 v190, v185, v31
	v_fmac_f32_e32 v191, v189, v31
	v_fmac_f32_e32 v238, v185, v43
	v_fmac_f32_e32 v239, v189, v43
	v_add_f32_dpp v190, v190, v190 quad_perm:[1,0,3,2] row_mask:0xf bank_mask:0xf bound_ctrl:1
	v_add_f32_dpp v191, v191, v191 quad_perm:[1,0,3,2] row_mask:0xf bank_mask:0xf bound_ctrl:1
	v_add_f32_dpp v238, v238, v238 quad_perm:[1,0,3,2] row_mask:0xf bank_mask:0xf bound_ctrl:1
	v_add_f32_dpp v239, v239, v239 quad_perm:[1,0,3,2] row_mask:0xf bank_mask:0xf bound_ctrl:1
	v_add_f32_dpp v190, v190, v190 quad_perm:[2,3,0,1] row_mask:0xf bank_mask:0xf bound_ctrl:1
	v_add_f32_dpp v191, v191, v191 quad_perm:[2,3,0,1] row_mask:0xf bank_mask:0xf bound_ctrl:1
	v_add_f32_dpp v238, v238, v238 quad_perm:[2,3,0,1] row_mask:0xf bank_mask:0xf bound_ctrl:1
	v_add_f32_dpp v239, v239, v239 quad_perm:[2,3,0,1] row_mask:0xf bank_mask:0xf bound_ctrl:1
	v_add_f32_dpp v190, v190, v190 row_half_mirror row_mask:0xf bank_mask:0xf bound_ctrl:1
	v_add_f32_dpp v191, v191, v191 row_half_mirror row_mask:0xf bank_mask:0xf bound_ctrl:1
	v_fmac_f32_e32 v182, v66, v36
	v_fmac_f32_e32 v183, v66, v37
	v_add_f32_dpp v190, v190, v190 row_mirror row_mask:0xf bank_mask:0xf bound_ctrl:1
	v_add_f32_dpp v191, v191, v191 row_mirror row_mask:0xf bank_mask:0xf bound_ctrl:1
	v_fmac_f32_e32 v184, v66, v38
	v_fmac_f32_e32 v185, v66, v39
	v_fmac_f32_e32 v186, v67, v36
	v_fmac_f32_e32 v187, v67, v37
	v_fmac_f32_e32 v188, v67, v38
	v_fmac_f32_e32 v189, v67, v39
	v_fmac_f32_e32 v182, v190, v32
	v_fmac_f32_e32 v183, v190, v33
	v_fmac_f32_e32 v184, v190, v34
	v_fmac_f32_e32 v185, v190, v35
	v_fmac_f32_e32 v186, v191, v32
	v_fmac_f32_e32 v187, v191, v33
	v_fmac_f32_e32 v188, v191, v34
	v_fmac_f32_e32 v189, v191, v35
	s_mov_b64 exec, s[10:11]
	ds_write2st64_b64 v192, v[128:129], v[238:239] offset0:36 offset1:38
	s_mov_b64 exec, -1
	ds_read_b128 v[28:31], v151 offset:13824
	ds_read_b128 v[32:35], v151 offset:22016
	ds_read_b128 v[36:39], v151 offset:30208
	ds_read_b128 v[40:43], v151 offset:38400
	ds_read_b64 v[66:67], v181 offset:5632
	s_waitcnt lgkmcnt(11)
	v_mul_f32_e32 v190, v182, v48
	v_mul_f32_e32 v191, v186, v48
	v_mul_f32_e32 v128, v182, v60
	v_mul_f32_e32 v129, v186, v60
	v_fmac_f32_e32 v190, v183, v49
	v_fmac_f32_e32 v191, v187, v49
	v_fmac_f32_e32 v128, v183, v61
	v_fmac_f32_e32 v129, v187, v61
	v_fmac_f32_e32 v190, v184, v50
	v_fmac_f32_e32 v191, v188, v50
	v_fmac_f32_e32 v128, v184, v62
	v_fmac_f32_e32 v129, v188, v62
	v_fmac_f32_e32 v190, v185, v51
	v_fmac_f32_e32 v191, v189, v51
	v_fmac_f32_e32 v128, v185, v63
	v_fmac_f32_e32 v129, v189, v63
	v_add_f32_dpp v190, v190, v190 quad_perm:[1,0,3,2] row_mask:0xf bank_mask:0xf bound_ctrl:1
	v_add_f32_dpp v191, v191, v191 quad_perm:[1,0,3,2] row_mask:0xf bank_mask:0xf bound_ctrl:1
	v_add_f32_dpp v128, v128, v128 quad_perm:[1,0,3,2] row_mask:0xf bank_mask:0xf bound_ctrl:1
	v_add_f32_dpp v129, v129, v129 quad_perm:[1,0,3,2] row_mask:0xf bank_mask:0xf bound_ctrl:1
	v_add_f32_dpp v190, v190, v190 quad_perm:[2,3,0,1] row_mask:0xf bank_mask:0xf bound_ctrl:1
	v_add_f32_dpp v191, v191, v191 quad_perm:[2,3,0,1] row_mask:0xf bank_mask:0xf bound_ctrl:1
	v_add_f32_dpp v128, v128, v128 quad_perm:[2,3,0,1] row_mask:0xf bank_mask:0xf bound_ctrl:1
	v_add_f32_dpp v129, v129, v129 quad_perm:[2,3,0,1] row_mask:0xf bank_mask:0xf bound_ctrl:1
	v_add_f32_dpp v190, v190, v190 row_half_mirror row_mask:0xf bank_mask:0xf bound_ctrl:1
	v_add_f32_dpp v191, v191, v191 row_half_mirror row_mask:0xf bank_mask:0xf bound_ctrl:1
	v_fmac_f32_e32 v182, v126, v56
	v_fmac_f32_e32 v183, v126, v57
	v_add_f32_dpp v190, v190, v190 row_mirror row_mask:0xf bank_mask:0xf bound_ctrl:1
	v_add_f32_dpp v191, v191, v191 row_mirror row_mask:0xf bank_mask:0xf bound_ctrl:1
	v_fmac_f32_e32 v184, v126, v58
	v_fmac_f32_e32 v185, v126, v59
	v_fmac_f32_e32 v186, v127, v56
	v_fmac_f32_e32 v187, v127, v57
	v_fmac_f32_e32 v188, v127, v58
	v_fmac_f32_e32 v189, v127, v59
	v_fmac_f32_e32 v182, v190, v52
	v_fmac_f32_e32 v183, v190, v53
	v_fmac_f32_e32 v184, v190, v54
	v_fmac_f32_e32 v185, v190, v55
	v_fmac_f32_e32 v186, v191, v52
	v_fmac_f32_e32 v187, v191, v53
	v_fmac_f32_e32 v188, v191, v54
	v_fmac_f32_e32 v189, v191, v55
	ds_read_b128 v[48:51], v151 offset:14080
	ds_read_b128 v[52:55], v151 offset:22272
	ds_read_b128 v[56:59], v151 offset:30464
	ds_read_b128 v[60:63], v151 offset:38656
	ds_read_b64 v[126:127], v181 offset:5888
	s_waitcnt lgkmcnt(11)
	v_mul_f32_e32 v190, v182, v8
	v_mul_f32_e32 v191, v186, v8
	v_mul_f32_e32 v238, v182, v20
	v_mul_f32_e32 v239, v186, v20
	v_fmac_f32_e32 v190, v183, v9
	v_fmac_f32_e32 v191, v187, v9
	v_fmac_f32_e32 v238, v183, v21
	v_fmac_f32_e32 v239, v187, v21
	v_fmac_f32_e32 v190, v184, v10
	v_fmac_f32_e32 v191, v188, v10
	v_fmac_f32_e32 v238, v184, v22
	v_fmac_f32_e32 v239, v188, v22
	v_fmac_f32_e32 v190, v185, v11
	v_fmac_f32_e32 v191, v189, v11
	v_fmac_f32_e32 v238, v185, v23
	v_fmac_f32_e32 v239, v189, v23
	v_add_f32_dpp v190, v190, v190 quad_perm:[1,0,3,2] row_mask:0xf bank_mask:0xf bound_ctrl:1
	v_add_f32_dpp v191, v191, v191 quad_perm:[1,0,3,2] row_mask:0xf bank_mask:0xf bound_ctrl:1
	v_add_f32_dpp v238, v238, v238 quad_perm:[1,0,3,2] row_mask:0xf bank_mask:0xf bound_ctrl:1
	v_add_f32_dpp v239, v239, v239 quad_perm:[1,0,3,2] row_mask:0xf bank_mask:0xf bound_ctrl:1
	v_add_f32_dpp v190, v190, v190 quad_perm:[2,3,0,1] row_mask:0xf bank_mask:0xf bound_ctrl:1
	v_add_f32_dpp v191, v191, v191 quad_perm:[2,3,0,1] row_mask:0xf bank_mask:0xf bound_ctrl:1
	v_add_f32_dpp v238, v238, v238 quad_perm:[2,3,0,1] row_mask:0xf bank_mask:0xf bound_ctrl:1
	v_add_f32_dpp v239, v239, v239 quad_perm:[2,3,0,1] row_mask:0xf bank_mask:0xf bound_ctrl:1
	v_add_f32_dpp v190, v190, v190 row_half_mirror row_mask:0xf bank_mask:0xf bound_ctrl:1
	v_add_f32_dpp v191, v191, v191 row_half_mirror row_mask:0xf bank_mask:0xf bound_ctrl:1
	v_fmac_f32_e32 v182, v64, v16
	v_fmac_f32_e32 v183, v64, v17
	v_add_f32_dpp v190, v190, v190 row_mirror row_mask:0xf bank_mask:0xf bound_ctrl:1
	v_add_f32_dpp v191, v191, v191 row_mirror row_mask:0xf bank_mask:0xf bound_ctrl:1
	v_fmac_f32_e32 v184, v64, v18
	v_fmac_f32_e32 v185, v64, v19
	v_fmac_f32_e32 v186, v65, v16
	v_fmac_f32_e32 v187, v65, v17
	v_fmac_f32_e32 v188, v65, v18
	v_fmac_f32_e32 v189, v65, v19
	v_fmac_f32_e32 v182, v190, v12
	v_fmac_f32_e32 v183, v190, v13
	v_fmac_f32_e32 v184, v190, v14
	v_fmac_f32_e32 v185, v190, v15
	v_fmac_f32_e32 v186, v191, v12
	v_fmac_f32_e32 v187, v191, v13
	v_fmac_f32_e32 v188, v191, v14
	v_fmac_f32_e32 v189, v191, v15
	s_mov_b64 exec, s[10:11]
	ds_write2st64_b64 v192, v[128:129], v[238:239] offset0:40 offset1:42
	s_mov_b64 exec, -1
	ds_read_b128 v[8:11], v151 offset:14336
	ds_read_b128 v[12:15], v151 offset:22528
	ds_read_b128 v[16:19], v151 offset:30720
	ds_read_b128 v[20:23], v151 offset:38912
	ds_read_b64 v[64:65], v181 offset:6144
	s_waitcnt lgkmcnt(11)
	v_mul_f32_e32 v190, v182, v28
	v_mul_f32_e32 v191, v186, v28
	v_mul_f32_e32 v128, v182, v40
	v_mul_f32_e32 v129, v186, v40
	v_fmac_f32_e32 v190, v183, v29
	v_fmac_f32_e32 v191, v187, v29
	v_fmac_f32_e32 v128, v183, v41
	v_fmac_f32_e32 v129, v187, v41
	v_fmac_f32_e32 v190, v184, v30
	v_fmac_f32_e32 v191, v188, v30
	v_fmac_f32_e32 v128, v184, v42
	v_fmac_f32_e32 v129, v188, v42
	v_fmac_f32_e32 v190, v185, v31
	v_fmac_f32_e32 v191, v189, v31
	v_fmac_f32_e32 v128, v185, v43
	v_fmac_f32_e32 v129, v189, v43
	v_add_f32_dpp v190, v190, v190 quad_perm:[1,0,3,2] row_mask:0xf bank_mask:0xf bound_ctrl:1
	v_add_f32_dpp v191, v191, v191 quad_perm:[1,0,3,2] row_mask:0xf bank_mask:0xf bound_ctrl:1
	v_add_f32_dpp v128, v128, v128 quad_perm:[1,0,3,2] row_mask:0xf bank_mask:0xf bound_ctrl:1
	v_add_f32_dpp v129, v129, v129 quad_perm:[1,0,3,2] row_mask:0xf bank_mask:0xf bound_ctrl:1
	v_add_f32_dpp v190, v190, v190 quad_perm:[2,3,0,1] row_mask:0xf bank_mask:0xf bound_ctrl:1
	v_add_f32_dpp v191, v191, v191 quad_perm:[2,3,0,1] row_mask:0xf bank_mask:0xf bound_ctrl:1
	v_add_f32_dpp v128, v128, v128 quad_perm:[2,3,0,1] row_mask:0xf bank_mask:0xf bound_ctrl:1
	v_add_f32_dpp v129, v129, v129 quad_perm:[2,3,0,1] row_mask:0xf bank_mask:0xf bound_ctrl:1
	v_add_f32_dpp v190, v190, v190 row_half_mirror row_mask:0xf bank_mask:0xf bound_ctrl:1
	v_add_f32_dpp v191, v191, v191 row_half_mirror row_mask:0xf bank_mask:0xf bound_ctrl:1
	v_fmac_f32_e32 v182, v66, v36
	v_fmac_f32_e32 v183, v66, v37
	v_add_f32_dpp v190, v190, v190 row_mirror row_mask:0xf bank_mask:0xf bound_ctrl:1
	v_add_f32_dpp v191, v191, v191 row_mirror row_mask:0xf bank_mask:0xf bound_ctrl:1
	v_fmac_f32_e32 v184, v66, v38
	v_fmac_f32_e32 v185, v66, v39
	v_fmac_f32_e32 v186, v67, v36
	v_fmac_f32_e32 v187, v67, v37
	v_fmac_f32_e32 v188, v67, v38
	v_fmac_f32_e32 v189, v67, v39
	v_fmac_f32_e32 v182, v190, v32
	v_fmac_f32_e32 v183, v190, v33
	v_fmac_f32_e32 v184, v190, v34
	v_fmac_f32_e32 v185, v190, v35
	v_fmac_f32_e32 v186, v191, v32
	v_fmac_f32_e32 v187, v191, v33
	v_fmac_f32_e32 v188, v191, v34
	v_fmac_f32_e32 v189, v191, v35
	ds_read_b128 v[28:31], v151 offset:14592
	ds_read_b128 v[32:35], v151 offset:22784
	ds_read_b128 v[36:39], v151 offset:30976
	ds_read_b128 v[40:43], v151 offset:39168
	ds_read_b64 v[66:67], v181 offset:6400
	s_waitcnt lgkmcnt(11)
	v_mul_f32_e32 v190, v182, v48
	v_mul_f32_e32 v191, v186, v48
	v_mul_f32_e32 v238, v182, v60
	v_mul_f32_e32 v239, v186, v60
	v_fmac_f32_e32 v190, v183, v49
	v_fmac_f32_e32 v191, v187, v49
	v_fmac_f32_e32 v238, v183, v61
	v_fmac_f32_e32 v239, v187, v61
	v_fmac_f32_e32 v190, v184, v50
	v_fmac_f32_e32 v191, v188, v50
	v_fmac_f32_e32 v238, v184, v62
	v_fmac_f32_e32 v239, v188, v62
	v_fmac_f32_e32 v190, v185, v51
	v_fmac_f32_e32 v191, v189, v51
	v_fmac_f32_e32 v238, v185, v63
	v_fmac_f32_e32 v239, v189, v63
	v_add_f32_dpp v190, v190, v190 quad_perm:[1,0,3,2] row_mask:0xf bank_mask:0xf bound_ctrl:1
	v_add_f32_dpp v191, v191, v191 quad_perm:[1,0,3,2] row_mask:0xf bank_mask:0xf bound_ctrl:1
	v_add_f32_dpp v238, v238, v238 quad_perm:[1,0,3,2] row_mask:0xf bank_mask:0xf bound_ctrl:1
	v_add_f32_dpp v239, v239, v239 quad_perm:[1,0,3,2] row_mask:0xf bank_mask:0xf bound_ctrl:1
	v_add_f32_dpp v190, v190, v190 quad_perm:[2,3,0,1] row_mask:0xf bank_mask:0xf bound_ctrl:1
	v_add_f32_dpp v191, v191, v191 quad_perm:[2,3,0,1] row_mask:0xf bank_mask:0xf bound_ctrl:1
	v_add_f32_dpp v238, v238, v238 quad_perm:[2,3,0,1] row_mask:0xf bank_mask:0xf bound_ctrl:1
	v_add_f32_dpp v239, v239, v239 quad_perm:[2,3,0,1] row_mask:0xf bank_mask:0xf bound_ctrl:1
	v_add_f32_dpp v190, v190, v190 row_half_mirror row_mask:0xf bank_mask:0xf bound_ctrl:1
	v_add_f32_dpp v191, v191, v191 row_half_mirror row_mask:0xf bank_mask:0xf bound_ctrl:1
	v_fmac_f32_e32 v182, v126, v56
	v_fmac_f32_e32 v183, v126, v57
	v_add_f32_dpp v190, v190, v190 row_mirror row_mask:0xf bank_mask:0xf bound_ctrl:1
	v_add_f32_dpp v191, v191, v191 row_mirror row_mask:0xf bank_mask:0xf bound_ctrl:1
	v_fmac_f32_e32 v184, v126, v58
	v_fmac_f32_e32 v185, v126, v59
	v_fmac_f32_e32 v186, v127, v56
	v_fmac_f32_e32 v187, v127, v57
	v_fmac_f32_e32 v188, v127, v58
	v_fmac_f32_e32 v189, v127, v59
	v_fmac_f32_e32 v182, v190, v52
	v_fmac_f32_e32 v183, v190, v53
	v_fmac_f32_e32 v184, v190, v54
	v_fmac_f32_e32 v185, v190, v55
	v_fmac_f32_e32 v186, v191, v52
	v_fmac_f32_e32 v187, v191, v53
	v_fmac_f32_e32 v188, v191, v54
	v_fmac_f32_e32 v189, v191, v55
	s_mov_b64 exec, s[10:11]
	ds_write2st64_b64 v192, v[128:129], v[238:239] offset0:44 offset1:46
	s_mov_b64 exec, -1
	ds_read_b128 v[48:51], v151 offset:14848
	ds_read_b128 v[52:55], v151 offset:23040
	ds_read_b128 v[56:59], v151 offset:31232
	ds_read_b128 v[60:63], v151 offset:39424
	ds_read_b64 v[126:127], v181 offset:6656
	s_waitcnt lgkmcnt(11)
	v_mul_f32_e32 v190, v182, v8
	v_mul_f32_e32 v191, v186, v8
	v_mul_f32_e32 v128, v182, v20
	v_mul_f32_e32 v129, v186, v20
	v_fmac_f32_e32 v190, v183, v9
	v_fmac_f32_e32 v191, v187, v9
	v_fmac_f32_e32 v128, v183, v21
	v_fmac_f32_e32 v129, v187, v21
	v_fmac_f32_e32 v190, v184, v10
	v_fmac_f32_e32 v191, v188, v10
	v_fmac_f32_e32 v128, v184, v22
	v_fmac_f32_e32 v129, v188, v22
	v_fmac_f32_e32 v190, v185, v11
	v_fmac_f32_e32 v191, v189, v11
	v_fmac_f32_e32 v128, v185, v23
	v_fmac_f32_e32 v129, v189, v23
	v_add_f32_dpp v190, v190, v190 quad_perm:[1,0,3,2] row_mask:0xf bank_mask:0xf bound_ctrl:1
	v_add_f32_dpp v191, v191, v191 quad_perm:[1,0,3,2] row_mask:0xf bank_mask:0xf bound_ctrl:1
	v_add_f32_dpp v128, v128, v128 quad_perm:[1,0,3,2] row_mask:0xf bank_mask:0xf bound_ctrl:1
	v_add_f32_dpp v129, v129, v129 quad_perm:[1,0,3,2] row_mask:0xf bank_mask:0xf bound_ctrl:1
	v_add_f32_dpp v190, v190, v190 quad_perm:[2,3,0,1] row_mask:0xf bank_mask:0xf bound_ctrl:1
	v_add_f32_dpp v191, v191, v191 quad_perm:[2,3,0,1] row_mask:0xf bank_mask:0xf bound_ctrl:1
	v_add_f32_dpp v128, v128, v128 quad_perm:[2,3,0,1] row_mask:0xf bank_mask:0xf bound_ctrl:1
	v_add_f32_dpp v129, v129, v129 quad_perm:[2,3,0,1] row_mask:0xf bank_mask:0xf bound_ctrl:1
	v_add_f32_dpp v190, v190, v190 row_half_mirror row_mask:0xf bank_mask:0xf bound_ctrl:1
	v_add_f32_dpp v191, v191, v191 row_half_mirror row_mask:0xf bank_mask:0xf bound_ctrl:1
	v_fmac_f32_e32 v182, v64, v16
	v_fmac_f32_e32 v183, v64, v17
	v_add_f32_dpp v190, v190, v190 row_mirror row_mask:0xf bank_mask:0xf bound_ctrl:1
	v_add_f32_dpp v191, v191, v191 row_mirror row_mask:0xf bank_mask:0xf bound_ctrl:1
	v_fmac_f32_e32 v184, v64, v18
	v_fmac_f32_e32 v185, v64, v19
	v_fmac_f32_e32 v186, v65, v16
	v_fmac_f32_e32 v187, v65, v17
	v_fmac_f32_e32 v188, v65, v18
	v_fmac_f32_e32 v189, v65, v19
	v_fmac_f32_e32 v182, v190, v12
	v_fmac_f32_e32 v183, v190, v13
	v_fmac_f32_e32 v184, v190, v14
	v_fmac_f32_e32 v185, v190, v15
	v_fmac_f32_e32 v186, v191, v12
	v_fmac_f32_e32 v187, v191, v13
	v_fmac_f32_e32 v188, v191, v14
	v_fmac_f32_e32 v189, v191, v15
	ds_read_b128 v[8:11], v151 offset:15104
	ds_read_b128 v[12:15], v151 offset:23296
	ds_read_b128 v[16:19], v151 offset:31488
	ds_read_b128 v[20:23], v151 offset:39680
	ds_read_b64 v[64:65], v181 offset:6912
	s_waitcnt lgkmcnt(11)
	v_mul_f32_e32 v190, v182, v28
	v_mul_f32_e32 v191, v186, v28
	v_mul_f32_e32 v238, v182, v40
	v_mul_f32_e32 v239, v186, v40
	v_fmac_f32_e32 v190, v183, v29
	v_fmac_f32_e32 v191, v187, v29
	v_fmac_f32_e32 v238, v183, v41
	v_fmac_f32_e32 v239, v187, v41
	v_fmac_f32_e32 v190, v184, v30
	v_fmac_f32_e32 v191, v188, v30
	v_fmac_f32_e32 v238, v184, v42
	v_fmac_f32_e32 v239, v188, v42
	v_fmac_f32_e32 v190, v185, v31
	v_fmac_f32_e32 v191, v189, v31
	v_fmac_f32_e32 v238, v185, v43
	v_fmac_f32_e32 v239, v189, v43
	v_add_f32_dpp v190, v190, v190 quad_perm:[1,0,3,2] row_mask:0xf bank_mask:0xf bound_ctrl:1
	v_add_f32_dpp v191, v191, v191 quad_perm:[1,0,3,2] row_mask:0xf bank_mask:0xf bound_ctrl:1
	v_add_f32_dpp v238, v238, v238 quad_perm:[1,0,3,2] row_mask:0xf bank_mask:0xf bound_ctrl:1
	v_add_f32_dpp v239, v239, v239 quad_perm:[1,0,3,2] row_mask:0xf bank_mask:0xf bound_ctrl:1
	v_add_f32_dpp v190, v190, v190 quad_perm:[2,3,0,1] row_mask:0xf bank_mask:0xf bound_ctrl:1
	v_add_f32_dpp v191, v191, v191 quad_perm:[2,3,0,1] row_mask:0xf bank_mask:0xf bound_ctrl:1
	v_add_f32_dpp v238, v238, v238 quad_perm:[2,3,0,1] row_mask:0xf bank_mask:0xf bound_ctrl:1
	v_add_f32_dpp v239, v239, v239 quad_perm:[2,3,0,1] row_mask:0xf bank_mask:0xf bound_ctrl:1
	v_add_f32_dpp v190, v190, v190 row_half_mirror row_mask:0xf bank_mask:0xf bound_ctrl:1
	v_add_f32_dpp v191, v191, v191 row_half_mirror row_mask:0xf bank_mask:0xf bound_ctrl:1
	v_fmac_f32_e32 v182, v66, v36
	v_fmac_f32_e32 v183, v66, v37
	v_add_f32_dpp v190, v190, v190 row_mirror row_mask:0xf bank_mask:0xf bound_ctrl:1
	v_add_f32_dpp v191, v191, v191 row_mirror row_mask:0xf bank_mask:0xf bound_ctrl:1
	v_fmac_f32_e32 v184, v66, v38
	v_fmac_f32_e32 v185, v66, v39
	v_fmac_f32_e32 v186, v67, v36
	v_fmac_f32_e32 v187, v67, v37
	v_fmac_f32_e32 v188, v67, v38
	v_fmac_f32_e32 v189, v67, v39
	v_fmac_f32_e32 v182, v190, v32
	v_fmac_f32_e32 v183, v190, v33
	v_fmac_f32_e32 v184, v190, v34
	v_fmac_f32_e32 v185, v190, v35
	v_fmac_f32_e32 v186, v191, v32
	v_fmac_f32_e32 v187, v191, v33
	v_fmac_f32_e32 v188, v191, v34
	v_fmac_f32_e32 v189, v191, v35
	s_mov_b64 exec, s[10:11]
	ds_write2st64_b64 v192, v[128:129], v[238:239] offset0:48 offset1:50
	s_mov_b64 exec, -1
	ds_read_b128 v[28:31], v151 offset:15360
	ds_read_b128 v[32:35], v151 offset:23552
	ds_read_b128 v[36:39], v151 offset:31744
	ds_read_b128 v[40:43], v151 offset:39936
	ds_read_b64 v[66:67], v181 offset:7168
	s_waitcnt lgkmcnt(11)
	v_mul_f32_e32 v190, v182, v48
	v_mul_f32_e32 v191, v186, v48
	v_mul_f32_e32 v128, v182, v60
	v_mul_f32_e32 v129, v186, v60
	v_fmac_f32_e32 v190, v183, v49
	v_fmac_f32_e32 v191, v187, v49
	v_fmac_f32_e32 v128, v183, v61
	v_fmac_f32_e32 v129, v187, v61
	v_fmac_f32_e32 v190, v184, v50
	v_fmac_f32_e32 v191, v188, v50
	v_fmac_f32_e32 v128, v184, v62
	v_fmac_f32_e32 v129, v188, v62
	v_fmac_f32_e32 v190, v185, v51
	v_fmac_f32_e32 v191, v189, v51
	v_fmac_f32_e32 v128, v185, v63
	v_fmac_f32_e32 v129, v189, v63
	v_add_f32_dpp v190, v190, v190 quad_perm:[1,0,3,2] row_mask:0xf bank_mask:0xf bound_ctrl:1
	v_add_f32_dpp v191, v191, v191 quad_perm:[1,0,3,2] row_mask:0xf bank_mask:0xf bound_ctrl:1
	v_add_f32_dpp v128, v128, v128 quad_perm:[1,0,3,2] row_mask:0xf bank_mask:0xf bound_ctrl:1
	v_add_f32_dpp v129, v129, v129 quad_perm:[1,0,3,2] row_mask:0xf bank_mask:0xf bound_ctrl:1
	v_add_f32_dpp v190, v190, v190 quad_perm:[2,3,0,1] row_mask:0xf bank_mask:0xf bound_ctrl:1
	v_add_f32_dpp v191, v191, v191 quad_perm:[2,3,0,1] row_mask:0xf bank_mask:0xf bound_ctrl:1
	v_add_f32_dpp v128, v128, v128 quad_perm:[2,3,0,1] row_mask:0xf bank_mask:0xf bound_ctrl:1
	v_add_f32_dpp v129, v129, v129 quad_perm:[2,3,0,1] row_mask:0xf bank_mask:0xf bound_ctrl:1
	v_add_f32_dpp v190, v190, v190 row_half_mirror row_mask:0xf bank_mask:0xf bound_ctrl:1
	v_add_f32_dpp v191, v191, v191 row_half_mirror row_mask:0xf bank_mask:0xf bound_ctrl:1
	v_fmac_f32_e32 v182, v126, v56
	v_fmac_f32_e32 v183, v126, v57
	v_add_f32_dpp v190, v190, v190 row_mirror row_mask:0xf bank_mask:0xf bound_ctrl:1
	v_add_f32_dpp v191, v191, v191 row_mirror row_mask:0xf bank_mask:0xf bound_ctrl:1
	v_fmac_f32_e32 v184, v126, v58
	v_fmac_f32_e32 v185, v126, v59
	v_fmac_f32_e32 v186, v127, v56
	v_fmac_f32_e32 v187, v127, v57
	v_fmac_f32_e32 v188, v127, v58
	v_fmac_f32_e32 v189, v127, v59
	v_fmac_f32_e32 v182, v190, v52
	v_fmac_f32_e32 v183, v190, v53
	v_fmac_f32_e32 v184, v190, v54
	v_fmac_f32_e32 v185, v190, v55
	v_fmac_f32_e32 v186, v191, v52
	v_fmac_f32_e32 v187, v191, v53
	v_fmac_f32_e32 v188, v191, v54
	v_fmac_f32_e32 v189, v191, v55
	ds_read_b128 v[48:51], v151 offset:15616
	ds_read_b128 v[52:55], v151 offset:23808
	ds_read_b128 v[56:59], v151 offset:32000
	ds_read_b128 v[60:63], v151 offset:40192
	ds_read_b64 v[126:127], v181 offset:7424
	s_waitcnt lgkmcnt(11)
	v_mul_f32_e32 v190, v182, v8
	v_mul_f32_e32 v191, v186, v8
	v_mul_f32_e32 v238, v182, v20
	v_mul_f32_e32 v239, v186, v20
	v_fmac_f32_e32 v190, v183, v9
	v_fmac_f32_e32 v191, v187, v9
	v_fmac_f32_e32 v238, v183, v21
	v_fmac_f32_e32 v239, v187, v21
	v_fmac_f32_e32 v190, v184, v10
	v_fmac_f32_e32 v191, v188, v10
	v_fmac_f32_e32 v238, v184, v22
	v_fmac_f32_e32 v239, v188, v22
	v_fmac_f32_e32 v190, v185, v11
	v_fmac_f32_e32 v191, v189, v11
	v_fmac_f32_e32 v238, v185, v23
	v_fmac_f32_e32 v239, v189, v23
	v_add_f32_dpp v190, v190, v190 quad_perm:[1,0,3,2] row_mask:0xf bank_mask:0xf bound_ctrl:1
	v_add_f32_dpp v191, v191, v191 quad_perm:[1,0,3,2] row_mask:0xf bank_mask:0xf bound_ctrl:1
	v_add_f32_dpp v238, v238, v238 quad_perm:[1,0,3,2] row_mask:0xf bank_mask:0xf bound_ctrl:1
	v_add_f32_dpp v239, v239, v239 quad_perm:[1,0,3,2] row_mask:0xf bank_mask:0xf bound_ctrl:1
	v_add_f32_dpp v190, v190, v190 quad_perm:[2,3,0,1] row_mask:0xf bank_mask:0xf bound_ctrl:1
	v_add_f32_dpp v191, v191, v191 quad_perm:[2,3,0,1] row_mask:0xf bank_mask:0xf bound_ctrl:1
	v_add_f32_dpp v238, v238, v238 quad_perm:[2,3,0,1] row_mask:0xf bank_mask:0xf bound_ctrl:1
	v_add_f32_dpp v239, v239, v239 quad_perm:[2,3,0,1] row_mask:0xf bank_mask:0xf bound_ctrl:1
	v_add_f32_dpp v190, v190, v190 row_half_mirror row_mask:0xf bank_mask:0xf bound_ctrl:1
	v_add_f32_dpp v191, v191, v191 row_half_mirror row_mask:0xf bank_mask:0xf bound_ctrl:1
	v_fmac_f32_e32 v182, v64, v16
	v_fmac_f32_e32 v183, v64, v17
	v_add_f32_dpp v190, v190, v190 row_mirror row_mask:0xf bank_mask:0xf bound_ctrl:1
	v_add_f32_dpp v191, v191, v191 row_mirror row_mask:0xf bank_mask:0xf bound_ctrl:1
	v_fmac_f32_e32 v184, v64, v18
	v_fmac_f32_e32 v185, v64, v19
	v_fmac_f32_e32 v186, v65, v16
	v_fmac_f32_e32 v187, v65, v17
	v_fmac_f32_e32 v188, v65, v18
	v_fmac_f32_e32 v189, v65, v19
	v_fmac_f32_e32 v182, v190, v12
	v_fmac_f32_e32 v183, v190, v13
	v_fmac_f32_e32 v184, v190, v14
	v_fmac_f32_e32 v185, v190, v15
	v_fmac_f32_e32 v186, v191, v12
	v_fmac_f32_e32 v187, v191, v13
	v_fmac_f32_e32 v188, v191, v14
	v_fmac_f32_e32 v189, v191, v15
	s_mov_b64 exec, s[10:11]
	ds_write2st64_b64 v192, v[128:129], v[238:239] offset0:52 offset1:54
	s_mov_b64 exec, -1
	ds_read_b128 v[8:11], v151 offset:15872
	ds_read_b128 v[12:15], v151 offset:24064
	ds_read_b128 v[16:19], v151 offset:32256
	ds_read_b128 v[20:23], v151 offset:40448
	ds_read_b64 v[64:65], v181 offset:7680
	s_waitcnt lgkmcnt(11)
	v_mul_f32_e32 v190, v182, v28
	v_mul_f32_e32 v191, v186, v28
	v_mul_f32_e32 v128, v182, v40
	v_mul_f32_e32 v129, v186, v40
	v_fmac_f32_e32 v190, v183, v29
	v_fmac_f32_e32 v191, v187, v29
	v_fmac_f32_e32 v128, v183, v41
	v_fmac_f32_e32 v129, v187, v41
	v_fmac_f32_e32 v190, v184, v30
	v_fmac_f32_e32 v191, v188, v30
	v_fmac_f32_e32 v128, v184, v42
	v_fmac_f32_e32 v129, v188, v42
	v_fmac_f32_e32 v190, v185, v31
	v_fmac_f32_e32 v191, v189, v31
	v_fmac_f32_e32 v128, v185, v43
	v_fmac_f32_e32 v129, v189, v43
	v_add_f32_dpp v190, v190, v190 quad_perm:[1,0,3,2] row_mask:0xf bank_mask:0xf bound_ctrl:1
	v_add_f32_dpp v191, v191, v191 quad_perm:[1,0,3,2] row_mask:0xf bank_mask:0xf bound_ctrl:1
	v_add_f32_dpp v128, v128, v128 quad_perm:[1,0,3,2] row_mask:0xf bank_mask:0xf bound_ctrl:1
	v_add_f32_dpp v129, v129, v129 quad_perm:[1,0,3,2] row_mask:0xf bank_mask:0xf bound_ctrl:1
	v_add_f32_dpp v190, v190, v190 quad_perm:[2,3,0,1] row_mask:0xf bank_mask:0xf bound_ctrl:1
	v_add_f32_dpp v191, v191, v191 quad_perm:[2,3,0,1] row_mask:0xf bank_mask:0xf bound_ctrl:1
	v_add_f32_dpp v128, v128, v128 quad_perm:[2,3,0,1] row_mask:0xf bank_mask:0xf bound_ctrl:1
	v_add_f32_dpp v129, v129, v129 quad_perm:[2,3,0,1] row_mask:0xf bank_mask:0xf bound_ctrl:1
	v_add_f32_dpp v190, v190, v190 row_half_mirror row_mask:0xf bank_mask:0xf bound_ctrl:1
	v_add_f32_dpp v191, v191, v191 row_half_mirror row_mask:0xf bank_mask:0xf bound_ctrl:1
	v_fmac_f32_e32 v182, v66, v36
	v_fmac_f32_e32 v183, v66, v37
	v_add_f32_dpp v190, v190, v190 row_mirror row_mask:0xf bank_mask:0xf bound_ctrl:1
	v_add_f32_dpp v191, v191, v191 row_mirror row_mask:0xf bank_mask:0xf bound_ctrl:1
	v_fmac_f32_e32 v184, v66, v38
	v_fmac_f32_e32 v185, v66, v39
	v_fmac_f32_e32 v186, v67, v36
	v_fmac_f32_e32 v187, v67, v37
	v_fmac_f32_e32 v188, v67, v38
	v_fmac_f32_e32 v189, v67, v39
	v_fmac_f32_e32 v182, v190, v32
	v_fmac_f32_e32 v183, v190, v33
	v_fmac_f32_e32 v184, v190, v34
	v_fmac_f32_e32 v185, v190, v35
	v_fmac_f32_e32 v186, v191, v32
	v_fmac_f32_e32 v187, v191, v33
	v_fmac_f32_e32 v188, v191, v34
	v_fmac_f32_e32 v189, v191, v35
	ds_read_b128 v[28:31], v151 offset:16128
	ds_read_b128 v[32:35], v151 offset:24320
	ds_read_b128 v[36:39], v151 offset:32512
	ds_read_b128 v[40:43], v151 offset:40704
	ds_read_b64 v[66:67], v181 offset:7936
	s_waitcnt lgkmcnt(11)
	v_mul_f32_e32 v190, v182, v48
	v_mul_f32_e32 v191, v186, v48
	v_mul_f32_e32 v238, v182, v60
	v_mul_f32_e32 v239, v186, v60
	v_fmac_f32_e32 v190, v183, v49
	v_fmac_f32_e32 v191, v187, v49
	v_fmac_f32_e32 v238, v183, v61
	v_fmac_f32_e32 v239, v187, v61
	v_fmac_f32_e32 v190, v184, v50
	v_fmac_f32_e32 v191, v188, v50
	v_fmac_f32_e32 v238, v184, v62
	v_fmac_f32_e32 v239, v188, v62
	v_fmac_f32_e32 v190, v185, v51
	v_fmac_f32_e32 v191, v189, v51
	v_fmac_f32_e32 v238, v185, v63
	v_fmac_f32_e32 v239, v189, v63
	v_add_f32_dpp v190, v190, v190 quad_perm:[1,0,3,2] row_mask:0xf bank_mask:0xf bound_ctrl:1
	v_add_f32_dpp v191, v191, v191 quad_perm:[1,0,3,2] row_mask:0xf bank_mask:0xf bound_ctrl:1
	v_add_f32_dpp v238, v238, v238 quad_perm:[1,0,3,2] row_mask:0xf bank_mask:0xf bound_ctrl:1
	v_add_f32_dpp v239, v239, v239 quad_perm:[1,0,3,2] row_mask:0xf bank_mask:0xf bound_ctrl:1
	v_add_f32_dpp v190, v190, v190 quad_perm:[2,3,0,1] row_mask:0xf bank_mask:0xf bound_ctrl:1
	v_add_f32_dpp v191, v191, v191 quad_perm:[2,3,0,1] row_mask:0xf bank_mask:0xf bound_ctrl:1
	v_add_f32_dpp v238, v238, v238 quad_perm:[2,3,0,1] row_mask:0xf bank_mask:0xf bound_ctrl:1
	v_add_f32_dpp v239, v239, v239 quad_perm:[2,3,0,1] row_mask:0xf bank_mask:0xf bound_ctrl:1
	v_add_f32_dpp v190, v190, v190 row_half_mirror row_mask:0xf bank_mask:0xf bound_ctrl:1
	v_add_f32_dpp v191, v191, v191 row_half_mirror row_mask:0xf bank_mask:0xf bound_ctrl:1
	v_fmac_f32_e32 v182, v126, v56
	v_fmac_f32_e32 v183, v126, v57
	v_add_f32_dpp v190, v190, v190 row_mirror row_mask:0xf bank_mask:0xf bound_ctrl:1
	v_add_f32_dpp v191, v191, v191 row_mirror row_mask:0xf bank_mask:0xf bound_ctrl:1
	v_fmac_f32_e32 v184, v126, v58
	v_fmac_f32_e32 v185, v126, v59
	v_fmac_f32_e32 v186, v127, v56
	v_fmac_f32_e32 v187, v127, v57
	v_fmac_f32_e32 v188, v127, v58
	v_fmac_f32_e32 v189, v127, v59
	v_fmac_f32_e32 v182, v190, v52
	v_fmac_f32_e32 v183, v190, v53
	v_fmac_f32_e32 v184, v190, v54
	v_fmac_f32_e32 v185, v190, v55
	v_fmac_f32_e32 v186, v191, v52
	v_fmac_f32_e32 v187, v191, v53
	v_fmac_f32_e32 v188, v191, v54
	v_fmac_f32_e32 v189, v191, v55
	s_mov_b64 exec, s[10:11]
	ds_write2st64_b64 v192, v[128:129], v[238:239] offset0:56 offset1:58
	s_mov_b64 exec, -1
	s_waitcnt lgkmcnt(6)
	v_mul_f32_e32 v190, v182, v8
	v_mul_f32_e32 v191, v186, v8
	v_mul_f32_e32 v128, v182, v20
	v_mul_f32_e32 v129, v186, v20
	v_fmac_f32_e32 v190, v183, v9
	v_fmac_f32_e32 v191, v187, v9
	v_fmac_f32_e32 v128, v183, v21
	v_fmac_f32_e32 v129, v187, v21
	v_fmac_f32_e32 v190, v184, v10
	v_fmac_f32_e32 v191, v188, v10
	v_fmac_f32_e32 v128, v184, v22
	v_fmac_f32_e32 v129, v188, v22
	v_fmac_f32_e32 v190, v185, v11
	v_fmac_f32_e32 v191, v189, v11
	v_fmac_f32_e32 v128, v185, v23
	v_fmac_f32_e32 v129, v189, v23
	v_add_f32_dpp v190, v190, v190 quad_perm:[1,0,3,2] row_mask:0xf bank_mask:0xf bound_ctrl:1
	v_add_f32_dpp v191, v191, v191 quad_perm:[1,0,3,2] row_mask:0xf bank_mask:0xf bound_ctrl:1
	v_add_f32_dpp v128, v128, v128 quad_perm:[1,0,3,2] row_mask:0xf bank_mask:0xf bound_ctrl:1
	v_add_f32_dpp v129, v129, v129 quad_perm:[1,0,3,2] row_mask:0xf bank_mask:0xf bound_ctrl:1
	v_add_f32_dpp v190, v190, v190 quad_perm:[2,3,0,1] row_mask:0xf bank_mask:0xf bound_ctrl:1
	v_add_f32_dpp v191, v191, v191 quad_perm:[2,3,0,1] row_mask:0xf bank_mask:0xf bound_ctrl:1
	v_add_f32_dpp v128, v128, v128 quad_perm:[2,3,0,1] row_mask:0xf bank_mask:0xf bound_ctrl:1
	v_add_f32_dpp v129, v129, v129 quad_perm:[2,3,0,1] row_mask:0xf bank_mask:0xf bound_ctrl:1
	v_add_f32_dpp v190, v190, v190 row_half_mirror row_mask:0xf bank_mask:0xf bound_ctrl:1
	v_add_f32_dpp v191, v191, v191 row_half_mirror row_mask:0xf bank_mask:0xf bound_ctrl:1
	v_fmac_f32_e32 v182, v64, v16
	v_fmac_f32_e32 v183, v64, v17
	v_add_f32_dpp v190, v190, v190 row_mirror row_mask:0xf bank_mask:0xf bound_ctrl:1
	v_add_f32_dpp v191, v191, v191 row_mirror row_mask:0xf bank_mask:0xf bound_ctrl:1
	v_fmac_f32_e32 v184, v64, v18
	v_fmac_f32_e32 v185, v64, v19
	v_fmac_f32_e32 v186, v65, v16
	v_fmac_f32_e32 v187, v65, v17
	v_fmac_f32_e32 v188, v65, v18
	v_fmac_f32_e32 v189, v65, v19
	v_fmac_f32_e32 v182, v190, v12
	v_fmac_f32_e32 v183, v190, v13
	v_fmac_f32_e32 v184, v190, v14
	v_fmac_f32_e32 v185, v190, v15
	v_fmac_f32_e32 v186, v191, v12
	v_fmac_f32_e32 v187, v191, v13
	v_fmac_f32_e32 v188, v191, v14
	v_fmac_f32_e32 v189, v191, v15
	s_waitcnt lgkmcnt(1)
	v_mul_f32_e32 v190, v182, v28
	v_mul_f32_e32 v191, v186, v28
	v_mul_f32_e32 v238, v182, v40
	v_mul_f32_e32 v239, v186, v40
	v_fmac_f32_e32 v190, v183, v29
	v_fmac_f32_e32 v191, v187, v29
	v_fmac_f32_e32 v238, v183, v41
	v_fmac_f32_e32 v239, v187, v41
	v_fmac_f32_e32 v190, v184, v30
	v_fmac_f32_e32 v191, v188, v30
	v_fmac_f32_e32 v238, v184, v42
	v_fmac_f32_e32 v239, v188, v42
	v_fmac_f32_e32 v190, v185, v31
	v_fmac_f32_e32 v191, v189, v31
	v_fmac_f32_e32 v238, v185, v43
	v_fmac_f32_e32 v239, v189, v43
	v_add_f32_dpp v190, v190, v190 quad_perm:[1,0,3,2] row_mask:0xf bank_mask:0xf bound_ctrl:1
	v_add_f32_dpp v191, v191, v191 quad_perm:[1,0,3,2] row_mask:0xf bank_mask:0xf bound_ctrl:1
	v_add_f32_dpp v238, v238, v238 quad_perm:[1,0,3,2] row_mask:0xf bank_mask:0xf bound_ctrl:1
	v_add_f32_dpp v239, v239, v239 quad_perm:[1,0,3,2] row_mask:0xf bank_mask:0xf bound_ctrl:1
	v_add_f32_dpp v190, v190, v190 quad_perm:[2,3,0,1] row_mask:0xf bank_mask:0xf bound_ctrl:1
	v_add_f32_dpp v191, v191, v191 quad_perm:[2,3,0,1] row_mask:0xf bank_mask:0xf bound_ctrl:1
	v_add_f32_dpp v238, v238, v238 quad_perm:[2,3,0,1] row_mask:0xf bank_mask:0xf bound_ctrl:1
	v_add_f32_dpp v239, v239, v239 quad_perm:[2,3,0,1] row_mask:0xf bank_mask:0xf bound_ctrl:1
	v_add_f32_dpp v190, v190, v190 row_half_mirror row_mask:0xf bank_mask:0xf bound_ctrl:1
	v_add_f32_dpp v191, v191, v191 row_half_mirror row_mask:0xf bank_mask:0xf bound_ctrl:1
	v_fmac_f32_e32 v182, v66, v36
	v_fmac_f32_e32 v183, v66, v37
	v_add_f32_dpp v190, v190, v190 row_mirror row_mask:0xf bank_mask:0xf bound_ctrl:1
	v_add_f32_dpp v191, v191, v191 row_mirror row_mask:0xf bank_mask:0xf bound_ctrl:1
	v_fmac_f32_e32 v184, v66, v38
	v_fmac_f32_e32 v185, v66, v39
	v_fmac_f32_e32 v186, v67, v36
	v_fmac_f32_e32 v187, v67, v37
	v_fmac_f32_e32 v188, v67, v38
	v_fmac_f32_e32 v189, v67, v39
	v_fmac_f32_e32 v182, v190, v32
	v_fmac_f32_e32 v183, v190, v33
	v_fmac_f32_e32 v184, v190, v34
	v_fmac_f32_e32 v185, v190, v35
	v_fmac_f32_e32 v186, v191, v32
	v_fmac_f32_e32 v187, v191, v33
	v_fmac_f32_e32 v188, v191, v34
	v_fmac_f32_e32 v189, v191, v35
	s_mov_b64 exec, s[10:11]
	ds_write2st64_b64 v192, v[128:129], v[238:239] offset0:60 offset1:62
	s_mov_b64 exec, -1
	ds_read_b128 v[4:7], v151 offset:65280
	s_waitcnt lgkmcnt(0)
	v_mul_f32_e32 v182, v182, v4
	v_mul_f32_e32 v183, v183, v5
	v_mul_f32_e32 v184, v184, v6
	v_mul_f32_e32 v185, v185, v7
	v_mul_f32_e32 v186, v186, v4
	v_mul_f32_e32 v187, v187, v5
	v_mul_f32_e32 v188, v188, v6
	v_mul_f32_e32 v189, v189, v7
	s_branch .LBB0_182

.LBB0_296:
	s_or_b64 exec, exec, s[12:13]
	s_waitcnt lgkmcnt(0)
	s_barrier
	v_mbcnt_lo_u32_b32 v186, -1, 0
	v_mbcnt_hi_u32_b32 v186, -1, v186
	v_lshlrev_b32_e32 v186, 2, v186
	v_add_u32_e32 v186, 0xe000, v186
	v_cndmask_b32_e64 v185, v186, v152, s[8:9]
	v_mbcnt_lo_u32_b32 v186, -1, 0
	v_mbcnt_hi_u32_b32 v186, -1, v186
	v_and_b32_e32 v186, 12, v186
	v_lshlrev_b32_e32 v186, 6, v186
	v_add_u32_e32 v185, 0x1c000, v151
	v_add_u32_e32 v185, v186, v185
	s_mov_b32 s12, 0x11111111
	s_mov_b32 s13, 0x11111111
	ds_read_b128 v[8:11], v145 offset:16128
	ds_read_b128 v[12:15], v145 offset:24320
	ds_read_b128 v[16:19], v145 offset:32512
	ds_read_b128 v[20:23], v145 offset:40704
	ds_read2st64_b32 v[240:241], v151 offset0:223 offset1:222
	ds_read_b128 v[28:31], v145 offset:15872
	ds_read_b128 v[32:35], v145 offset:24064
	ds_read_b128 v[36:39], v145 offset:32256
	ds_read_b128 v[40:43], v145 offset:40448
	ds_read_b128 v[48:51], v145 offset:15616
	ds_read_b128 v[52:55], v145 offset:23808
	ds_read_b128 v[56:59], v145 offset:32000
	ds_read_b128 v[60:63], v145 offset:40192
	ds_read2st64_b32 v[242:243], v151 offset0:221 offset1:220
	s_waitcnt lgkmcnt(9)
	v_mul_f32_e32 v183, v179, v8
	v_mul_f32_e32 v184, v179, v20
	v_fmac_f32_e32 v183, v180, v9
	v_fmac_f32_e32 v184, v180, v21
	v_fmac_f32_e32 v183, v181, v10
	v_fmac_f32_e32 v184, v181, v22
	v_fmac_f32_e32 v183, v182, v11
	v_fmac_f32_e32 v184, v182, v23
	v_fmac_f32_e32 v179, v240, v16
	v_add_f32_dpp v183, v183, v183 quad_perm:[1,0,3,2] row_mask:0xf bank_mask:0xf bound_ctrl:1
	v_add_f32_dpp v184, v184, v184 quad_perm:[1,0,3,2] row_mask:0xf bank_mask:0xf bound_ctrl:1
	v_fmac_f32_e32 v180, v240, v17
	v_add_f32_dpp v183, v183, v183 quad_perm:[2,3,0,1] row_mask:0xf bank_mask:0xf bound_ctrl:1
	v_add_f32_dpp v184, v184, v184 quad_perm:[2,3,0,1] row_mask:0xf bank_mask:0xf bound_ctrl:1
	v_fmac_f32_e32 v181, v240, v18
	v_add_f32_dpp v183, v183, v183 row_half_mirror row_mask:0xf bank_mask:0xf bound_ctrl:1
	v_fmac_f32_e32 v182, v240, v19
	s_nop 0
	v_add_f32_dpp v183, v183, v183 row_mirror row_mask:0xf bank_mask:0xf bound_ctrl:1
	v_fmac_f32_e32 v179, v183, v12
	v_fmac_f32_e32 v180, v183, v13
	v_fmac_f32_e32 v181, v183, v14
	v_fmac_f32_e32 v182, v183, v15
	ds_read_b128 v[8:11], v145 offset:15360
	ds_read_b128 v[12:15], v145 offset:23552
	ds_read_b128 v[16:19], v145 offset:31744
	ds_read_b128 v[20:23], v145 offset:39936
	s_waitcnt lgkmcnt(9)
	v_mul_f32_e32 v183, v179, v28
	v_mul_f32_e32 v238, v179, v40
	v_fmac_f32_e32 v183, v180, v29
	v_fmac_f32_e32 v238, v180, v41
	v_fmac_f32_e32 v183, v181, v30
	v_fmac_f32_e32 v238, v181, v42
	v_fmac_f32_e32 v183, v182, v31
	v_fmac_f32_e32 v238, v182, v43
	v_fmac_f32_e32 v179, v241, v36
	v_add_f32_dpp v183, v183, v183 quad_perm:[1,0,3,2] row_mask:0xf bank_mask:0xf bound_ctrl:1
	v_add_f32_dpp v238, v238, v238 quad_perm:[1,0,3,2] row_mask:0xf bank_mask:0xf bound_ctrl:1
	v_fmac_f32_e32 v180, v241, v37
	v_add_f32_dpp v183, v183, v183 quad_perm:[2,3,0,1] row_mask:0xf bank_mask:0xf bound_ctrl:1
	v_add_f32_dpp v238, v238, v238 quad_perm:[2,3,0,1] row_mask:0xf bank_mask:0xf bound_ctrl:1
	v_fmac_f32_e32 v181, v241, v38
	v_add_f32_dpp v183, v183, v183 row_half_mirror row_mask:0xf bank_mask:0xf bound_ctrl:1
	v_fmac_f32_e32 v182, v241, v39
	s_nop 0
	v_add_f32_dpp v183, v183, v183 row_mirror row_mask:0xf bank_mask:0xf bound_ctrl:1
	v_fmac_f32_e32 v179, v183, v32
	v_fmac_f32_e32 v180, v183, v33
	v_fmac_f32_e32 v181, v183, v34
	v_fmac_f32_e32 v182, v183, v35
	s_mov_b64 exec, s[12:13]
	ds_write2st64_b32 v185, v184, v238 offset0:124 offset1:120
	s_mov_b64 exec, -1
	ds_read_b128 v[28:31], v145 offset:15104
	ds_read_b128 v[32:35], v145 offset:23296
	ds_read_b128 v[36:39], v145 offset:31488
	ds_read_b128 v[40:43], v145 offset:39680
	ds_read2st64_b32 v[240:241], v151 offset0:219 offset1:218
	s_waitcnt lgkmcnt(10)
	v_mul_f32_e32 v183, v179, v48
	v_mul_f32_e32 v184, v179, v60
	v_fmac_f32_e32 v183, v180, v49
	v_fmac_f32_e32 v184, v180, v61
	v_fmac_f32_e32 v183, v181, v50
	v_fmac_f32_e32 v184, v181, v62
	v_fmac_f32_e32 v183, v182, v51
	v_fmac_f32_e32 v184, v182, v63
	v_fmac_f32_e32 v179, v242, v56
	v_add_f32_dpp v183, v183, v183 quad_perm:[1,0,3,2] row_mask:0xf bank_mask:0xf bound_ctrl:1
	v_add_f32_dpp v184, v184, v184 quad_perm:[1,0,3,2] row_mask:0xf bank_mask:0xf bound_ctrl:1
	v_fmac_f32_e32 v180, v242, v57
	v_add_f32_dpp v183, v183, v183 quad_perm:[2,3,0,1] row_mask:0xf bank_mask:0xf bound_ctrl:1
	v_add_f32_dpp v184, v184, v184 quad_perm:[2,3,0,1] row_mask:0xf bank_mask:0xf bound_ctrl:1
	v_fmac_f32_e32 v181, v242, v58
	v_add_f32_dpp v183, v183, v183 row_half_mirror row_mask:0xf bank_mask:0xf bound_ctrl:1
	v_fmac_f32_e32 v182, v242, v59
	s_nop 0
	v_add_f32_dpp v183, v183, v183 row_mirror row_mask:0xf bank_mask:0xf bound_ctrl:1
	v_fmac_f32_e32 v179, v183, v52
	v_fmac_f32_e32 v180, v183, v53
	v_fmac_f32_e32 v181, v183, v54
	v_fmac_f32_e32 v182, v183, v55
	ds_read_b128 v[48:51], v145 offset:14848
	ds_read_b128 v[52:55], v145 offset:23040
	ds_read_b128 v[56:59], v145 offset:31232
	ds_read_b128 v[60:63], v145 offset:39424
	s_waitcnt lgkmcnt(10)
	v_mul_f32_e32 v183, v179, v8
	v_mul_f32_e32 v238, v179, v20
	v_fmac_f32_e32 v183, v180, v9
	v_fmac_f32_e32 v238, v180, v21
	v_fmac_f32_e32 v183, v181, v10
	v_fmac_f32_e32 v238, v181, v22
	v_fmac_f32_e32 v183, v182, v11
	v_fmac_f32_e32 v238, v182, v23
	v_fmac_f32_e32 v179, v243, v16
	v_add_f32_dpp v183, v183, v183 quad_perm:[1,0,3,2] row_mask:0xf bank_mask:0xf bound_ctrl:1
	v_add_f32_dpp v238, v238, v238 quad_perm:[1,0,3,2] row_mask:0xf bank_mask:0xf bound_ctrl:1
	v_fmac_f32_e32 v180, v243, v17
	v_add_f32_dpp v183, v183, v183 quad_perm:[2,3,0,1] row_mask:0xf bank_mask:0xf bound_ctrl:1
	v_add_f32_dpp v238, v238, v238 quad_perm:[2,3,0,1] row_mask:0xf bank_mask:0xf bound_ctrl:1
	v_fmac_f32_e32 v181, v243, v18
	v_add_f32_dpp v183, v183, v183 row_half_mirror row_mask:0xf bank_mask:0xf bound_ctrl:1
	v_fmac_f32_e32 v182, v243, v19
	s_nop 0
	v_add_f32_dpp v183, v183, v183 row_mirror row_mask:0xf bank_mask:0xf bound_ctrl:1
	v_fmac_f32_e32 v179, v183, v12
	v_fmac_f32_e32 v180, v183, v13
	v_fmac_f32_e32 v181, v183, v14
	v_fmac_f32_e32 v182, v183, v15
	s_mov_b64 exec, s[12:13]
	ds_write2st64_b32 v185, v184, v238 offset0:116 offset1:112
	s_mov_b64 exec, -1
	ds_read_b128 v[8:11], v145 offset:14592
	ds_read_b128 v[12:15], v145 offset:22784
	ds_read_b128 v[16:19], v145 offset:30976
	ds_read_b128 v[20:23], v145 offset:39168
	ds_read2st64_b32 v[242:243], v151 offset0:217 offset1:216
	s_waitcnt lgkmcnt(10)
	v_mul_f32_e32 v183, v179, v28
	v_mul_f32_e32 v184, v179, v40
	v_fmac_f32_e32 v183, v180, v29
	v_fmac_f32_e32 v184, v180, v41
	v_fmac_f32_e32 v183, v181, v30
	v_fmac_f32_e32 v184, v181, v42
	v_fmac_f32_e32 v183, v182, v31
	v_fmac_f32_e32 v184, v182, v43
	v_fmac_f32_e32 v179, v240, v36
	v_add_f32_dpp v183, v183, v183 quad_perm:[1,0,3,2] row_mask:0xf bank_mask:0xf bound_ctrl:1
	v_add_f32_dpp v184, v184, v184 quad_perm:[1,0,3,2] row_mask:0xf bank_mask:0xf bound_ctrl:1
	v_fmac_f32_e32 v180, v240, v37
	v_add_f32_dpp v183, v183, v183 quad_perm:[2,3,0,1] row_mask:0xf bank_mask:0xf bound_ctrl:1
	v_add_f32_dpp v184, v184, v184 quad_perm:[2,3,0,1] row_mask:0xf bank_mask:0xf bound_ctrl:1
	v_fmac_f32_e32 v181, v240, v38
	v_add_f32_dpp v183, v183, v183 row_half_mirror row_mask:0xf bank_mask:0xf bound_ctrl:1
	v_fmac_f32_e32 v182, v240, v39
	s_nop 0
	v_add_f32_dpp v183, v183, v183 row_mirror row_mask:0xf bank_mask:0xf bound_ctrl:1
	v_fmac_f32_e32 v179, v183, v32
	v_fmac_f32_e32 v180, v183, v33
	v_fmac_f32_e32 v181, v183, v34
	v_fmac_f32_e32 v182, v183, v35
	ds_read_b128 v[28:31], v145 offset:14336
	ds_read_b128 v[32:35], v145 offset:22528
	ds_read_b128 v[36:39], v145 offset:30720
	ds_read_b128 v[40:43], v145 offset:38912
	s_waitcnt lgkmcnt(10)
	v_mul_f32_e32 v183, v179, v48
	v_mul_f32_e32 v238, v179, v60
	v_fmac_f32_e32 v183, v180, v49
	v_fmac_f32_e32 v238, v180, v61
	v_fmac_f32_e32 v183, v181, v50
	v_fmac_f32_e32 v238, v181, v62
	v_fmac_f32_e32 v183, v182, v51
	v_fmac_f32_e32 v238, v182, v63
	v_fmac_f32_e32 v179, v241, v56
	v_add_f32_dpp v183, v183, v183 quad_perm:[1,0,3,2] row_mask:0xf bank_mask:0xf bound_ctrl:1
	v_add_f32_dpp v238, v238, v238 quad_perm:[1,0,3,2] row_mask:0xf bank_mask:0xf bound_ctrl:1
	v_fmac_f32_e32 v180, v241, v57
	v_add_f32_dpp v183, v183, v183 quad_perm:[2,3,0,1] row_mask:0xf bank_mask:0xf bound_ctrl:1
	v_add_f32_dpp v238, v238, v238 quad_perm:[2,3,0,1] row_mask:0xf bank_mask:0xf bound_ctrl:1
	v_fmac_f32_e32 v181, v241, v58
	v_add_f32_dpp v183, v183, v183 row_half_mirror row_mask:0xf bank_mask:0xf bound_ctrl:1
	v_fmac_f32_e32 v182, v241, v59
	s_nop 0
	v_add_f32_dpp v183, v183, v183 row_mirror row_mask:0xf bank_mask:0xf bound_ctrl:1
	v_fmac_f32_e32 v179, v183, v52
	v_fmac_f32_e32 v180, v183, v53
	v_fmac_f32_e32 v181, v183, v54
	v_fmac_f32_e32 v182, v183, v55
	s_mov_b64 exec, s[12:13]
	ds_write2st64_b32 v185, v184, v238 offset0:108 offset1:104
	s_mov_b64 exec, -1
	ds_read_b128 v[48:51], v145 offset:14080
	ds_read_b128 v[52:55], v145 offset:22272
	ds_read_b128 v[56:59], v145 offset:30464
	ds_read_b128 v[60:63], v145 offset:38656
	ds_read2st64_b32 v[240:241], v151 offset0:215 offset1:214
	s_waitcnt lgkmcnt(10)
	v_mul_f32_e32 v183, v179, v8
	v_mul_f32_e32 v184, v179, v20
	v_fmac_f32_e32 v183, v180, v9
	v_fmac_f32_e32 v184, v180, v21
	v_fmac_f32_e32 v183, v181, v10
	v_fmac_f32_e32 v184, v181, v22
	v_fmac_f32_e32 v183, v182, v11
	v_fmac_f32_e32 v184, v182, v23
	v_fmac_f32_e32 v179, v242, v16
	v_add_f32_dpp v183, v183, v183 quad_perm:[1,0,3,2] row_mask:0xf bank_mask:0xf bound_ctrl:1
	v_add_f32_dpp v184, v184, v184 quad_perm:[1,0,3,2] row_mask:0xf bank_mask:0xf bound_ctrl:1
	v_fmac_f32_e32 v180, v242, v17
	v_add_f32_dpp v183, v183, v183 quad_perm:[2,3,0,1] row_mask:0xf bank_mask:0xf bound_ctrl:1
	v_add_f32_dpp v184, v184, v184 quad_perm:[2,3,0,1] row_mask:0xf bank_mask:0xf bound_ctrl:1
	v_fmac_f32_e32 v181, v242, v18
	v_add_f32_dpp v183, v183, v183 row_half_mirror row_mask:0xf bank_mask:0xf bound_ctrl:1
	v_fmac_f32_e32 v182, v242, v19
	s_nop 0
	v_add_f32_dpp v183, v183, v183 row_mirror row_mask:0xf bank_mask:0xf bound_ctrl:1
	v_fmac_f32_e32 v179, v183, v12
	v_fmac_f32_e32 v180, v183, v13
	v_fmac_f32_e32 v181, v183, v14
	v_fmac_f32_e32 v182, v183, v15
	ds_read_b128 v[8:11], v145 offset:13824
	ds_read_b128 v[12:15], v145 offset:22016
	ds_read_b128 v[16:19], v145 offset:30208
	ds_read_b128 v[20:23], v145 offset:38400
	s_waitcnt lgkmcnt(10)
	v_mul_f32_e32 v183, v179, v28
	v_mul_f32_e32 v238, v179, v40
	v_fmac_f32_e32 v183, v180, v29
	v_fmac_f32_e32 v238, v180, v41
	v_fmac_f32_e32 v183, v181, v30
	v_fmac_f32_e32 v238, v181, v42
	v_fmac_f32_e32 v183, v182, v31
	v_fmac_f32_e32 v238, v182, v43
	v_fmac_f32_e32 v179, v243, v36
	v_add_f32_dpp v183, v183, v183 quad_perm:[1,0,3,2] row_mask:0xf bank_mask:0xf bound_ctrl:1
	v_add_f32_dpp v238, v238, v238 quad_perm:[1,0,3,2] row_mask:0xf bank_mask:0xf bound_ctrl:1
	v_fmac_f32_e32 v180, v243, v37
	v_add_f32_dpp v183, v183, v183 quad_perm:[2,3,0,1] row_mask:0xf bank_mask:0xf bound_ctrl:1
	v_add_f32_dpp v238, v238, v238 quad_perm:[2,3,0,1] row_mask:0xf bank_mask:0xf bound_ctrl:1
	v_fmac_f32_e32 v181, v243, v38
	v_add_f32_dpp v183, v183, v183 row_half_mirror row_mask:0xf bank_mask:0xf bound_ctrl:1
	v_fmac_f32_e32 v182, v243, v39
	s_nop 0
	v_add_f32_dpp v183, v183, v183 row_mirror row_mask:0xf bank_mask:0xf bound_ctrl:1
	v_fmac_f32_e32 v179, v183, v32
	v_fmac_f32_e32 v180, v183, v33
	v_fmac_f32_e32 v181, v183, v34
	v_fmac_f32_e32 v182, v183, v35
	s_mov_b64 exec, s[12:13]
	ds_write2st64_b32 v185, v184, v238 offset0:100 offset1:96
	s_mov_b64 exec, -1
	ds_read_b128 v[28:31], v145 offset:13568
	ds_read_b128 v[32:35], v145 offset:21760
	ds_read_b128 v[36:39], v145 offset:29952
	ds_read_b128 v[40:43], v145 offset:38144
	ds_read2st64_b32 v[242:243], v151 offset0:213 offset1:212
	s_waitcnt lgkmcnt(10)
	v_mul_f32_e32 v183, v179, v48
	v_mul_f32_e32 v184, v179, v60
	v_fmac_f32_e32 v183, v180, v49
	v_fmac_f32_e32 v184, v180, v61
	v_fmac_f32_e32 v183, v181, v50
	v_fmac_f32_e32 v184, v181, v62
	v_fmac_f32_e32 v183, v182, v51
	v_fmac_f32_e32 v184, v182, v63
	v_fmac_f32_e32 v179, v240, v56
	v_add_f32_dpp v183, v183, v183 quad_perm:[1,0,3,2] row_mask:0xf bank_mask:0xf bound_ctrl:1
	v_add_f32_dpp v184, v184, v184 quad_perm:[1,0,3,2] row_mask:0xf bank_mask:0xf bound_ctrl:1
	v_fmac_f32_e32 v180, v240, v57
	v_add_f32_dpp v183, v183, v183 quad_perm:[2,3,0,1] row_mask:0xf bank_mask:0xf bound_ctrl:1
	v_add_f32_dpp v184, v184, v184 quad_perm:[2,3,0,1] row_mask:0xf bank_mask:0xf bound_ctrl:1
	v_fmac_f32_e32 v181, v240, v58
	v_add_f32_dpp v183, v183, v183 row_half_mirror row_mask:0xf bank_mask:0xf bound_ctrl:1
	v_fmac_f32_e32 v182, v240, v59
	s_nop 0
	v_add_f32_dpp v183, v183, v183 row_mirror row_mask:0xf bank_mask:0xf bound_ctrl:1
	v_fmac_f32_e32 v179, v183, v52
	v_fmac_f32_e32 v180, v183, v53
	v_fmac_f32_e32 v181, v183, v54
	v_fmac_f32_e32 v182, v183, v55
	ds_read_b128 v[48:51], v145 offset:13312
	ds_read_b128 v[52:55], v145 offset:21504
	ds_read_b128 v[56:59], v145 offset:29696
	ds_read_b128 v[60:63], v145 offset:37888
	s_waitcnt lgkmcnt(10)
	v_mul_f32_e32 v183, v179, v8
	v_mul_f32_e32 v238, v179, v20
	v_fmac_f32_e32 v183, v180, v9
	v_fmac_f32_e32 v238, v180, v21
	v_fmac_f32_e32 v183, v181, v10
	v_fmac_f32_e32 v238, v181, v22
	v_fmac_f32_e32 v183, v182, v11
	v_fmac_f32_e32 v238, v182, v23
	v_fmac_f32_e32 v179, v241, v16
	v_add_f32_dpp v183, v183, v183 quad_perm:[1,0,3,2] row_mask:0xf bank_mask:0xf bound_ctrl:1
	v_add_f32_dpp v238, v238, v238 quad_perm:[1,0,3,2] row_mask:0xf bank_mask:0xf bound_ctrl:1
	v_fmac_f32_e32 v180, v241, v17
	v_add_f32_dpp v183, v183, v183 quad_perm:[2,3,0,1] row_mask:0xf bank_mask:0xf bound_ctrl:1
	v_add_f32_dpp v238, v238, v238 quad_perm:[2,3,0,1] row_mask:0xf bank_mask:0xf bound_ctrl:1
	v_fmac_f32_e32 v181, v241, v18
	v_add_f32_dpp v183, v183, v183 row_half_mirror row_mask:0xf bank_mask:0xf bound_ctrl:1
	v_fmac_f32_e32 v182, v241, v19
	s_nop 0
	v_add_f32_dpp v183, v183, v183 row_mirror row_mask:0xf bank_mask:0xf bound_ctrl:1
	v_fmac_f32_e32 v179, v183, v12
	v_fmac_f32_e32 v180, v183, v13
	v_fmac_f32_e32 v181, v183, v14
	v_fmac_f32_e32 v182, v183, v15
	s_mov_b64 exec, s[12:13]
	ds_write2st64_b32 v185, v184, v238 offset0:92 offset1:88
	s_mov_b64 exec, -1
	ds_read_b128 v[8:11], v145 offset:13056
	ds_read_b128 v[12:15], v145 offset:21248
	ds_read_b128 v[16:19], v145 offset:29440
	ds_read_b128 v[20:23], v145 offset:37632
	ds_read2st64_b32 v[240:241], v151 offset0:211 offset1:210
	s_waitcnt lgkmcnt(10)
	v_mul_f32_e32 v183, v179, v28
	v_mul_f32_e32 v184, v179, v40
	v_fmac_f32_e32 v183, v180, v29
	v_fmac_f32_e32 v184, v180, v41
	v_fmac_f32_e32 v183, v181, v30
	v_fmac_f32_e32 v184, v181, v42
	v_fmac_f32_e32 v183, v182, v31
	v_fmac_f32_e32 v184, v182, v43
	v_fmac_f32_e32 v179, v242, v36
	v_add_f32_dpp v183, v183, v183 quad_perm:[1,0,3,2] row_mask:0xf bank_mask:0xf bound_ctrl:1
	v_add_f32_dpp v184, v184, v184 quad_perm:[1,0,3,2] row_mask:0xf bank_mask:0xf bound_ctrl:1
	v_fmac_f32_e32 v180, v242, v37
	v_add_f32_dpp v183, v183, v183 quad_perm:[2,3,0,1] row_mask:0xf bank_mask:0xf bound_ctrl:1
	v_add_f32_dpp v184, v184, v184 quad_perm:[2,3,0,1] row_mask:0xf bank_mask:0xf bound_ctrl:1
	v_fmac_f32_e32 v181, v242, v38
	v_add_f32_dpp v183, v183, v183 row_half_mirror row_mask:0xf bank_mask:0xf bound_ctrl:1
	v_fmac_f32_e32 v182, v242, v39
	s_nop 0
	v_add_f32_dpp v183, v183, v183 row_mirror row_mask:0xf bank_mask:0xf bound_ctrl:1
	v_fmac_f32_e32 v179, v183, v32
	v_fmac_f32_e32 v180, v183, v33
	v_fmac_f32_e32 v181, v183, v34
	v_fmac_f32_e32 v182, v183, v35
	ds_read_b128 v[28:31], v145 offset:12800
	ds_read_b128 v[32:35], v145 offset:20992
	ds_read_b128 v[36:39], v145 offset:29184
	ds_read_b128 v[40:43], v145 offset:37376
	s_waitcnt lgkmcnt(10)
	v_mul_f32_e32 v183, v179, v48
	v_mul_f32_e32 v238, v179, v60
	v_fmac_f32_e32 v183, v180, v49
	v_fmac_f32_e32 v238, v180, v61
	v_fmac_f32_e32 v183, v181, v50
	v_fmac_f32_e32 v238, v181, v62
	v_fmac_f32_e32 v183, v182, v51
	v_fmac_f32_e32 v238, v182, v63
	v_fmac_f32_e32 v179, v243, v56
	v_add_f32_dpp v183, v183, v183 quad_perm:[1,0,3,2] row_mask:0xf bank_mask:0xf bound_ctrl:1
	v_add_f32_dpp v238, v238, v238 quad_perm:[1,0,3,2] row_mask:0xf bank_mask:0xf bound_ctrl:1
	v_fmac_f32_e32 v180, v243, v57
	v_add_f32_dpp v183, v183, v183 quad_perm:[2,3,0,1] row_mask:0xf bank_mask:0xf bound_ctrl:1
	v_add_f32_dpp v238, v238, v238 quad_perm:[2,3,0,1] row_mask:0xf bank_mask:0xf bound_ctrl:1
	v_fmac_f32_e32 v181, v243, v58
	v_add_f32_dpp v183, v183, v183 row_half_mirror row_mask:0xf bank_mask:0xf bound_ctrl:1
	v_fmac_f32_e32 v182, v243, v59
	s_nop 0
	v_add_f32_dpp v183, v183, v183 row_mirror row_mask:0xf bank_mask:0xf bound_ctrl:1
	v_fmac_f32_e32 v179, v183, v52
	v_fmac_f32_e32 v180, v183, v53
	v_fmac_f32_e32 v181, v183, v54
	v_fmac_f32_e32 v182, v183, v55
	s_mov_b64 exec, s[12:13]
	ds_write2st64_b32 v185, v184, v238 offset0:84 offset1:80
	s_mov_b64 exec, -1
	ds_read_b128 v[48:51], v145 offset:12544
	ds_read_b128 v[52:55], v145 offset:20736
	ds_read_b128 v[56:59], v145 offset:28928
	ds_read_b128 v[60:63], v145 offset:37120
	ds_read2st64_b32 v[242:243], v151 offset0:209 offset1:208
	s_waitcnt lgkmcnt(10)
	v_mul_f32_e32 v183, v179, v8
	v_mul_f32_e32 v184, v179, v20
	v_fmac_f32_e32 v183, v180, v9
	v_fmac_f32_e32 v184, v180, v21
	v_fmac_f32_e32 v183, v181, v10
	v_fmac_f32_e32 v184, v181, v22
	v_fmac_f32_e32 v183, v182, v11
	v_fmac_f32_e32 v184, v182, v23
	v_fmac_f32_e32 v179, v240, v16
	v_add_f32_dpp v183, v183, v183 quad_perm:[1,0,3,2] row_mask:0xf bank_mask:0xf bound_ctrl:1
	v_add_f32_dpp v184, v184, v184 quad_perm:[1,0,3,2] row_mask:0xf bank_mask:0xf bound_ctrl:1
	v_fmac_f32_e32 v180, v240, v17
	v_add_f32_dpp v183, v183, v183 quad_perm:[2,3,0,1] row_mask:0xf bank_mask:0xf bound_ctrl:1
	v_add_f32_dpp v184, v184, v184 quad_perm:[2,3,0,1] row_mask:0xf bank_mask:0xf bound_ctrl:1
	v_fmac_f32_e32 v181, v240, v18
	v_add_f32_dpp v183, v183, v183 row_half_mirror row_mask:0xf bank_mask:0xf bound_ctrl:1
	v_fmac_f32_e32 v182, v240, v19
	s_nop 0
	v_add_f32_dpp v183, v183, v183 row_mirror row_mask:0xf bank_mask:0xf bound_ctrl:1
	v_fmac_f32_e32 v179, v183, v12
	v_fmac_f32_e32 v180, v183, v13
	v_fmac_f32_e32 v181, v183, v14
	v_fmac_f32_e32 v182, v183, v15
	ds_read_b128 v[8:11], v145 offset:12288
	ds_read_b128 v[12:15], v145 offset:20480
	ds_read_b128 v[16:19], v145 offset:28672
	ds_read_b128 v[20:23], v145 offset:36864
	s_waitcnt lgkmcnt(10)
	v_mul_f32_e32 v183, v179, v28
	v_mul_f32_e32 v238, v179, v40
	v_fmac_f32_e32 v183, v180, v29
	v_fmac_f32_e32 v238, v180, v41
	v_fmac_f32_e32 v183, v181, v30
	v_fmac_f32_e32 v238, v181, v42
	v_fmac_f32_e32 v183, v182, v31
	v_fmac_f32_e32 v238, v182, v43
	v_fmac_f32_e32 v179, v241, v36
	v_add_f32_dpp v183, v183, v183 quad_perm:[1,0,3,2] row_mask:0xf bank_mask:0xf bound_ctrl:1
	v_add_f32_dpp v238, v238, v238 quad_perm:[1,0,3,2] row_mask:0xf bank_mask:0xf bound_ctrl:1
	v_fmac_f32_e32 v180, v241, v37
	v_add_f32_dpp v183, v183, v183 quad_perm:[2,3,0,1] row_mask:0xf bank_mask:0xf bound_ctrl:1
	v_add_f32_dpp v238, v238, v238 quad_perm:[2,3,0,1] row_mask:0xf bank_mask:0xf bound_ctrl:1
	v_fmac_f32_e32 v181, v241, v38
	v_add_f32_dpp v183, v183, v183 row_half_mirror row_mask:0xf bank_mask:0xf bound_ctrl:1
	v_fmac_f32_e32 v182, v241, v39
	s_nop 0
	v_add_f32_dpp v183, v183, v183 row_mirror row_mask:0xf bank_mask:0xf bound_ctrl:1
	v_fmac_f32_e32 v179, v183, v32
	v_fmac_f32_e32 v180, v183, v33
	v_fmac_f32_e32 v181, v183, v34
	v_fmac_f32_e32 v182, v183, v35
	s_mov_b64 exec, s[12:13]
	ds_write2st64_b32 v185, v184, v238 offset0:76 offset1:72
	s_mov_b64 exec, -1
	ds_read_b128 v[28:31], v145 offset:12032
	ds_read_b128 v[32:35], v145 offset:20224
	ds_read_b128 v[36:39], v145 offset:28416
	ds_read_b128 v[40:43], v145 offset:36608
	ds_read2st64_b32 v[240:241], v151 offset0:207 offset1:206
	s_waitcnt lgkmcnt(10)
	v_mul_f32_e32 v183, v179, v48
	v_mul_f32_e32 v184, v179, v60
	v_fmac_f32_e32 v183, v180, v49
	v_fmac_f32_e32 v184, v180, v61
	v_fmac_f32_e32 v183, v181, v50
	v_fmac_f32_e32 v184, v181, v62
	v_fmac_f32_e32 v183, v182, v51
	v_fmac_f32_e32 v184, v182, v63
	v_fmac_f32_e32 v179, v242, v56
	v_add_f32_dpp v183, v183, v183 quad_perm:[1,0,3,2] row_mask:0xf bank_mask:0xf bound_ctrl:1
	v_add_f32_dpp v184, v184, v184 quad_perm:[1,0,3,2] row_mask:0xf bank_mask:0xf bound_ctrl:1
	v_fmac_f32_e32 v180, v242, v57
	v_add_f32_dpp v183, v183, v183 quad_perm:[2,3,0,1] row_mask:0xf bank_mask:0xf bound_ctrl:1
	v_add_f32_dpp v184, v184, v184 quad_perm:[2,3,0,1] row_mask:0xf bank_mask:0xf bound_ctrl:1
	v_fmac_f32_e32 v181, v242, v58
	v_add_f32_dpp v183, v183, v183 row_half_mirror row_mask:0xf bank_mask:0xf bound_ctrl:1
	v_fmac_f32_e32 v182, v242, v59
	s_nop 0
	v_add_f32_dpp v183, v183, v183 row_mirror row_mask:0xf bank_mask:0xf bound_ctrl:1
	v_fmac_f32_e32 v179, v183, v52
	v_fmac_f32_e32 v180, v183, v53
	v_fmac_f32_e32 v181, v183, v54
	v_fmac_f32_e32 v182, v183, v55
	ds_read_b128 v[48:51], v145 offset:11776
	ds_read_b128 v[52:55], v145 offset:19968
	ds_read_b128 v[56:59], v145 offset:28160
	ds_read_b128 v[60:63], v145 offset:36352
	s_waitcnt lgkmcnt(10)
	v_mul_f32_e32 v183, v179, v8
	v_mul_f32_e32 v238, v179, v20
	v_fmac_f32_e32 v183, v180, v9
	v_fmac_f32_e32 v238, v180, v21
	v_fmac_f32_e32 v183, v181, v10
	v_fmac_f32_e32 v238, v181, v22
	v_fmac_f32_e32 v183, v182, v11
	v_fmac_f32_e32 v238, v182, v23
	v_fmac_f32_e32 v179, v243, v16
	v_add_f32_dpp v183, v183, v183 quad_perm:[1,0,3,2] row_mask:0xf bank_mask:0xf bound_ctrl:1
	v_add_f32_dpp v238, v238, v238 quad_perm:[1,0,3,2] row_mask:0xf bank_mask:0xf bound_ctrl:1
	v_fmac_f32_e32 v180, v243, v17
	v_add_f32_dpp v183, v183, v183 quad_perm:[2,3,0,1] row_mask:0xf bank_mask:0xf bound_ctrl:1
	v_add_f32_dpp v238, v238, v238 quad_perm:[2,3,0,1] row_mask:0xf bank_mask:0xf bound_ctrl:1
	v_fmac_f32_e32 v181, v243, v18
	v_add_f32_dpp v183, v183, v183 row_half_mirror row_mask:0xf bank_mask:0xf bound_ctrl:1
	v_fmac_f32_e32 v182, v243, v19
	s_nop 0
	v_add_f32_dpp v183, v183, v183 row_mirror row_mask:0xf bank_mask:0xf bound_ctrl:1
	v_fmac_f32_e32 v179, v183, v12
	v_fmac_f32_e32 v180, v183, v13
	v_fmac_f32_e32 v181, v183, v14
	v_fmac_f32_e32 v182, v183, v15
	s_mov_b64 exec, s[12:13]
	ds_write2st64_b32 v185, v184, v238 offset0:68 offset1:64
	s_mov_b64 exec, -1
	ds_read_b128 v[8:11], v145 offset:11520
	ds_read_b128 v[12:15], v145 offset:19712
	ds_read_b128 v[16:19], v145 offset:27904
	ds_read_b128 v[20:23], v145 offset:36096
	ds_read2st64_b32 v[242:243], v151 offset0:205 offset1:204
	s_waitcnt lgkmcnt(10)
	v_mul_f32_e32 v183, v179, v28
	v_mul_f32_e32 v184, v179, v40
	v_fmac_f32_e32 v183, v180, v29
	v_fmac_f32_e32 v184, v180, v41
	v_fmac_f32_e32 v183, v181, v30
	v_fmac_f32_e32 v184, v181, v42
	v_fmac_f32_e32 v183, v182, v31
	v_fmac_f32_e32 v184, v182, v43
	v_fmac_f32_e32 v179, v240, v36
	v_add_f32_dpp v183, v183, v183 quad_perm:[1,0,3,2] row_mask:0xf bank_mask:0xf bound_ctrl:1
	v_add_f32_dpp v184, v184, v184 quad_perm:[1,0,3,2] row_mask:0xf bank_mask:0xf bound_ctrl:1
	v_fmac_f32_e32 v180, v240, v37
	v_add_f32_dpp v183, v183, v183 quad_perm:[2,3,0,1] row_mask:0xf bank_mask:0xf bound_ctrl:1
	v_add_f32_dpp v184, v184, v184 quad_perm:[2,3,0,1] row_mask:0xf bank_mask:0xf bound_ctrl:1
	v_fmac_f32_e32 v181, v240, v38
	v_add_f32_dpp v183, v183, v183 row_half_mirror row_mask:0xf bank_mask:0xf bound_ctrl:1
	v_fmac_f32_e32 v182, v240, v39
	s_nop 0
	v_add_f32_dpp v183, v183, v183 row_mirror row_mask:0xf bank_mask:0xf bound_ctrl:1
	v_fmac_f32_e32 v179, v183, v32
	v_fmac_f32_e32 v180, v183, v33
	v_fmac_f32_e32 v181, v183, v34
	v_fmac_f32_e32 v182, v183, v35
	ds_read_b128 v[28:31], v145 offset:11264
	ds_read_b128 v[32:35], v145 offset:19456
	ds_read_b128 v[36:39], v145 offset:27648
	ds_read_b128 v[40:43], v145 offset:35840
	s_waitcnt lgkmcnt(10)
	v_mul_f32_e32 v183, v179, v48
	v_mul_f32_e32 v238, v179, v60
	v_fmac_f32_e32 v183, v180, v49
	v_fmac_f32_e32 v238, v180, v61
	v_fmac_f32_e32 v183, v181, v50
	v_fmac_f32_e32 v238, v181, v62
	v_fmac_f32_e32 v183, v182, v51
	v_fmac_f32_e32 v238, v182, v63
	v_fmac_f32_e32 v179, v241, v56
	v_add_f32_dpp v183, v183, v183 quad_perm:[1,0,3,2] row_mask:0xf bank_mask:0xf bound_ctrl:1
	v_add_f32_dpp v238, v238, v238 quad_perm:[1,0,3,2] row_mask:0xf bank_mask:0xf bound_ctrl:1
	v_fmac_f32_e32 v180, v241, v57
	v_add_f32_dpp v183, v183, v183 quad_perm:[2,3,0,1] row_mask:0xf bank_mask:0xf bound_ctrl:1
	v_add_f32_dpp v238, v238, v238 quad_perm:[2,3,0,1] row_mask:0xf bank_mask:0xf bound_ctrl:1
	v_fmac_f32_e32 v181, v241, v58
	v_add_f32_dpp v183, v183, v183 row_half_mirror row_mask:0xf bank_mask:0xf bound_ctrl:1
	v_fmac_f32_e32 v182, v241, v59
	s_nop 0
	v_add_f32_dpp v183, v183, v183 row_mirror row_mask:0xf bank_mask:0xf bound_ctrl:1
	v_fmac_f32_e32 v179, v183, v52
	v_fmac_f32_e32 v180, v183, v53
	v_fmac_f32_e32 v181, v183, v54
	v_fmac_f32_e32 v182, v183, v55
	s_mov_b64 exec, s[12:13]
	ds_write2st64_b32 v185, v184, v238 offset0:60 offset1:56
	s_mov_b64 exec, -1
	ds_read_b128 v[48:51], v145 offset:11008
	ds_read_b128 v[52:55], v145 offset:19200
	ds_read_b128 v[56:59], v145 offset:27392
	ds_read_b128 v[60:63], v145 offset:35584
	ds_read2st64_b32 v[240:241], v151 offset0:203 offset1:202
	s_waitcnt lgkmcnt(10)
	v_mul_f32_e32 v183, v179, v8
	v_mul_f32_e32 v184, v179, v20
	v_fmac_f32_e32 v183, v180, v9
	v_fmac_f32_e32 v184, v180, v21
	v_fmac_f32_e32 v183, v181, v10
	v_fmac_f32_e32 v184, v181, v22
	v_fmac_f32_e32 v183, v182, v11
	v_fmac_f32_e32 v184, v182, v23
	v_fmac_f32_e32 v179, v242, v16
	v_add_f32_dpp v183, v183, v183 quad_perm:[1,0,3,2] row_mask:0xf bank_mask:0xf bound_ctrl:1
	v_add_f32_dpp v184, v184, v184 quad_perm:[1,0,3,2] row_mask:0xf bank_mask:0xf bound_ctrl:1
	v_fmac_f32_e32 v180, v242, v17
	v_add_f32_dpp v183, v183, v183 quad_perm:[2,3,0,1] row_mask:0xf bank_mask:0xf bound_ctrl:1
	v_add_f32_dpp v184, v184, v184 quad_perm:[2,3,0,1] row_mask:0xf bank_mask:0xf bound_ctrl:1
	v_fmac_f32_e32 v181, v242, v18
	v_add_f32_dpp v183, v183, v183 row_half_mirror row_mask:0xf bank_mask:0xf bound_ctrl:1
	v_fmac_f32_e32 v182, v242, v19
	s_nop 0
	v_add_f32_dpp v183, v183, v183 row_mirror row_mask:0xf bank_mask:0xf bound_ctrl:1
	v_fmac_f32_e32 v179, v183, v12
	v_fmac_f32_e32 v180, v183, v13
	v_fmac_f32_e32 v181, v183, v14
	v_fmac_f32_e32 v182, v183, v15
	ds_read_b128 v[8:11], v145 offset:10752
	ds_read_b128 v[12:15], v145 offset:18944
	ds_read_b128 v[16:19], v145 offset:27136
	ds_read_b128 v[20:23], v145 offset:35328
	s_waitcnt lgkmcnt(10)
	v_mul_f32_e32 v183, v179, v28
	v_mul_f32_e32 v238, v179, v40
	v_fmac_f32_e32 v183, v180, v29
	v_fmac_f32_e32 v238, v180, v41
	v_fmac_f32_e32 v183, v181, v30
	v_fmac_f32_e32 v238, v181, v42
	v_fmac_f32_e32 v183, v182, v31
	v_fmac_f32_e32 v238, v182, v43
	v_fmac_f32_e32 v179, v243, v36
	v_add_f32_dpp v183, v183, v183 quad_perm:[1,0,3,2] row_mask:0xf bank_mask:0xf bound_ctrl:1
	v_add_f32_dpp v238, v238, v238 quad_perm:[1,0,3,2] row_mask:0xf bank_mask:0xf bound_ctrl:1
	v_fmac_f32_e32 v180, v243, v37
	v_add_f32_dpp v183, v183, v183 quad_perm:[2,3,0,1] row_mask:0xf bank_mask:0xf bound_ctrl:1
	v_add_f32_dpp v238, v238, v238 quad_perm:[2,3,0,1] row_mask:0xf bank_mask:0xf bound_ctrl:1
	v_fmac_f32_e32 v181, v243, v38
	v_add_f32_dpp v183, v183, v183 row_half_mirror row_mask:0xf bank_mask:0xf bound_ctrl:1
	v_fmac_f32_e32 v182, v243, v39
	s_nop 0
	v_add_f32_dpp v183, v183, v183 row_mirror row_mask:0xf bank_mask:0xf bound_ctrl:1
	v_fmac_f32_e32 v179, v183, v32
	v_fmac_f32_e32 v180, v183, v33
	v_fmac_f32_e32 v181, v183, v34
	v_fmac_f32_e32 v182, v183, v35
	s_mov_b64 exec, s[12:13]
	ds_write2st64_b32 v185, v184, v238 offset0:52 offset1:48
	s_mov_b64 exec, -1
	ds_read_b128 v[28:31], v145 offset:10496
	ds_read_b128 v[32:35], v145 offset:18688
	ds_read_b128 v[36:39], v145 offset:26880
	ds_read_b128 v[40:43], v145 offset:35072
	ds_read2st64_b32 v[242:243], v151 offset0:201 offset1:200
	s_waitcnt lgkmcnt(10)
	v_mul_f32_e32 v183, v179, v48
	v_mul_f32_e32 v184, v179, v60
	v_fmac_f32_e32 v183, v180, v49
	v_fmac_f32_e32 v184, v180, v61
	v_fmac_f32_e32 v183, v181, v50
	v_fmac_f32_e32 v184, v181, v62
	v_fmac_f32_e32 v183, v182, v51
	v_fmac_f32_e32 v184, v182, v63
	v_fmac_f32_e32 v179, v240, v56
	v_add_f32_dpp v183, v183, v183 quad_perm:[1,0,3,2] row_mask:0xf bank_mask:0xf bound_ctrl:1
	v_add_f32_dpp v184, v184, v184 quad_perm:[1,0,3,2] row_mask:0xf bank_mask:0xf bound_ctrl:1
	v_fmac_f32_e32 v180, v240, v57
	v_add_f32_dpp v183, v183, v183 quad_perm:[2,3,0,1] row_mask:0xf bank_mask:0xf bound_ctrl:1
	v_add_f32_dpp v184, v184, v184 quad_perm:[2,3,0,1] row_mask:0xf bank_mask:0xf bound_ctrl:1
	v_fmac_f32_e32 v181, v240, v58
	v_add_f32_dpp v183, v183, v183 row_half_mirror row_mask:0xf bank_mask:0xf bound_ctrl:1
	v_fmac_f32_e32 v182, v240, v59
	s_nop 0
	v_add_f32_dpp v183, v183, v183 row_mirror row_mask:0xf bank_mask:0xf bound_ctrl:1
	v_fmac_f32_e32 v179, v183, v52
	v_fmac_f32_e32 v180, v183, v53
	v_fmac_f32_e32 v181, v183, v54
	v_fmac_f32_e32 v182, v183, v55
	ds_read_b128 v[48:51], v145 offset:10240
	ds_read_b128 v[52:55], v145 offset:18432
	ds_read_b128 v[56:59], v145 offset:26624
	ds_read_b128 v[60:63], v145 offset:34816
	s_waitcnt lgkmcnt(10)
	v_mul_f32_e32 v183, v179, v8
	v_mul_f32_e32 v238, v179, v20
	v_fmac_f32_e32 v183, v180, v9
	v_fmac_f32_e32 v238, v180, v21
	v_fmac_f32_e32 v183, v181, v10
	v_fmac_f32_e32 v238, v181, v22
	v_fmac_f32_e32 v183, v182, v11
	v_fmac_f32_e32 v238, v182, v23
	v_fmac_f32_e32 v179, v241, v16
	v_add_f32_dpp v183, v183, v183 quad_perm:[1,0,3,2] row_mask:0xf bank_mask:0xf bound_ctrl:1
	v_add_f32_dpp v238, v238, v238 quad_perm:[1,0,3,2] row_mask:0xf bank_mask:0xf bound_ctrl:1
	v_fmac_f32_e32 v180, v241, v17
	v_add_f32_dpp v183, v183, v183 quad_perm:[2,3,0,1] row_mask:0xf bank_mask:0xf bound_ctrl:1
	v_add_f32_dpp v238, v238, v238 quad_perm:[2,3,0,1] row_mask:0xf bank_mask:0xf bound_ctrl:1
	v_fmac_f32_e32 v181, v241, v18
	v_add_f32_dpp v183, v183, v183 row_half_mirror row_mask:0xf bank_mask:0xf bound_ctrl:1
	v_fmac_f32_e32 v182, v241, v19
	s_nop 0
	v_add_f32_dpp v183, v183, v183 row_mirror row_mask:0xf bank_mask:0xf bound_ctrl:1
	v_fmac_f32_e32 v179, v183, v12
	v_fmac_f32_e32 v180, v183, v13
	v_fmac_f32_e32 v181, v183, v14
	v_fmac_f32_e32 v182, v183, v15
	s_mov_b64 exec, s[12:13]
	ds_write2st64_b32 v185, v184, v238 offset0:44 offset1:40
	s_mov_b64 exec, -1
	ds_read_b128 v[8:11], v145 offset:9984
	ds_read_b128 v[12:15], v145 offset:18176
	ds_read_b128 v[16:19], v145 offset:26368
	ds_read_b128 v[20:23], v145 offset:34560
	ds_read2st64_b32 v[240:241], v151 offset0:199 offset1:198
	s_waitcnt lgkmcnt(10)
	v_mul_f32_e32 v183, v179, v28
	v_mul_f32_e32 v184, v179, v40
	v_fmac_f32_e32 v183, v180, v29
	v_fmac_f32_e32 v184, v180, v41
	v_fmac_f32_e32 v183, v181, v30
	v_fmac_f32_e32 v184, v181, v42
	v_fmac_f32_e32 v183, v182, v31
	v_fmac_f32_e32 v184, v182, v43
	v_fmac_f32_e32 v179, v242, v36
	v_add_f32_dpp v183, v183, v183 quad_perm:[1,0,3,2] row_mask:0xf bank_mask:0xf bound_ctrl:1
	v_add_f32_dpp v184, v184, v184 quad_perm:[1,0,3,2] row_mask:0xf bank_mask:0xf bound_ctrl:1
	v_fmac_f32_e32 v180, v242, v37
	v_add_f32_dpp v183, v183, v183 quad_perm:[2,3,0,1] row_mask:0xf bank_mask:0xf bound_ctrl:1
	v_add_f32_dpp v184, v184, v184 quad_perm:[2,3,0,1] row_mask:0xf bank_mask:0xf bound_ctrl:1
	v_fmac_f32_e32 v181, v242, v38
	v_add_f32_dpp v183, v183, v183 row_half_mirror row_mask:0xf bank_mask:0xf bound_ctrl:1
	v_fmac_f32_e32 v182, v242, v39
	s_nop 0
	v_add_f32_dpp v183, v183, v183 row_mirror row_mask:0xf bank_mask:0xf bound_ctrl:1
	v_fmac_f32_e32 v179, v183, v32
	v_fmac_f32_e32 v180, v183, v33
	v_fmac_f32_e32 v181, v183, v34
	v_fmac_f32_e32 v182, v183, v35
	ds_read_b128 v[28:31], v145 offset:9728
	ds_read_b128 v[32:35], v145 offset:17920
	ds_read_b128 v[36:39], v145 offset:26112
	ds_read_b128 v[40:43], v145 offset:34304
	s_waitcnt lgkmcnt(10)
	v_mul_f32_e32 v183, v179, v48
	v_mul_f32_e32 v238, v179, v60
	v_fmac_f32_e32 v183, v180, v49
	v_fmac_f32_e32 v238, v180, v61
	v_fmac_f32_e32 v183, v181, v50
	v_fmac_f32_e32 v238, v181, v62
	v_fmac_f32_e32 v183, v182, v51
	v_fmac_f32_e32 v238, v182, v63
	v_fmac_f32_e32 v179, v243, v56
	v_add_f32_dpp v183, v183, v183 quad_perm:[1,0,3,2] row_mask:0xf bank_mask:0xf bound_ctrl:1
	v_add_f32_dpp v238, v238, v238 quad_perm:[1,0,3,2] row_mask:0xf bank_mask:0xf bound_ctrl:1
	v_fmac_f32_e32 v180, v243, v57
	v_add_f32_dpp v183, v183, v183 quad_perm:[2,3,0,1] row_mask:0xf bank_mask:0xf bound_ctrl:1
	v_add_f32_dpp v238, v238, v238 quad_perm:[2,3,0,1] row_mask:0xf bank_mask:0xf bound_ctrl:1
	v_fmac_f32_e32 v181, v243, v58
	v_add_f32_dpp v183, v183, v183 row_half_mirror row_mask:0xf bank_mask:0xf bound_ctrl:1
	v_fmac_f32_e32 v182, v243, v59
	s_nop 0
	v_add_f32_dpp v183, v183, v183 row_mirror row_mask:0xf bank_mask:0xf bound_ctrl:1
	v_fmac_f32_e32 v179, v183, v52
	v_fmac_f32_e32 v180, v183, v53
	v_fmac_f32_e32 v181, v183, v54
	v_fmac_f32_e32 v182, v183, v55
	s_mov_b64 exec, s[12:13]
	ds_write2st64_b32 v185, v184, v238 offset0:36 offset1:32
	s_mov_b64 exec, -1
	ds_read_b128 v[48:51], v145 offset:9472
	ds_read_b128 v[52:55], v145 offset:17664
	ds_read_b128 v[56:59], v145 offset:25856
	ds_read_b128 v[60:63], v145 offset:34048
	ds_read2st64_b32 v[242:243], v151 offset0:197 offset1:196
	s_waitcnt lgkmcnt(10)
	v_mul_f32_e32 v183, v179, v8
	v_mul_f32_e32 v184, v179, v20
	v_fmac_f32_e32 v183, v180, v9
	v_fmac_f32_e32 v184, v180, v21
	v_fmac_f32_e32 v183, v181, v10
	v_fmac_f32_e32 v184, v181, v22
	v_fmac_f32_e32 v183, v182, v11
	v_fmac_f32_e32 v184, v182, v23
	v_fmac_f32_e32 v179, v240, v16
	v_add_f32_dpp v183, v183, v183 quad_perm:[1,0,3,2] row_mask:0xf bank_mask:0xf bound_ctrl:1
	v_add_f32_dpp v184, v184, v184 quad_perm:[1,0,3,2] row_mask:0xf bank_mask:0xf bound_ctrl:1
	v_fmac_f32_e32 v180, v240, v17
	v_add_f32_dpp v183, v183, v183 quad_perm:[2,3,0,1] row_mask:0xf bank_mask:0xf bound_ctrl:1
	v_add_f32_dpp v184, v184, v184 quad_perm:[2,3,0,1] row_mask:0xf bank_mask:0xf bound_ctrl:1
	v_fmac_f32_e32 v181, v240, v18
	v_add_f32_dpp v183, v183, v183 row_half_mirror row_mask:0xf bank_mask:0xf bound_ctrl:1
	v_fmac_f32_e32 v182, v240, v19
	s_nop 0
	v_add_f32_dpp v183, v183, v183 row_mirror row_mask:0xf bank_mask:0xf bound_ctrl:1
	v_fmac_f32_e32 v179, v183, v12
	v_fmac_f32_e32 v180, v183, v13
	v_fmac_f32_e32 v181, v183, v14
	v_fmac_f32_e32 v182, v183, v15
	ds_read_b128 v[8:11], v145 offset:9216
	ds_read_b128 v[12:15], v145 offset:17408
	ds_read_b128 v[16:19], v145 offset:25600
	ds_read_b128 v[20:23], v145 offset:33792
	s_waitcnt lgkmcnt(10)
	v_mul_f32_e32 v183, v179, v28
	v_mul_f32_e32 v238, v179, v40
	v_fmac_f32_e32 v183, v180, v29
	v_fmac_f32_e32 v238, v180, v41
	v_fmac_f32_e32 v183, v181, v30
	v_fmac_f32_e32 v238, v181, v42
	v_fmac_f32_e32 v183, v182, v31
	v_fmac_f32_e32 v238, v182, v43
	v_fmac_f32_e32 v179, v241, v36
	v_add_f32_dpp v183, v183, v183 quad_perm:[1,0,3,2] row_mask:0xf bank_mask:0xf bound_ctrl:1
	v_add_f32_dpp v238, v238, v238 quad_perm:[1,0,3,2] row_mask:0xf bank_mask:0xf bound_ctrl:1
	v_fmac_f32_e32 v180, v241, v37
	v_add_f32_dpp v183, v183, v183 quad_perm:[2,3,0,1] row_mask:0xf bank_mask:0xf bound_ctrl:1
	v_add_f32_dpp v238, v238, v238 quad_perm:[2,3,0,1] row_mask:0xf bank_mask:0xf bound_ctrl:1
	v_fmac_f32_e32 v181, v241, v38
	v_add_f32_dpp v183, v183, v183 row_half_mirror row_mask:0xf bank_mask:0xf bound_ctrl:1
	v_fmac_f32_e32 v182, v241, v39
	s_nop 0
	v_add_f32_dpp v183, v183, v183 row_mirror row_mask:0xf bank_mask:0xf bound_ctrl:1
	v_fmac_f32_e32 v179, v183, v32
	v_fmac_f32_e32 v180, v183, v33
	v_fmac_f32_e32 v181, v183, v34
	v_fmac_f32_e32 v182, v183, v35
	s_mov_b64 exec, s[12:13]
	ds_write2st64_b32 v185, v184, v238 offset0:28 offset1:24
	s_mov_b64 exec, -1
	ds_read_b128 v[28:31], v145 offset:8960
	ds_read_b128 v[32:35], v145 offset:17152
	ds_read_b128 v[36:39], v145 offset:25344
	ds_read_b128 v[40:43], v145 offset:33536
	ds_read2st64_b32 v[240:241], v151 offset0:195 offset1:194
	s_waitcnt lgkmcnt(10)
	v_mul_f32_e32 v183, v179, v48
	v_mul_f32_e32 v184, v179, v60
	v_fmac_f32_e32 v183, v180, v49
	v_fmac_f32_e32 v184, v180, v61
	v_fmac_f32_e32 v183, v181, v50
	v_fmac_f32_e32 v184, v181, v62
	v_fmac_f32_e32 v183, v182, v51
	v_fmac_f32_e32 v184, v182, v63
	v_fmac_f32_e32 v179, v242, v56
	v_add_f32_dpp v183, v183, v183 quad_perm:[1,0,3,2] row_mask:0xf bank_mask:0xf bound_ctrl:1
	v_add_f32_dpp v184, v184, v184 quad_perm:[1,0,3,2] row_mask:0xf bank_mask:0xf bound_ctrl:1
	v_fmac_f32_e32 v180, v242, v57
	v_add_f32_dpp v183, v183, v183 quad_perm:[2,3,0,1] row_mask:0xf bank_mask:0xf bound_ctrl:1
	v_add_f32_dpp v184, v184, v184 quad_perm:[2,3,0,1] row_mask:0xf bank_mask:0xf bound_ctrl:1
	v_fmac_f32_e32 v181, v242, v58
	v_add_f32_dpp v183, v183, v183 row_half_mirror row_mask:0xf bank_mask:0xf bound_ctrl:1
	v_fmac_f32_e32 v182, v242, v59
	s_nop 0
	v_add_f32_dpp v183, v183, v183 row_mirror row_mask:0xf bank_mask:0xf bound_ctrl:1
	v_fmac_f32_e32 v179, v183, v52
	v_fmac_f32_e32 v180, v183, v53
	v_fmac_f32_e32 v181, v183, v54
	v_fmac_f32_e32 v182, v183, v55
	ds_read_b128 v[48:51], v145 offset:8704
	ds_read_b128 v[52:55], v145 offset:16896
	ds_read_b128 v[56:59], v145 offset:25088
	ds_read_b128 v[60:63], v145 offset:33280
	s_waitcnt lgkmcnt(10)
	v_mul_f32_e32 v183, v179, v8
	v_mul_f32_e32 v238, v179, v20
	v_fmac_f32_e32 v183, v180, v9
	v_fmac_f32_e32 v238, v180, v21
	v_fmac_f32_e32 v183, v181, v10
	v_fmac_f32_e32 v238, v181, v22
	v_fmac_f32_e32 v183, v182, v11
	v_fmac_f32_e32 v238, v182, v23
	v_fmac_f32_e32 v179, v243, v16
	v_add_f32_dpp v183, v183, v183 quad_perm:[1,0,3,2] row_mask:0xf bank_mask:0xf bound_ctrl:1
	v_add_f32_dpp v238, v238, v238 quad_perm:[1,0,3,2] row_mask:0xf bank_mask:0xf bound_ctrl:1
	v_fmac_f32_e32 v180, v243, v17
	v_add_f32_dpp v183, v183, v183 quad_perm:[2,3,0,1] row_mask:0xf bank_mask:0xf bound_ctrl:1
	v_add_f32_dpp v238, v238, v238 quad_perm:[2,3,0,1] row_mask:0xf bank_mask:0xf bound_ctrl:1
	v_fmac_f32_e32 v181, v243, v18
	v_add_f32_dpp v183, v183, v183 row_half_mirror row_mask:0xf bank_mask:0xf bound_ctrl:1
	v_fmac_f32_e32 v182, v243, v19
	s_nop 0
	v_add_f32_dpp v183, v183, v183 row_mirror row_mask:0xf bank_mask:0xf bound_ctrl:1
	v_fmac_f32_e32 v179, v183, v12
	v_fmac_f32_e32 v180, v183, v13
	v_fmac_f32_e32 v181, v183, v14
	v_fmac_f32_e32 v182, v183, v15
	s_mov_b64 exec, s[12:13]
	ds_write2st64_b32 v185, v184, v238 offset0:20 offset1:16
	s_mov_b64 exec, -1
	ds_read_b128 v[8:11], v145 offset:8448
	ds_read_b128 v[12:15], v145 offset:16640
	ds_read_b128 v[16:19], v145 offset:24832
	ds_read_b128 v[20:23], v145 offset:33024
	ds_read2st64_b32 v[242:243], v151 offset0:193 offset1:192
	s_waitcnt lgkmcnt(10)
	v_mul_f32_e32 v183, v179, v28
	v_mul_f32_e32 v184, v179, v40
	v_fmac_f32_e32 v183, v180, v29
	v_fmac_f32_e32 v184, v180, v41
	v_fmac_f32_e32 v183, v181, v30
	v_fmac_f32_e32 v184, v181, v42
	v_fmac_f32_e32 v183, v182, v31
	v_fmac_f32_e32 v184, v182, v43
	v_fmac_f32_e32 v179, v240, v36
	v_add_f32_dpp v183, v183, v183 quad_perm:[1,0,3,2] row_mask:0xf bank_mask:0xf bound_ctrl:1
	v_add_f32_dpp v184, v184, v184 quad_perm:[1,0,3,2] row_mask:0xf bank_mask:0xf bound_ctrl:1
	v_fmac_f32_e32 v180, v240, v37
	v_add_f32_dpp v183, v183, v183 quad_perm:[2,3,0,1] row_mask:0xf bank_mask:0xf bound_ctrl:1
	v_add_f32_dpp v184, v184, v184 quad_perm:[2,3,0,1] row_mask:0xf bank_mask:0xf bound_ctrl:1
	v_fmac_f32_e32 v181, v240, v38
	v_add_f32_dpp v183, v183, v183 row_half_mirror row_mask:0xf bank_mask:0xf bound_ctrl:1
	v_fmac_f32_e32 v182, v240, v39
	s_nop 0
	v_add_f32_dpp v183, v183, v183 row_mirror row_mask:0xf bank_mask:0xf bound_ctrl:1
	v_fmac_f32_e32 v179, v183, v32
	v_fmac_f32_e32 v180, v183, v33
	v_fmac_f32_e32 v181, v183, v34
	v_fmac_f32_e32 v182, v183, v35
	ds_read_b128 v[28:31], v145 offset:8192
	ds_read_b128 v[32:35], v145 offset:16384
	ds_read_b128 v[36:39], v145 offset:24576
	ds_read_b128 v[40:43], v145 offset:32768
	s_waitcnt lgkmcnt(10)
	v_mul_f32_e32 v183, v179, v48
	v_mul_f32_e32 v238, v179, v60
	v_fmac_f32_e32 v183, v180, v49
	v_fmac_f32_e32 v238, v180, v61
	v_fmac_f32_e32 v183, v181, v50
	v_fmac_f32_e32 v238, v181, v62
	v_fmac_f32_e32 v183, v182, v51
	v_fmac_f32_e32 v238, v182, v63
	v_fmac_f32_e32 v179, v241, v56
	v_add_f32_dpp v183, v183, v183 quad_perm:[1,0,3,2] row_mask:0xf bank_mask:0xf bound_ctrl:1
	v_add_f32_dpp v238, v238, v238 quad_perm:[1,0,3,2] row_mask:0xf bank_mask:0xf bound_ctrl:1
	v_fmac_f32_e32 v180, v241, v57
	v_add_f32_dpp v183, v183, v183 quad_perm:[2,3,0,1] row_mask:0xf bank_mask:0xf bound_ctrl:1
	v_add_f32_dpp v238, v238, v238 quad_perm:[2,3,0,1] row_mask:0xf bank_mask:0xf bound_ctrl:1
	v_fmac_f32_e32 v181, v241, v58
	v_add_f32_dpp v183, v183, v183 row_half_mirror row_mask:0xf bank_mask:0xf bound_ctrl:1
	v_fmac_f32_e32 v182, v241, v59
	s_nop 0
	v_add_f32_dpp v183, v183, v183 row_mirror row_mask:0xf bank_mask:0xf bound_ctrl:1
	v_fmac_f32_e32 v179, v183, v52
	v_fmac_f32_e32 v180, v183, v53
	v_fmac_f32_e32 v181, v183, v54
	v_fmac_f32_e32 v182, v183, v55
	s_mov_b64 exec, s[12:13]
	ds_write2st64_b32 v185, v184, v238 offset0:12 offset1:8
	s_mov_b64 exec, -1
	s_waitcnt lgkmcnt(5)
	v_mul_f32_e32 v183, v179, v8
	v_mul_f32_e32 v184, v179, v20
	v_fmac_f32_e32 v183, v180, v9
	v_fmac_f32_e32 v184, v180, v21
	v_fmac_f32_e32 v183, v181, v10
	v_fmac_f32_e32 v184, v181, v22
	v_fmac_f32_e32 v183, v182, v11
	v_fmac_f32_e32 v184, v182, v23
	v_fmac_f32_e32 v179, v242, v16
	v_add_f32_dpp v183, v183, v183 quad_perm:[1,0,3,2] row_mask:0xf bank_mask:0xf bound_ctrl:1
	v_add_f32_dpp v184, v184, v184 quad_perm:[1,0,3,2] row_mask:0xf bank_mask:0xf bound_ctrl:1
	v_fmac_f32_e32 v180, v242, v17
	v_add_f32_dpp v183, v183, v183 quad_perm:[2,3,0,1] row_mask:0xf bank_mask:0xf bound_ctrl:1
	v_add_f32_dpp v184, v184, v184 quad_perm:[2,3,0,1] row_mask:0xf bank_mask:0xf bound_ctrl:1
	v_fmac_f32_e32 v181, v242, v18
	v_add_f32_dpp v183, v183, v183 row_half_mirror row_mask:0xf bank_mask:0xf bound_ctrl:1
	v_fmac_f32_e32 v182, v242, v19
	s_nop 0
	v_add_f32_dpp v183, v183, v183 row_mirror row_mask:0xf bank_mask:0xf bound_ctrl:1
	v_fmac_f32_e32 v179, v183, v12
	v_fmac_f32_e32 v180, v183, v13
	v_fmac_f32_e32 v181, v183, v14
	v_fmac_f32_e32 v182, v183, v15
	s_waitcnt lgkmcnt(1)
	v_mul_f32_e32 v183, v179, v28
	v_mul_f32_e32 v238, v179, v40
	v_fmac_f32_e32 v183, v180, v29
	v_fmac_f32_e32 v238, v180, v41
	v_fmac_f32_e32 v183, v181, v30
	v_fmac_f32_e32 v238, v181, v42
	v_fmac_f32_e32 v183, v182, v31
	v_fmac_f32_e32 v238, v182, v43
	v_fmac_f32_e32 v179, v243, v36
	v_add_f32_dpp v183, v183, v183 quad_perm:[1,0,3,2] row_mask:0xf bank_mask:0xf bound_ctrl:1
	v_add_f32_dpp v238, v238, v238 quad_perm:[1,0,3,2] row_mask:0xf bank_mask:0xf bound_ctrl:1
	v_fmac_f32_e32 v180, v243, v37
	v_add_f32_dpp v183, v183, v183 quad_perm:[2,3,0,1] row_mask:0xf bank_mask:0xf bound_ctrl:1
	v_add_f32_dpp v238, v238, v238 quad_perm:[2,3,0,1] row_mask:0xf bank_mask:0xf bound_ctrl:1
	v_fmac_f32_e32 v181, v243, v38
	v_add_f32_dpp v183, v183, v183 row_half_mirror row_mask:0xf bank_mask:0xf bound_ctrl:1
	v_fmac_f32_e32 v182, v243, v39
	s_nop 0
	v_add_f32_dpp v183, v183, v183 row_mirror row_mask:0xf bank_mask:0xf bound_ctrl:1
	v_fmac_f32_e32 v179, v183, v32
	v_fmac_f32_e32 v180, v183, v33
	v_fmac_f32_e32 v181, v183, v34
	v_fmac_f32_e32 v182, v183, v35
	s_mov_b64 exec, s[12:13]
	ds_write2st64_b32 v185, v184, v238 offset0:4 offset1:0
	s_mov_b64 exec, -1
	ds_read_b128 v[4:7], v145 offset:57344
	s_waitcnt lgkmcnt(0)
	v_mul_f32_e32 v179, v179, v4
	v_mul_f32_e32 v180, v180, v5
	v_mul_f32_e32 v181, v181, v6
	v_mul_f32_e32 v182, v182, v7
	s_waitcnt lgkmcnt(0)
	s_barrier
	s_and_saveexec_b64 s[12:13], s[10:11]
	s_cbranch_execz .LBB0_265
	v_lshrrev_b32_e32 v244, 4, v134
	v_lshl_add_u32 v244, v244, 9, v153
	ds_read_b128 v[4:7], v244
	ds_read_b128 v[8:11], v244 offset:256
	ds_read_b128 v[200:203], v244 offset:512
	ds_read_b128 v[204:207], v244 offset:768
	s_waitcnt lgkmcnt(0)
	v_pk_add_f32 v[4:5], v[4:5], v[200:201]
	v_pk_add_f32 v[6:7], v[6:7], v[202:203]
	v_pk_add_f32 v[8:9], v[8:9], v[204:205]
	v_pk_add_f32 v[10:11], v[10:11], v[206:207]
	v_pk_add_f32 v[10:11], v[6:7], v[10:11]
	v_pk_add_f32 v[8:9], v[4:5], v[8:9]
	ds_read_b128 v[4:7], v150
	s_waitcnt lgkmcnt(0)
	v_pk_add_f32 v[6:7], v[10:11], v[6:7]
	v_pk_add_f32 v[4:5], v[8:9], v[4:5]
	s_nop 0
	v_cvt_pk_bf16_f32 v4, v4, v5
	v_cvt_pk_bf16_f32 v5, v6, v7
	v_lshlrev_b64 v[6:7], 11, v[124:125]
	v_lshl_add_u64 v[6:7], v[106:107], 0, v[6:7]
	global_store_dwordx2 v[6:7], v[4:5], off
	s_branch .LBB0_265

.LBB0_380:
	s_or_b64 exec, exec, s[10:11]
	s_waitcnt lgkmcnt(0)
	s_barrier
	v_mbcnt_lo_u32_b32 v177, -1, 0
	v_mbcnt_hi_u32_b32 v177, -1, v177
	v_lshlrev_b32_e32 v177, 2, v177
	v_add_u32_e32 v177, 0xe000, v177
	v_cndmask_b32_e64 v176, v177, v149, s[6:7]
	v_mbcnt_lo_u32_b32 v177, -1, 0
	v_mbcnt_hi_u32_b32 v177, -1, v177
	v_and_b32_e32 v177, 12, v177
	v_lshlrev_b32_e32 v177, 6, v177
	v_add_u32_e32 v176, 0x1c000, v148
	v_add_u32_e32 v176, v177, v176
	s_mov_b32 s10, 0x11111111
	s_mov_b32 s11, 0x11111111
	ds_read_b128 v[8:11], v142 offset:8192
	ds_read_b128 v[12:15], v142 offset:16384
	ds_read_b128 v[16:19], v142 offset:24576
	ds_read_b128 v[20:23], v142 offset:32768
	ds_read2st64_b32 v[240:241], v148 offset0:192 offset1:193
	ds_read_b128 v[28:31], v142 offset:8448
	ds_read_b128 v[32:35], v142 offset:16640
	ds_read_b128 v[36:39], v142 offset:24832
	ds_read_b128 v[40:43], v142 offset:33024
	ds_read_b128 v[48:51], v142 offset:8704
	ds_read_b128 v[52:55], v142 offset:16896
	ds_read_b128 v[56:59], v142 offset:25088
	ds_read_b128 v[60:63], v142 offset:33280
	ds_read2st64_b32 v[242:243], v148 offset0:194 offset1:195
	s_waitcnt lgkmcnt(9)
	v_mul_f32_e32 v174, v170, v8
	v_mul_f32_e32 v175, v170, v20
	v_fmac_f32_e32 v174, v171, v9
	v_fmac_f32_e32 v175, v171, v21
	v_fmac_f32_e32 v174, v172, v10
	v_fmac_f32_e32 v175, v172, v22
	v_fmac_f32_e32 v174, v173, v11
	v_fmac_f32_e32 v175, v173, v23
	v_fmac_f32_e32 v170, v240, v16
	v_add_f32_dpp v174, v174, v174 quad_perm:[1,0,3,2] row_mask:0xf bank_mask:0xf bound_ctrl:1
	v_add_f32_dpp v175, v175, v175 quad_perm:[1,0,3,2] row_mask:0xf bank_mask:0xf bound_ctrl:1
	v_fmac_f32_e32 v171, v240, v17
	v_add_f32_dpp v174, v174, v174 quad_perm:[2,3,0,1] row_mask:0xf bank_mask:0xf bound_ctrl:1
	v_add_f32_dpp v175, v175, v175 quad_perm:[2,3,0,1] row_mask:0xf bank_mask:0xf bound_ctrl:1
	v_fmac_f32_e32 v172, v240, v18
	v_add_f32_dpp v174, v174, v174 row_half_mirror row_mask:0xf bank_mask:0xf bound_ctrl:1
	v_fmac_f32_e32 v173, v240, v19
	s_nop 0
	v_add_f32_dpp v174, v174, v174 row_mirror row_mask:0xf bank_mask:0xf bound_ctrl:1
	v_fmac_f32_e32 v170, v174, v12
	v_fmac_f32_e32 v171, v174, v13
	v_fmac_f32_e32 v172, v174, v14
	v_fmac_f32_e32 v173, v174, v15
	ds_read_b128 v[8:11], v142 offset:8960
	ds_read_b128 v[12:15], v142 offset:17152
	ds_read_b128 v[16:19], v142 offset:25344
	ds_read_b128 v[20:23], v142 offset:33536
	s_waitcnt lgkmcnt(9)
	v_mul_f32_e32 v174, v170, v28
	v_mul_f32_e32 v238, v170, v40
	v_fmac_f32_e32 v174, v171, v29
	v_fmac_f32_e32 v238, v171, v41
	v_fmac_f32_e32 v174, v172, v30
	v_fmac_f32_e32 v238, v172, v42
	v_fmac_f32_e32 v174, v173, v31
	v_fmac_f32_e32 v238, v173, v43
	v_fmac_f32_e32 v170, v241, v36
	v_add_f32_dpp v174, v174, v174 quad_perm:[1,0,3,2] row_mask:0xf bank_mask:0xf bound_ctrl:1
	v_add_f32_dpp v238, v238, v238 quad_perm:[1,0,3,2] row_mask:0xf bank_mask:0xf bound_ctrl:1
	v_fmac_f32_e32 v171, v241, v37
	v_add_f32_dpp v174, v174, v174 quad_perm:[2,3,0,1] row_mask:0xf bank_mask:0xf bound_ctrl:1
	v_add_f32_dpp v238, v238, v238 quad_perm:[2,3,0,1] row_mask:0xf bank_mask:0xf bound_ctrl:1
	v_fmac_f32_e32 v172, v241, v38
	v_add_f32_dpp v174, v174, v174 row_half_mirror row_mask:0xf bank_mask:0xf bound_ctrl:1
	v_fmac_f32_e32 v173, v241, v39
	s_nop 0
	v_add_f32_dpp v174, v174, v174 row_mirror row_mask:0xf bank_mask:0xf bound_ctrl:1
	v_fmac_f32_e32 v170, v174, v32
	v_fmac_f32_e32 v171, v174, v33
	v_fmac_f32_e32 v172, v174, v34
	v_fmac_f32_e32 v173, v174, v35
	s_mov_b64 exec, s[10:11]
	ds_write2st64_b32 v176, v175, v238 offset0:0 offset1:4
	s_mov_b64 exec, -1
	ds_read_b128 v[28:31], v142 offset:9216
	ds_read_b128 v[32:35], v142 offset:17408
	ds_read_b128 v[36:39], v142 offset:25600
	ds_read_b128 v[40:43], v142 offset:33792
	ds_read2st64_b32 v[240:241], v148 offset0:196 offset1:197
	s_waitcnt lgkmcnt(10)
	v_mul_f32_e32 v174, v170, v48
	v_mul_f32_e32 v175, v170, v60
	v_fmac_f32_e32 v174, v171, v49
	v_fmac_f32_e32 v175, v171, v61
	v_fmac_f32_e32 v174, v172, v50
	v_fmac_f32_e32 v175, v172, v62
	v_fmac_f32_e32 v174, v173, v51
	v_fmac_f32_e32 v175, v173, v63
	v_fmac_f32_e32 v170, v242, v56
	v_add_f32_dpp v174, v174, v174 quad_perm:[1,0,3,2] row_mask:0xf bank_mask:0xf bound_ctrl:1
	v_add_f32_dpp v175, v175, v175 quad_perm:[1,0,3,2] row_mask:0xf bank_mask:0xf bound_ctrl:1
	v_fmac_f32_e32 v171, v242, v57
	v_add_f32_dpp v174, v174, v174 quad_perm:[2,3,0,1] row_mask:0xf bank_mask:0xf bound_ctrl:1
	v_add_f32_dpp v175, v175, v175 quad_perm:[2,3,0,1] row_mask:0xf bank_mask:0xf bound_ctrl:1
	v_fmac_f32_e32 v172, v242, v58
	v_add_f32_dpp v174, v174, v174 row_half_mirror row_mask:0xf bank_mask:0xf bound_ctrl:1
	v_fmac_f32_e32 v173, v242, v59
	s_nop 0
	v_add_f32_dpp v174, v174, v174 row_mirror row_mask:0xf bank_mask:0xf bound_ctrl:1
	v_fmac_f32_e32 v170, v174, v52
	v_fmac_f32_e32 v171, v174, v53
	v_fmac_f32_e32 v172, v174, v54
	v_fmac_f32_e32 v173, v174, v55
	ds_read_b128 v[48:51], v142 offset:9472
	ds_read_b128 v[52:55], v142 offset:17664
	ds_read_b128 v[56:59], v142 offset:25856
	ds_read_b128 v[60:63], v142 offset:34048
	s_waitcnt lgkmcnt(10)
	v_mul_f32_e32 v174, v170, v8
	v_mul_f32_e32 v238, v170, v20
	v_fmac_f32_e32 v174, v171, v9
	v_fmac_f32_e32 v238, v171, v21
	v_fmac_f32_e32 v174, v172, v10
	v_fmac_f32_e32 v238, v172, v22
	v_fmac_f32_e32 v174, v173, v11
	v_fmac_f32_e32 v238, v173, v23
	v_fmac_f32_e32 v170, v243, v16
	v_add_f32_dpp v174, v174, v174 quad_perm:[1,0,3,2] row_mask:0xf bank_mask:0xf bound_ctrl:1
	v_add_f32_dpp v238, v238, v238 quad_perm:[1,0,3,2] row_mask:0xf bank_mask:0xf bound_ctrl:1
	v_fmac_f32_e32 v171, v243, v17
	v_add_f32_dpp v174, v174, v174 quad_perm:[2,3,0,1] row_mask:0xf bank_mask:0xf bound_ctrl:1
	v_add_f32_dpp v238, v238, v238 quad_perm:[2,3,0,1] row_mask:0xf bank_mask:0xf bound_ctrl:1
	v_fmac_f32_e32 v172, v243, v18
	v_add_f32_dpp v174, v174, v174 row_half_mirror row_mask:0xf bank_mask:0xf bound_ctrl:1
	v_fmac_f32_e32 v173, v243, v19
	s_nop 0
	v_add_f32_dpp v174, v174, v174 row_mirror row_mask:0xf bank_mask:0xf bound_ctrl:1
	v_fmac_f32_e32 v170, v174, v12
	v_fmac_f32_e32 v171, v174, v13
	v_fmac_f32_e32 v172, v174, v14
	v_fmac_f32_e32 v173, v174, v15
	s_mov_b64 exec, s[10:11]
	ds_write2st64_b32 v176, v175, v238 offset0:8 offset1:12
	s_mov_b64 exec, -1
	ds_read_b128 v[8:11], v142 offset:9728
	ds_read_b128 v[12:15], v142 offset:17920
	ds_read_b128 v[16:19], v142 offset:26112
	ds_read_b128 v[20:23], v142 offset:34304
	ds_read2st64_b32 v[242:243], v148 offset0:198 offset1:199
	s_waitcnt lgkmcnt(10)
	v_mul_f32_e32 v174, v170, v28
	v_mul_f32_e32 v175, v170, v40
	v_fmac_f32_e32 v174, v171, v29
	v_fmac_f32_e32 v175, v171, v41
	v_fmac_f32_e32 v174, v172, v30
	v_fmac_f32_e32 v175, v172, v42
	v_fmac_f32_e32 v174, v173, v31
	v_fmac_f32_e32 v175, v173, v43
	v_fmac_f32_e32 v170, v240, v36
	v_add_f32_dpp v174, v174, v174 quad_perm:[1,0,3,2] row_mask:0xf bank_mask:0xf bound_ctrl:1
	v_add_f32_dpp v175, v175, v175 quad_perm:[1,0,3,2] row_mask:0xf bank_mask:0xf bound_ctrl:1
	v_fmac_f32_e32 v171, v240, v37
	v_add_f32_dpp v174, v174, v174 quad_perm:[2,3,0,1] row_mask:0xf bank_mask:0xf bound_ctrl:1
	v_add_f32_dpp v175, v175, v175 quad_perm:[2,3,0,1] row_mask:0xf bank_mask:0xf bound_ctrl:1
	v_fmac_f32_e32 v172, v240, v38
	v_add_f32_dpp v174, v174, v174 row_half_mirror row_mask:0xf bank_mask:0xf bound_ctrl:1
	v_fmac_f32_e32 v173, v240, v39
	s_nop 0
	v_add_f32_dpp v174, v174, v174 row_mirror row_mask:0xf bank_mask:0xf bound_ctrl:1
	v_fmac_f32_e32 v170, v174, v32
	v_fmac_f32_e32 v171, v174, v33
	v_fmac_f32_e32 v172, v174, v34
	v_fmac_f32_e32 v173, v174, v35
	ds_read_b128 v[28:31], v142 offset:9984
	ds_read_b128 v[32:35], v142 offset:18176
	ds_read_b128 v[36:39], v142 offset:26368
	ds_read_b128 v[40:43], v142 offset:34560
	s_waitcnt lgkmcnt(10)
	v_mul_f32_e32 v174, v170, v48
	v_mul_f32_e32 v238, v170, v60
	v_fmac_f32_e32 v174, v171, v49
	v_fmac_f32_e32 v238, v171, v61
	v_fmac_f32_e32 v174, v172, v50
	v_fmac_f32_e32 v238, v172, v62
	v_fmac_f32_e32 v174, v173, v51
	v_fmac_f32_e32 v238, v173, v63
	v_fmac_f32_e32 v170, v241, v56
	v_add_f32_dpp v174, v174, v174 quad_perm:[1,0,3,2] row_mask:0xf bank_mask:0xf bound_ctrl:1
	v_add_f32_dpp v238, v238, v238 quad_perm:[1,0,3,2] row_mask:0xf bank_mask:0xf bound_ctrl:1
	v_fmac_f32_e32 v171, v241, v57
	v_add_f32_dpp v174, v174, v174 quad_perm:[2,3,0,1] row_mask:0xf bank_mask:0xf bound_ctrl:1
	v_add_f32_dpp v238, v238, v238 quad_perm:[2,3,0,1] row_mask:0xf bank_mask:0xf bound_ctrl:1
	v_fmac_f32_e32 v172, v241, v58
	v_add_f32_dpp v174, v174, v174 row_half_mirror row_mask:0xf bank_mask:0xf bound_ctrl:1
	v_fmac_f32_e32 v173, v241, v59
	s_nop 0
	v_add_f32_dpp v174, v174, v174 row_mirror row_mask:0xf bank_mask:0xf bound_ctrl:1
	v_fmac_f32_e32 v170, v174, v52
	v_fmac_f32_e32 v171, v174, v53
	v_fmac_f32_e32 v172, v174, v54
	v_fmac_f32_e32 v173, v174, v55
	s_mov_b64 exec, s[10:11]
	ds_write2st64_b32 v176, v175, v238 offset0:16 offset1:20
	s_mov_b64 exec, -1
	ds_read_b128 v[48:51], v142 offset:10240
	ds_read_b128 v[52:55], v142 offset:18432
	ds_read_b128 v[56:59], v142 offset:26624
	ds_read_b128 v[60:63], v142 offset:34816
	ds_read2st64_b32 v[240:241], v148 offset0:200 offset1:201
	s_waitcnt lgkmcnt(10)
	v_mul_f32_e32 v174, v170, v8
	v_mul_f32_e32 v175, v170, v20
	v_fmac_f32_e32 v174, v171, v9
	v_fmac_f32_e32 v175, v171, v21
	v_fmac_f32_e32 v174, v172, v10
	v_fmac_f32_e32 v175, v172, v22
	v_fmac_f32_e32 v174, v173, v11
	v_fmac_f32_e32 v175, v173, v23
	v_fmac_f32_e32 v170, v242, v16
	v_add_f32_dpp v174, v174, v174 quad_perm:[1,0,3,2] row_mask:0xf bank_mask:0xf bound_ctrl:1
	v_add_f32_dpp v175, v175, v175 quad_perm:[1,0,3,2] row_mask:0xf bank_mask:0xf bound_ctrl:1
	v_fmac_f32_e32 v171, v242, v17
	v_add_f32_dpp v174, v174, v174 quad_perm:[2,3,0,1] row_mask:0xf bank_mask:0xf bound_ctrl:1
	v_add_f32_dpp v175, v175, v175 quad_perm:[2,3,0,1] row_mask:0xf bank_mask:0xf bound_ctrl:1
	v_fmac_f32_e32 v172, v242, v18
	v_add_f32_dpp v174, v174, v174 row_half_mirror row_mask:0xf bank_mask:0xf bound_ctrl:1
	v_fmac_f32_e32 v173, v242, v19
	s_nop 0
	v_add_f32_dpp v174, v174, v174 row_mirror row_mask:0xf bank_mask:0xf bound_ctrl:1
	v_fmac_f32_e32 v170, v174, v12
	v_fmac_f32_e32 v171, v174, v13
	v_fmac_f32_e32 v172, v174, v14
	v_fmac_f32_e32 v173, v174, v15
	ds_read_b128 v[8:11], v142 offset:10496
	ds_read_b128 v[12:15], v142 offset:18688
	ds_read_b128 v[16:19], v142 offset:26880
	ds_read_b128 v[20:23], v142 offset:35072
	s_waitcnt lgkmcnt(10)
	v_mul_f32_e32 v174, v170, v28
	v_mul_f32_e32 v238, v170, v40
	v_fmac_f32_e32 v174, v171, v29
	v_fmac_f32_e32 v238, v171, v41
	v_fmac_f32_e32 v174, v172, v30
	v_fmac_f32_e32 v238, v172, v42
	v_fmac_f32_e32 v174, v173, v31
	v_fmac_f32_e32 v238, v173, v43
	v_fmac_f32_e32 v170, v243, v36
	v_add_f32_dpp v174, v174, v174 quad_perm:[1,0,3,2] row_mask:0xf bank_mask:0xf bound_ctrl:1
	v_add_f32_dpp v238, v238, v238 quad_perm:[1,0,3,2] row_mask:0xf bank_mask:0xf bound_ctrl:1
	v_fmac_f32_e32 v171, v243, v37
	v_add_f32_dpp v174, v174, v174 quad_perm:[2,3,0,1] row_mask:0xf bank_mask:0xf bound_ctrl:1
	v_add_f32_dpp v238, v238, v238 quad_perm:[2,3,0,1] row_mask:0xf bank_mask:0xf bound_ctrl:1
	v_fmac_f32_e32 v172, v243, v38
	v_add_f32_dpp v174, v174, v174 row_half_mirror row_mask:0xf bank_mask:0xf bound_ctrl:1
	v_fmac_f32_e32 v173, v243, v39
	s_nop 0
	v_add_f32_dpp v174, v174, v174 row_mirror row_mask:0xf bank_mask:0xf bound_ctrl:1
	v_fmac_f32_e32 v170, v174, v32
	v_fmac_f32_e32 v171, v174, v33
	v_fmac_f32_e32 v172, v174, v34
	v_fmac_f32_e32 v173, v174, v35
	s_mov_b64 exec, s[10:11]
	ds_write2st64_b32 v176, v175, v238 offset0:24 offset1:28
	s_mov_b64 exec, -1
	ds_read_b128 v[28:31], v142 offset:10752
	ds_read_b128 v[32:35], v142 offset:18944
	ds_read_b128 v[36:39], v142 offset:27136
	ds_read_b128 v[40:43], v142 offset:35328
	ds_read2st64_b32 v[242:243], v148 offset0:202 offset1:203
	s_waitcnt lgkmcnt(10)
	v_mul_f32_e32 v174, v170, v48
	v_mul_f32_e32 v175, v170, v60
	v_fmac_f32_e32 v174, v171, v49
	v_fmac_f32_e32 v175, v171, v61
	v_fmac_f32_e32 v174, v172, v50
	v_fmac_f32_e32 v175, v172, v62
	v_fmac_f32_e32 v174, v173, v51
	v_fmac_f32_e32 v175, v173, v63
	v_fmac_f32_e32 v170, v240, v56
	v_add_f32_dpp v174, v174, v174 quad_perm:[1,0,3,2] row_mask:0xf bank_mask:0xf bound_ctrl:1
	v_add_f32_dpp v175, v175, v175 quad_perm:[1,0,3,2] row_mask:0xf bank_mask:0xf bound_ctrl:1
	v_fmac_f32_e32 v171, v240, v57
	v_add_f32_dpp v174, v174, v174 quad_perm:[2,3,0,1] row_mask:0xf bank_mask:0xf bound_ctrl:1
	v_add_f32_dpp v175, v175, v175 quad_perm:[2,3,0,1] row_mask:0xf bank_mask:0xf bound_ctrl:1
	v_fmac_f32_e32 v172, v240, v58
	v_add_f32_dpp v174, v174, v174 row_half_mirror row_mask:0xf bank_mask:0xf bound_ctrl:1
	v_fmac_f32_e32 v173, v240, v59
	s_nop 0
	v_add_f32_dpp v174, v174, v174 row_mirror row_mask:0xf bank_mask:0xf bound_ctrl:1
	v_fmac_f32_e32 v170, v174, v52
	v_fmac_f32_e32 v171, v174, v53
	v_fmac_f32_e32 v172, v174, v54
	v_fmac_f32_e32 v173, v174, v55
	ds_read_b128 v[48:51], v142 offset:11008
	ds_read_b128 v[52:55], v142 offset:19200
	ds_read_b128 v[56:59], v142 offset:27392
	ds_read_b128 v[60:63], v142 offset:35584
	s_waitcnt lgkmcnt(10)
	v_mul_f32_e32 v174, v170, v8
	v_mul_f32_e32 v238, v170, v20
	v_fmac_f32_e32 v174, v171, v9
	v_fmac_f32_e32 v238, v171, v21
	v_fmac_f32_e32 v174, v172, v10
	v_fmac_f32_e32 v238, v172, v22
	v_fmac_f32_e32 v174, v173, v11
	v_fmac_f32_e32 v238, v173, v23
	v_fmac_f32_e32 v170, v241, v16
	v_add_f32_dpp v174, v174, v174 quad_perm:[1,0,3,2] row_mask:0xf bank_mask:0xf bound_ctrl:1
	v_add_f32_dpp v238, v238, v238 quad_perm:[1,0,3,2] row_mask:0xf bank_mask:0xf bound_ctrl:1
	v_fmac_f32_e32 v171, v241, v17
	v_add_f32_dpp v174, v174, v174 quad_perm:[2,3,0,1] row_mask:0xf bank_mask:0xf bound_ctrl:1
	v_add_f32_dpp v238, v238, v238 quad_perm:[2,3,0,1] row_mask:0xf bank_mask:0xf bound_ctrl:1
	v_fmac_f32_e32 v172, v241, v18
	v_add_f32_dpp v174, v174, v174 row_half_mirror row_mask:0xf bank_mask:0xf bound_ctrl:1
	v_fmac_f32_e32 v173, v241, v19
	s_nop 0
	v_add_f32_dpp v174, v174, v174 row_mirror row_mask:0xf bank_mask:0xf bound_ctrl:1
	v_fmac_f32_e32 v170, v174, v12
	v_fmac_f32_e32 v171, v174, v13
	v_fmac_f32_e32 v172, v174, v14
	v_fmac_f32_e32 v173, v174, v15
	s_mov_b64 exec, s[10:11]
	ds_write2st64_b32 v176, v175, v238 offset0:32 offset1:36
	s_mov_b64 exec, -1
	ds_read_b128 v[8:11], v142 offset:11264
	ds_read_b128 v[12:15], v142 offset:19456
	ds_read_b128 v[16:19], v142 offset:27648
	ds_read_b128 v[20:23], v142 offset:35840
	ds_read2st64_b32 v[240:241], v148 offset0:204 offset1:205
	s_waitcnt lgkmcnt(10)
	v_mul_f32_e32 v174, v170, v28
	v_mul_f32_e32 v175, v170, v40
	v_fmac_f32_e32 v174, v171, v29
	v_fmac_f32_e32 v175, v171, v41
	v_fmac_f32_e32 v174, v172, v30
	v_fmac_f32_e32 v175, v172, v42
	v_fmac_f32_e32 v174, v173, v31
	v_fmac_f32_e32 v175, v173, v43
	v_fmac_f32_e32 v170, v242, v36
	v_add_f32_dpp v174, v174, v174 quad_perm:[1,0,3,2] row_mask:0xf bank_mask:0xf bound_ctrl:1
	v_add_f32_dpp v175, v175, v175 quad_perm:[1,0,3,2] row_mask:0xf bank_mask:0xf bound_ctrl:1
	v_fmac_f32_e32 v171, v242, v37
	v_add_f32_dpp v174, v174, v174 quad_perm:[2,3,0,1] row_mask:0xf bank_mask:0xf bound_ctrl:1
	v_add_f32_dpp v175, v175, v175 quad_perm:[2,3,0,1] row_mask:0xf bank_mask:0xf bound_ctrl:1
	v_fmac_f32_e32 v172, v242, v38
	v_add_f32_dpp v174, v174, v174 row_half_mirror row_mask:0xf bank_mask:0xf bound_ctrl:1
	v_fmac_f32_e32 v173, v242, v39
	s_nop 0
	v_add_f32_dpp v174, v174, v174 row_mirror row_mask:0xf bank_mask:0xf bound_ctrl:1
	v_fmac_f32_e32 v170, v174, v32
	v_fmac_f32_e32 v171, v174, v33
	v_fmac_f32_e32 v172, v174, v34
	v_fmac_f32_e32 v173, v174, v35
	ds_read_b128 v[28:31], v142 offset:11520
	ds_read_b128 v[32:35], v142 offset:19712
	ds_read_b128 v[36:39], v142 offset:27904
	ds_read_b128 v[40:43], v142 offset:36096
	s_waitcnt lgkmcnt(10)
	v_mul_f32_e32 v174, v170, v48
	v_mul_f32_e32 v238, v170, v60
	v_fmac_f32_e32 v174, v171, v49
	v_fmac_f32_e32 v238, v171, v61
	v_fmac_f32_e32 v174, v172, v50
	v_fmac_f32_e32 v238, v172, v62
	v_fmac_f32_e32 v174, v173, v51
	v_fmac_f32_e32 v238, v173, v63
	v_fmac_f32_e32 v170, v243, v56
	v_add_f32_dpp v174, v174, v174 quad_perm:[1,0,3,2] row_mask:0xf bank_mask:0xf bound_ctrl:1
	v_add_f32_dpp v238, v238, v238 quad_perm:[1,0,3,2] row_mask:0xf bank_mask:0xf bound_ctrl:1
	v_fmac_f32_e32 v171, v243, v57
	v_add_f32_dpp v174, v174, v174 quad_perm:[2,3,0,1] row_mask:0xf bank_mask:0xf bound_ctrl:1
	v_add_f32_dpp v238, v238, v238 quad_perm:[2,3,0,1] row_mask:0xf bank_mask:0xf bound_ctrl:1
	v_fmac_f32_e32 v172, v243, v58
	v_add_f32_dpp v174, v174, v174 row_half_mirror row_mask:0xf bank_mask:0xf bound_ctrl:1
	v_fmac_f32_e32 v173, v243, v59
	s_nop 0
	v_add_f32_dpp v174, v174, v174 row_mirror row_mask:0xf bank_mask:0xf bound_ctrl:1
	v_fmac_f32_e32 v170, v174, v52
	v_fmac_f32_e32 v171, v174, v53
	v_fmac_f32_e32 v172, v174, v54
	v_fmac_f32_e32 v173, v174, v55
	s_mov_b64 exec, s[10:11]
	ds_write2st64_b32 v176, v175, v238 offset0:40 offset1:44
	s_mov_b64 exec, -1
	ds_read_b128 v[48:51], v142 offset:11776
	ds_read_b128 v[52:55], v142 offset:19968
	ds_read_b128 v[56:59], v142 offset:28160
	ds_read_b128 v[60:63], v142 offset:36352
	ds_read2st64_b32 v[242:243], v148 offset0:206 offset1:207
	s_waitcnt lgkmcnt(10)
	v_mul_f32_e32 v174, v170, v8
	v_mul_f32_e32 v175, v170, v20
	v_fmac_f32_e32 v174, v171, v9
	v_fmac_f32_e32 v175, v171, v21
	v_fmac_f32_e32 v174, v172, v10
	v_fmac_f32_e32 v175, v172, v22
	v_fmac_f32_e32 v174, v173, v11
	v_fmac_f32_e32 v175, v173, v23
	v_fmac_f32_e32 v170, v240, v16
	v_add_f32_dpp v174, v174, v174 quad_perm:[1,0,3,2] row_mask:0xf bank_mask:0xf bound_ctrl:1
	v_add_f32_dpp v175, v175, v175 quad_perm:[1,0,3,2] row_mask:0xf bank_mask:0xf bound_ctrl:1
	v_fmac_f32_e32 v171, v240, v17
	v_add_f32_dpp v174, v174, v174 quad_perm:[2,3,0,1] row_mask:0xf bank_mask:0xf bound_ctrl:1
	v_add_f32_dpp v175, v175, v175 quad_perm:[2,3,0,1] row_mask:0xf bank_mask:0xf bound_ctrl:1
	v_fmac_f32_e32 v172, v240, v18
	v_add_f32_dpp v174, v174, v174 row_half_mirror row_mask:0xf bank_mask:0xf bound_ctrl:1
	v_fmac_f32_e32 v173, v240, v19
	s_nop 0
	v_add_f32_dpp v174, v174, v174 row_mirror row_mask:0xf bank_mask:0xf bound_ctrl:1
	v_fmac_f32_e32 v170, v174, v12
	v_fmac_f32_e32 v171, v174, v13
	v_fmac_f32_e32 v172, v174, v14
	v_fmac_f32_e32 v173, v174, v15
	ds_read_b128 v[8:11], v142 offset:12032
	ds_read_b128 v[12:15], v142 offset:20224
	ds_read_b128 v[16:19], v142 offset:28416
	ds_read_b128 v[20:23], v142 offset:36608
	s_waitcnt lgkmcnt(10)
	v_mul_f32_e32 v174, v170, v28
	v_mul_f32_e32 v238, v170, v40
	v_fmac_f32_e32 v174, v171, v29
	v_fmac_f32_e32 v238, v171, v41
	v_fmac_f32_e32 v174, v172, v30
	v_fmac_f32_e32 v238, v172, v42
	v_fmac_f32_e32 v174, v173, v31
	v_fmac_f32_e32 v238, v173, v43
	v_fmac_f32_e32 v170, v241, v36
	v_add_f32_dpp v174, v174, v174 quad_perm:[1,0,3,2] row_mask:0xf bank_mask:0xf bound_ctrl:1
	v_add_f32_dpp v238, v238, v238 quad_perm:[1,0,3,2] row_mask:0xf bank_mask:0xf bound_ctrl:1
	v_fmac_f32_e32 v171, v241, v37
	v_add_f32_dpp v174, v174, v174 quad_perm:[2,3,0,1] row_mask:0xf bank_mask:0xf bound_ctrl:1
	v_add_f32_dpp v238, v238, v238 quad_perm:[2,3,0,1] row_mask:0xf bank_mask:0xf bound_ctrl:1
	v_fmac_f32_e32 v172, v241, v38
	v_add_f32_dpp v174, v174, v174 row_half_mirror row_mask:0xf bank_mask:0xf bound_ctrl:1
	v_fmac_f32_e32 v173, v241, v39
	s_nop 0
	v_add_f32_dpp v174, v174, v174 row_mirror row_mask:0xf bank_mask:0xf bound_ctrl:1
	v_fmac_f32_e32 v170, v174, v32
	v_fmac_f32_e32 v171, v174, v33
	v_fmac_f32_e32 v172, v174, v34
	v_fmac_f32_e32 v173, v174, v35
	s_mov_b64 exec, s[10:11]
	ds_write2st64_b32 v176, v175, v238 offset0:48 offset1:52
	s_mov_b64 exec, -1
	ds_read_b128 v[28:31], v142 offset:12288
	ds_read_b128 v[32:35], v142 offset:20480
	ds_read_b128 v[36:39], v142 offset:28672
	ds_read_b128 v[40:43], v142 offset:36864
	ds_read2st64_b32 v[240:241], v148 offset0:208 offset1:209
	s_waitcnt lgkmcnt(10)
	v_mul_f32_e32 v174, v170, v48
	v_mul_f32_e32 v175, v170, v60
	v_fmac_f32_e32 v174, v171, v49
	v_fmac_f32_e32 v175, v171, v61
	v_fmac_f32_e32 v174, v172, v50
	v_fmac_f32_e32 v175, v172, v62
	v_fmac_f32_e32 v174, v173, v51
	v_fmac_f32_e32 v175, v173, v63
	v_fmac_f32_e32 v170, v242, v56
	v_add_f32_dpp v174, v174, v174 quad_perm:[1,0,3,2] row_mask:0xf bank_mask:0xf bound_ctrl:1
	v_add_f32_dpp v175, v175, v175 quad_perm:[1,0,3,2] row_mask:0xf bank_mask:0xf bound_ctrl:1
	v_fmac_f32_e32 v171, v242, v57
	v_add_f32_dpp v174, v174, v174 quad_perm:[2,3,0,1] row_mask:0xf bank_mask:0xf bound_ctrl:1
	v_add_f32_dpp v175, v175, v175 quad_perm:[2,3,0,1] row_mask:0xf bank_mask:0xf bound_ctrl:1
	v_fmac_f32_e32 v172, v242, v58
	v_add_f32_dpp v174, v174, v174 row_half_mirror row_mask:0xf bank_mask:0xf bound_ctrl:1
	v_fmac_f32_e32 v173, v242, v59
	s_nop 0
	v_add_f32_dpp v174, v174, v174 row_mirror row_mask:0xf bank_mask:0xf bound_ctrl:1
	v_fmac_f32_e32 v170, v174, v52
	v_fmac_f32_e32 v171, v174, v53
	v_fmac_f32_e32 v172, v174, v54
	v_fmac_f32_e32 v173, v174, v55
	ds_read_b128 v[48:51], v142 offset:12544
	ds_read_b128 v[52:55], v142 offset:20736
	ds_read_b128 v[56:59], v142 offset:28928
	ds_read_b128 v[60:63], v142 offset:37120
	s_waitcnt lgkmcnt(10)
	v_mul_f32_e32 v174, v170, v8
	v_mul_f32_e32 v238, v170, v20
	v_fmac_f32_e32 v174, v171, v9
	v_fmac_f32_e32 v238, v171, v21
	v_fmac_f32_e32 v174, v172, v10
	v_fmac_f32_e32 v238, v172, v22
	v_fmac_f32_e32 v174, v173, v11
	v_fmac_f32_e32 v238, v173, v23
	v_fmac_f32_e32 v170, v243, v16
	v_add_f32_dpp v174, v174, v174 quad_perm:[1,0,3,2] row_mask:0xf bank_mask:0xf bound_ctrl:1
	v_add_f32_dpp v238, v238, v238 quad_perm:[1,0,3,2] row_mask:0xf bank_mask:0xf bound_ctrl:1
	v_fmac_f32_e32 v171, v243, v17
	v_add_f32_dpp v174, v174, v174 quad_perm:[2,3,0,1] row_mask:0xf bank_mask:0xf bound_ctrl:1
	v_add_f32_dpp v238, v238, v238 quad_perm:[2,3,0,1] row_mask:0xf bank_mask:0xf bound_ctrl:1
	v_fmac_f32_e32 v172, v243, v18
	v_add_f32_dpp v174, v174, v174 row_half_mirror row_mask:0xf bank_mask:0xf bound_ctrl:1
	v_fmac_f32_e32 v173, v243, v19
	s_nop 0
	v_add_f32_dpp v174, v174, v174 row_mirror row_mask:0xf bank_mask:0xf bound_ctrl:1
	v_fmac_f32_e32 v170, v174, v12
	v_fmac_f32_e32 v171, v174, v13
	v_fmac_f32_e32 v172, v174, v14
	v_fmac_f32_e32 v173, v174, v15
	s_mov_b64 exec, s[10:11]
	ds_write2st64_b32 v176, v175, v238 offset0:56 offset1:60
	s_mov_b64 exec, -1
	ds_read_b128 v[8:11], v142 offset:12800
	ds_read_b128 v[12:15], v142 offset:20992
	ds_read_b128 v[16:19], v142 offset:29184
	ds_read_b128 v[20:23], v142 offset:37376
	ds_read2st64_b32 v[242:243], v148 offset0:210 offset1:211
	s_waitcnt lgkmcnt(10)
	v_mul_f32_e32 v174, v170, v28
	v_mul_f32_e32 v175, v170, v40
	v_fmac_f32_e32 v174, v171, v29
	v_fmac_f32_e32 v175, v171, v41
	v_fmac_f32_e32 v174, v172, v30
	v_fmac_f32_e32 v175, v172, v42
	v_fmac_f32_e32 v174, v173, v31
	v_fmac_f32_e32 v175, v173, v43
	v_fmac_f32_e32 v170, v240, v36
	v_add_f32_dpp v174, v174, v174 quad_perm:[1,0,3,2] row_mask:0xf bank_mask:0xf bound_ctrl:1
	v_add_f32_dpp v175, v175, v175 quad_perm:[1,0,3,2] row_mask:0xf bank_mask:0xf bound_ctrl:1
	v_fmac_f32_e32 v171, v240, v37
	v_add_f32_dpp v174, v174, v174 quad_perm:[2,3,0,1] row_mask:0xf bank_mask:0xf bound_ctrl:1
	v_add_f32_dpp v175, v175, v175 quad_perm:[2,3,0,1] row_mask:0xf bank_mask:0xf bound_ctrl:1
	v_fmac_f32_e32 v172, v240, v38
	v_add_f32_dpp v174, v174, v174 row_half_mirror row_mask:0xf bank_mask:0xf bound_ctrl:1
	v_fmac_f32_e32 v173, v240, v39
	s_nop 0
	v_add_f32_dpp v174, v174, v174 row_mirror row_mask:0xf bank_mask:0xf bound_ctrl:1
	v_fmac_f32_e32 v170, v174, v32
	v_fmac_f32_e32 v171, v174, v33
	v_fmac_f32_e32 v172, v174, v34
	v_fmac_f32_e32 v173, v174, v35
	ds_read_b128 v[28:31], v142 offset:13056
	ds_read_b128 v[32:35], v142 offset:21248
	ds_read_b128 v[36:39], v142 offset:29440
	ds_read_b128 v[40:43], v142 offset:37632
	s_waitcnt lgkmcnt(10)
	v_mul_f32_e32 v174, v170, v48
	v_mul_f32_e32 v238, v170, v60
	v_fmac_f32_e32 v174, v171, v49
	v_fmac_f32_e32 v238, v171, v61
	v_fmac_f32_e32 v174, v172, v50
	v_fmac_f32_e32 v238, v172, v62
	v_fmac_f32_e32 v174, v173, v51
	v_fmac_f32_e32 v238, v173, v63
	v_fmac_f32_e32 v170, v241, v56
	v_add_f32_dpp v174, v174, v174 quad_perm:[1,0,3,2] row_mask:0xf bank_mask:0xf bound_ctrl:1
	v_add_f32_dpp v238, v238, v238 quad_perm:[1,0,3,2] row_mask:0xf bank_mask:0xf bound_ctrl:1
	v_fmac_f32_e32 v171, v241, v57
	v_add_f32_dpp v174, v174, v174 quad_perm:[2,3,0,1] row_mask:0xf bank_mask:0xf bound_ctrl:1
	v_add_f32_dpp v238, v238, v238 quad_perm:[2,3,0,1] row_mask:0xf bank_mask:0xf bound_ctrl:1
	v_fmac_f32_e32 v172, v241, v58
	v_add_f32_dpp v174, v174, v174 row_half_mirror row_mask:0xf bank_mask:0xf bound_ctrl:1
	v_fmac_f32_e32 v173, v241, v59
	s_nop 0
	v_add_f32_dpp v174, v174, v174 row_mirror row_mask:0xf bank_mask:0xf bound_ctrl:1
	v_fmac_f32_e32 v170, v174, v52
	v_fmac_f32_e32 v171, v174, v53
	v_fmac_f32_e32 v172, v174, v54
	v_fmac_f32_e32 v173, v174, v55
	s_mov_b64 exec, s[10:11]
	ds_write2st64_b32 v176, v175, v238 offset0:64 offset1:68
	s_mov_b64 exec, -1
	ds_read_b128 v[48:51], v142 offset:13312
	ds_read_b128 v[52:55], v142 offset:21504
	ds_read_b128 v[56:59], v142 offset:29696
	ds_read_b128 v[60:63], v142 offset:37888
	ds_read2st64_b32 v[240:241], v148 offset0:212 offset1:213
	s_waitcnt lgkmcnt(10)
	v_mul_f32_e32 v174, v170, v8
	v_mul_f32_e32 v175, v170, v20
	v_fmac_f32_e32 v174, v171, v9
	v_fmac_f32_e32 v175, v171, v21
	v_fmac_f32_e32 v174, v172, v10
	v_fmac_f32_e32 v175, v172, v22
	v_fmac_f32_e32 v174, v173, v11
	v_fmac_f32_e32 v175, v173, v23
	v_fmac_f32_e32 v170, v242, v16
	v_add_f32_dpp v174, v174, v174 quad_perm:[1,0,3,2] row_mask:0xf bank_mask:0xf bound_ctrl:1
	v_add_f32_dpp v175, v175, v175 quad_perm:[1,0,3,2] row_mask:0xf bank_mask:0xf bound_ctrl:1
	v_fmac_f32_e32 v171, v242, v17
	v_add_f32_dpp v174, v174, v174 quad_perm:[2,3,0,1] row_mask:0xf bank_mask:0xf bound_ctrl:1
	v_add_f32_dpp v175, v175, v175 quad_perm:[2,3,0,1] row_mask:0xf bank_mask:0xf bound_ctrl:1
	v_fmac_f32_e32 v172, v242, v18
	v_add_f32_dpp v174, v174, v174 row_half_mirror row_mask:0xf bank_mask:0xf bound_ctrl:1
	v_fmac_f32_e32 v173, v242, v19
	s_nop 0
	v_add_f32_dpp v174, v174, v174 row_mirror row_mask:0xf bank_mask:0xf bound_ctrl:1
	v_fmac_f32_e32 v170, v174, v12
	v_fmac_f32_e32 v171, v174, v13
	v_fmac_f32_e32 v172, v174, v14
	v_fmac_f32_e32 v173, v174, v15
	ds_read_b128 v[8:11], v142 offset:13568
	ds_read_b128 v[12:15], v142 offset:21760
	ds_read_b128 v[16:19], v142 offset:29952
	ds_read_b128 v[20:23], v142 offset:38144
	s_waitcnt lgkmcnt(10)
	v_mul_f32_e32 v174, v170, v28
	v_mul_f32_e32 v238, v170, v40
	v_fmac_f32_e32 v174, v171, v29
	v_fmac_f32_e32 v238, v171, v41
	v_fmac_f32_e32 v174, v172, v30
	v_fmac_f32_e32 v238, v172, v42
	v_fmac_f32_e32 v174, v173, v31
	v_fmac_f32_e32 v238, v173, v43
	v_fmac_f32_e32 v170, v243, v36
	v_add_f32_dpp v174, v174, v174 quad_perm:[1,0,3,2] row_mask:0xf bank_mask:0xf bound_ctrl:1
	v_add_f32_dpp v238, v238, v238 quad_perm:[1,0,3,2] row_mask:0xf bank_mask:0xf bound_ctrl:1
	v_fmac_f32_e32 v171, v243, v37
	v_add_f32_dpp v174, v174, v174 quad_perm:[2,3,0,1] row_mask:0xf bank_mask:0xf bound_ctrl:1
	v_add_f32_dpp v238, v238, v238 quad_perm:[2,3,0,1] row_mask:0xf bank_mask:0xf bound_ctrl:1
	v_fmac_f32_e32 v172, v243, v38
	v_add_f32_dpp v174, v174, v174 row_half_mirror row_mask:0xf bank_mask:0xf bound_ctrl:1
	v_fmac_f32_e32 v173, v243, v39
	s_nop 0
	v_add_f32_dpp v174, v174, v174 row_mirror row_mask:0xf bank_mask:0xf bound_ctrl:1
	v_fmac_f32_e32 v170, v174, v32
	v_fmac_f32_e32 v171, v174, v33
	v_fmac_f32_e32 v172, v174, v34
	v_fmac_f32_e32 v173, v174, v35
	s_mov_b64 exec, s[10:11]
	ds_write2st64_b32 v176, v175, v238 offset0:72 offset1:76
	s_mov_b64 exec, -1
	ds_read_b128 v[28:31], v142 offset:13824
	ds_read_b128 v[32:35], v142 offset:22016
	ds_read_b128 v[36:39], v142 offset:30208
	ds_read_b128 v[40:43], v142 offset:38400
	ds_read2st64_b32 v[242:243], v148 offset0:214 offset1:215
	s_waitcnt lgkmcnt(10)
	v_mul_f32_e32 v174, v170, v48
	v_mul_f32_e32 v175, v170, v60
	v_fmac_f32_e32 v174, v171, v49
	v_fmac_f32_e32 v175, v171, v61
	v_fmac_f32_e32 v174, v172, v50
	v_fmac_f32_e32 v175, v172, v62
	v_fmac_f32_e32 v174, v173, v51
	v_fmac_f32_e32 v175, v173, v63
	v_fmac_f32_e32 v170, v240, v56
	v_add_f32_dpp v174, v174, v174 quad_perm:[1,0,3,2] row_mask:0xf bank_mask:0xf bound_ctrl:1
	v_add_f32_dpp v175, v175, v175 quad_perm:[1,0,3,2] row_mask:0xf bank_mask:0xf bound_ctrl:1
	v_fmac_f32_e32 v171, v240, v57
	v_add_f32_dpp v174, v174, v174 quad_perm:[2,3,0,1] row_mask:0xf bank_mask:0xf bound_ctrl:1
	v_add_f32_dpp v175, v175, v175 quad_perm:[2,3,0,1] row_mask:0xf bank_mask:0xf bound_ctrl:1
	v_fmac_f32_e32 v172, v240, v58
	v_add_f32_dpp v174, v174, v174 row_half_mirror row_mask:0xf bank_mask:0xf bound_ctrl:1
	v_fmac_f32_e32 v173, v240, v59
	s_nop 0
	v_add_f32_dpp v174, v174, v174 row_mirror row_mask:0xf bank_mask:0xf bound_ctrl:1
	v_fmac_f32_e32 v170, v174, v52
	v_fmac_f32_e32 v171, v174, v53
	v_fmac_f32_e32 v172, v174, v54
	v_fmac_f32_e32 v173, v174, v55
	ds_read_b128 v[48:51], v142 offset:14080
	ds_read_b128 v[52:55], v142 offset:22272
	ds_read_b128 v[56:59], v142 offset:30464
	ds_read_b128 v[60:63], v142 offset:38656
	s_waitcnt lgkmcnt(10)
	v_mul_f32_e32 v174, v170, v8
	v_mul_f32_e32 v238, v170, v20
	v_fmac_f32_e32 v174, v171, v9
	v_fmac_f32_e32 v238, v171, v21
	v_fmac_f32_e32 v174, v172, v10
	v_fmac_f32_e32 v238, v172, v22
	v_fmac_f32_e32 v174, v173, v11
	v_fmac_f32_e32 v238, v173, v23
	v_fmac_f32_e32 v170, v241, v16
	v_add_f32_dpp v174, v174, v174 quad_perm:[1,0,3,2] row_mask:0xf bank_mask:0xf bound_ctrl:1
	v_add_f32_dpp v238, v238, v238 quad_perm:[1,0,3,2] row_mask:0xf bank_mask:0xf bound_ctrl:1
	v_fmac_f32_e32 v171, v241, v17
	v_add_f32_dpp v174, v174, v174 quad_perm:[2,3,0,1] row_mask:0xf bank_mask:0xf bound_ctrl:1
	v_add_f32_dpp v238, v238, v238 quad_perm:[2,3,0,1] row_mask:0xf bank_mask:0xf bound_ctrl:1
	v_fmac_f32_e32 v172, v241, v18
	v_add_f32_dpp v174, v174, v174 row_half_mirror row_mask:0xf bank_mask:0xf bound_ctrl:1
	v_fmac_f32_e32 v173, v241, v19
	s_nop 0
	v_add_f32_dpp v174, v174, v174 row_mirror row_mask:0xf bank_mask:0xf bound_ctrl:1
	v_fmac_f32_e32 v170, v174, v12
	v_fmac_f32_e32 v171, v174, v13
	v_fmac_f32_e32 v172, v174, v14
	v_fmac_f32_e32 v173, v174, v15
	s_mov_b64 exec, s[10:11]
	ds_write2st64_b32 v176, v175, v238 offset0:80 offset1:84
	s_mov_b64 exec, -1
	ds_read_b128 v[8:11], v142 offset:14336
	ds_read_b128 v[12:15], v142 offset:22528
	ds_read_b128 v[16:19], v142 offset:30720
	ds_read_b128 v[20:23], v142 offset:38912
	ds_read2st64_b32 v[240:241], v148 offset0:216 offset1:217
	s_waitcnt lgkmcnt(10)
	v_mul_f32_e32 v174, v170, v28
	v_mul_f32_e32 v175, v170, v40
	v_fmac_f32_e32 v174, v171, v29
	v_fmac_f32_e32 v175, v171, v41
	v_fmac_f32_e32 v174, v172, v30
	v_fmac_f32_e32 v175, v172, v42
	v_fmac_f32_e32 v174, v173, v31
	v_fmac_f32_e32 v175, v173, v43
	v_fmac_f32_e32 v170, v242, v36
	v_add_f32_dpp v174, v174, v174 quad_perm:[1,0,3,2] row_mask:0xf bank_mask:0xf bound_ctrl:1
	v_add_f32_dpp v175, v175, v175 quad_perm:[1,0,3,2] row_mask:0xf bank_mask:0xf bound_ctrl:1
	v_fmac_f32_e32 v171, v242, v37
	v_add_f32_dpp v174, v174, v174 quad_perm:[2,3,0,1] row_mask:0xf bank_mask:0xf bound_ctrl:1
	v_add_f32_dpp v175, v175, v175 quad_perm:[2,3,0,1] row_mask:0xf bank_mask:0xf bound_ctrl:1
	v_fmac_f32_e32 v172, v242, v38
	v_add_f32_dpp v174, v174, v174 row_half_mirror row_mask:0xf bank_mask:0xf bound_ctrl:1
	v_fmac_f32_e32 v173, v242, v39
	s_nop 0
	v_add_f32_dpp v174, v174, v174 row_mirror row_mask:0xf bank_mask:0xf bound_ctrl:1
	v_fmac_f32_e32 v170, v174, v32
	v_fmac_f32_e32 v171, v174, v33
	v_fmac_f32_e32 v172, v174, v34
	v_fmac_f32_e32 v173, v174, v35
	ds_read_b128 v[28:31], v142 offset:14592
	ds_read_b128 v[32:35], v142 offset:22784
	ds_read_b128 v[36:39], v142 offset:30976
	ds_read_b128 v[40:43], v142 offset:39168
	s_waitcnt lgkmcnt(10)
	v_mul_f32_e32 v174, v170, v48
	v_mul_f32_e32 v238, v170, v60
	v_fmac_f32_e32 v174, v171, v49
	v_fmac_f32_e32 v238, v171, v61
	v_fmac_f32_e32 v174, v172, v50
	v_fmac_f32_e32 v238, v172, v62
	v_fmac_f32_e32 v174, v173, v51
	v_fmac_f32_e32 v238, v173, v63
	v_fmac_f32_e32 v170, v243, v56
	v_add_f32_dpp v174, v174, v174 quad_perm:[1,0,3,2] row_mask:0xf bank_mask:0xf bound_ctrl:1
	v_add_f32_dpp v238, v238, v238 quad_perm:[1,0,3,2] row_mask:0xf bank_mask:0xf bound_ctrl:1
	v_fmac_f32_e32 v171, v243, v57
	v_add_f32_dpp v174, v174, v174 quad_perm:[2,3,0,1] row_mask:0xf bank_mask:0xf bound_ctrl:1
	v_add_f32_dpp v238, v238, v238 quad_perm:[2,3,0,1] row_mask:0xf bank_mask:0xf bound_ctrl:1
	v_fmac_f32_e32 v172, v243, v58
	v_add_f32_dpp v174, v174, v174 row_half_mirror row_mask:0xf bank_mask:0xf bound_ctrl:1
	v_fmac_f32_e32 v173, v243, v59
	s_nop 0
	v_add_f32_dpp v174, v174, v174 row_mirror row_mask:0xf bank_mask:0xf bound_ctrl:1
	v_fmac_f32_e32 v170, v174, v52
	v_fmac_f32_e32 v171, v174, v53
	v_fmac_f32_e32 v172, v174, v54
	v_fmac_f32_e32 v173, v174, v55
	s_mov_b64 exec, s[10:11]
	ds_write2st64_b32 v176, v175, v238 offset0:88 offset1:92
	s_mov_b64 exec, -1
	ds_read_b128 v[48:51], v142 offset:14848
	ds_read_b128 v[52:55], v142 offset:23040
	ds_read_b128 v[56:59], v142 offset:31232
	ds_read_b128 v[60:63], v142 offset:39424
	ds_read2st64_b32 v[242:243], v148 offset0:218 offset1:219
	s_waitcnt lgkmcnt(10)
	v_mul_f32_e32 v174, v170, v8
	v_mul_f32_e32 v175, v170, v20
	v_fmac_f32_e32 v174, v171, v9
	v_fmac_f32_e32 v175, v171, v21
	v_fmac_f32_e32 v174, v172, v10
	v_fmac_f32_e32 v175, v172, v22
	v_fmac_f32_e32 v174, v173, v11
	v_fmac_f32_e32 v175, v173, v23
	v_fmac_f32_e32 v170, v240, v16
	v_add_f32_dpp v174, v174, v174 quad_perm:[1,0,3,2] row_mask:0xf bank_mask:0xf bound_ctrl:1
	v_add_f32_dpp v175, v175, v175 quad_perm:[1,0,3,2] row_mask:0xf bank_mask:0xf bound_ctrl:1
	v_fmac_f32_e32 v171, v240, v17
	v_add_f32_dpp v174, v174, v174 quad_perm:[2,3,0,1] row_mask:0xf bank_mask:0xf bound_ctrl:1
	v_add_f32_dpp v175, v175, v175 quad_perm:[2,3,0,1] row_mask:0xf bank_mask:0xf bound_ctrl:1
	v_fmac_f32_e32 v172, v240, v18
	v_add_f32_dpp v174, v174, v174 row_half_mirror row_mask:0xf bank_mask:0xf bound_ctrl:1
	v_fmac_f32_e32 v173, v240, v19
	s_nop 0
	v_add_f32_dpp v174, v174, v174 row_mirror row_mask:0xf bank_mask:0xf bound_ctrl:1
	v_fmac_f32_e32 v170, v174, v12
	v_fmac_f32_e32 v171, v174, v13
	v_fmac_f32_e32 v172, v174, v14
	v_fmac_f32_e32 v173, v174, v15
	ds_read_b128 v[8:11], v142 offset:15104
	ds_read_b128 v[12:15], v142 offset:23296
	ds_read_b128 v[16:19], v142 offset:31488
	ds_read_b128 v[20:23], v142 offset:39680
	s_waitcnt lgkmcnt(10)
	v_mul_f32_e32 v174, v170, v28
	v_mul_f32_e32 v238, v170, v40
	v_fmac_f32_e32 v174, v171, v29
	v_fmac_f32_e32 v238, v171, v41
	v_fmac_f32_e32 v174, v172, v30
	v_fmac_f32_e32 v238, v172, v42
	v_fmac_f32_e32 v174, v173, v31
	v_fmac_f32_e32 v238, v173, v43
	v_fmac_f32_e32 v170, v241, v36
	v_add_f32_dpp v174, v174, v174 quad_perm:[1,0,3,2] row_mask:0xf bank_mask:0xf bound_ctrl:1
	v_add_f32_dpp v238, v238, v238 quad_perm:[1,0,3,2] row_mask:0xf bank_mask:0xf bound_ctrl:1
	v_fmac_f32_e32 v171, v241, v37
	v_add_f32_dpp v174, v174, v174 quad_perm:[2,3,0,1] row_mask:0xf bank_mask:0xf bound_ctrl:1
	v_add_f32_dpp v238, v238, v238 quad_perm:[2,3,0,1] row_mask:0xf bank_mask:0xf bound_ctrl:1
	v_fmac_f32_e32 v172, v241, v38
	v_add_f32_dpp v174, v174, v174 row_half_mirror row_mask:0xf bank_mask:0xf bound_ctrl:1
	v_fmac_f32_e32 v173, v241, v39
	s_nop 0
	v_add_f32_dpp v174, v174, v174 row_mirror row_mask:0xf bank_mask:0xf bound_ctrl:1
	v_fmac_f32_e32 v170, v174, v32
	v_fmac_f32_e32 v171, v174, v33
	v_fmac_f32_e32 v172, v174, v34
	v_fmac_f32_e32 v173, v174, v35
	s_mov_b64 exec, s[10:11]
	ds_write2st64_b32 v176, v175, v238 offset0:96 offset1:100
	s_mov_b64 exec, -1
	ds_read_b128 v[28:31], v142 offset:15360
	ds_read_b128 v[32:35], v142 offset:23552
	ds_read_b128 v[36:39], v142 offset:31744
	ds_read_b128 v[40:43], v142 offset:39936
	ds_read2st64_b32 v[240:241], v148 offset0:220 offset1:221
	s_waitcnt lgkmcnt(10)
	v_mul_f32_e32 v174, v170, v48
	v_mul_f32_e32 v175, v170, v60
	v_fmac_f32_e32 v174, v171, v49
	v_fmac_f32_e32 v175, v171, v61
	v_fmac_f32_e32 v174, v172, v50
	v_fmac_f32_e32 v175, v172, v62
	v_fmac_f32_e32 v174, v173, v51
	v_fmac_f32_e32 v175, v173, v63
	v_fmac_f32_e32 v170, v242, v56
	v_add_f32_dpp v174, v174, v174 quad_perm:[1,0,3,2] row_mask:0xf bank_mask:0xf bound_ctrl:1
	v_add_f32_dpp v175, v175, v175 quad_perm:[1,0,3,2] row_mask:0xf bank_mask:0xf bound_ctrl:1
	v_fmac_f32_e32 v171, v242, v57
	v_add_f32_dpp v174, v174, v174 quad_perm:[2,3,0,1] row_mask:0xf bank_mask:0xf bound_ctrl:1
	v_add_f32_dpp v175, v175, v175 quad_perm:[2,3,0,1] row_mask:0xf bank_mask:0xf bound_ctrl:1
	v_fmac_f32_e32 v172, v242, v58
	v_add_f32_dpp v174, v174, v174 row_half_mirror row_mask:0xf bank_mask:0xf bound_ctrl:1
	v_fmac_f32_e32 v173, v242, v59
	s_nop 0
	v_add_f32_dpp v174, v174, v174 row_mirror row_mask:0xf bank_mask:0xf bound_ctrl:1
	v_fmac_f32_e32 v170, v174, v52
	v_fmac_f32_e32 v171, v174, v53
	v_fmac_f32_e32 v172, v174, v54
	v_fmac_f32_e32 v173, v174, v55
	ds_read_b128 v[48:51], v142 offset:15616
	ds_read_b128 v[52:55], v142 offset:23808
	ds_read_b128 v[56:59], v142 offset:32000
	ds_read_b128 v[60:63], v142 offset:40192
	s_waitcnt lgkmcnt(10)
	v_mul_f32_e32 v174, v170, v8
	v_mul_f32_e32 v238, v170, v20
	v_fmac_f32_e32 v174, v171, v9
	v_fmac_f32_e32 v238, v171, v21
	v_fmac_f32_e32 v174, v172, v10
	v_fmac_f32_e32 v238, v172, v22
	v_fmac_f32_e32 v174, v173, v11
	v_fmac_f32_e32 v238, v173, v23
	v_fmac_f32_e32 v170, v243, v16
	v_add_f32_dpp v174, v174, v174 quad_perm:[1,0,3,2] row_mask:0xf bank_mask:0xf bound_ctrl:1
	v_add_f32_dpp v238, v238, v238 quad_perm:[1,0,3,2] row_mask:0xf bank_mask:0xf bound_ctrl:1
	v_fmac_f32_e32 v171, v243, v17
	v_add_f32_dpp v174, v174, v174 quad_perm:[2,3,0,1] row_mask:0xf bank_mask:0xf bound_ctrl:1
	v_add_f32_dpp v238, v238, v238 quad_perm:[2,3,0,1] row_mask:0xf bank_mask:0xf bound_ctrl:1
	v_fmac_f32_e32 v172, v243, v18
	v_add_f32_dpp v174, v174, v174 row_half_mirror row_mask:0xf bank_mask:0xf bound_ctrl:1
	v_fmac_f32_e32 v173, v243, v19
	s_nop 0
	v_add_f32_dpp v174, v174, v174 row_mirror row_mask:0xf bank_mask:0xf bound_ctrl:1
	v_fmac_f32_e32 v170, v174, v12
	v_fmac_f32_e32 v171, v174, v13
	v_fmac_f32_e32 v172, v174, v14
	v_fmac_f32_e32 v173, v174, v15
	s_mov_b64 exec, s[10:11]
	ds_write2st64_b32 v176, v175, v238 offset0:104 offset1:108
	s_mov_b64 exec, -1
	ds_read_b128 v[8:11], v142 offset:15872
	ds_read_b128 v[12:15], v142 offset:24064
	ds_read_b128 v[16:19], v142 offset:32256
	ds_read_b128 v[20:23], v142 offset:40448
	ds_read2st64_b32 v[242:243], v148 offset0:222 offset1:223
	s_waitcnt lgkmcnt(10)
	v_mul_f32_e32 v174, v170, v28
	v_mul_f32_e32 v175, v170, v40
	v_fmac_f32_e32 v174, v171, v29
	v_fmac_f32_e32 v175, v171, v41
	v_fmac_f32_e32 v174, v172, v30
	v_fmac_f32_e32 v175, v172, v42
	v_fmac_f32_e32 v174, v173, v31
	v_fmac_f32_e32 v175, v173, v43
	v_fmac_f32_e32 v170, v240, v36
	v_add_f32_dpp v174, v174, v174 quad_perm:[1,0,3,2] row_mask:0xf bank_mask:0xf bound_ctrl:1
	v_add_f32_dpp v175, v175, v175 quad_perm:[1,0,3,2] row_mask:0xf bank_mask:0xf bound_ctrl:1
	v_fmac_f32_e32 v171, v240, v37
	v_add_f32_dpp v174, v174, v174 quad_perm:[2,3,0,1] row_mask:0xf bank_mask:0xf bound_ctrl:1
	v_add_f32_dpp v175, v175, v175 quad_perm:[2,3,0,1] row_mask:0xf bank_mask:0xf bound_ctrl:1
	v_fmac_f32_e32 v172, v240, v38
	v_add_f32_dpp v174, v174, v174 row_half_mirror row_mask:0xf bank_mask:0xf bound_ctrl:1
	v_fmac_f32_e32 v173, v240, v39
	s_nop 0
	v_add_f32_dpp v174, v174, v174 row_mirror row_mask:0xf bank_mask:0xf bound_ctrl:1
	v_fmac_f32_e32 v170, v174, v32
	v_fmac_f32_e32 v171, v174, v33
	v_fmac_f32_e32 v172, v174, v34
	v_fmac_f32_e32 v173, v174, v35
	ds_read_b128 v[28:31], v142 offset:16128
	ds_read_b128 v[32:35], v142 offset:24320
	ds_read_b128 v[36:39], v142 offset:32512
	ds_read_b128 v[40:43], v142 offset:40704
	s_waitcnt lgkmcnt(10)
	v_mul_f32_e32 v174, v170, v48
	v_mul_f32_e32 v238, v170, v60
	v_fmac_f32_e32 v174, v171, v49
	v_fmac_f32_e32 v238, v171, v61
	v_fmac_f32_e32 v174, v172, v50
	v_fmac_f32_e32 v238, v172, v62
	v_fmac_f32_e32 v174, v173, v51
	v_fmac_f32_e32 v238, v173, v63
	v_fmac_f32_e32 v170, v241, v56
	v_add_f32_dpp v174, v174, v174 quad_perm:[1,0,3,2] row_mask:0xf bank_mask:0xf bound_ctrl:1
	v_add_f32_dpp v238, v238, v238 quad_perm:[1,0,3,2] row_mask:0xf bank_mask:0xf bound_ctrl:1
	v_fmac_f32_e32 v171, v241, v57
	v_add_f32_dpp v174, v174, v174 quad_perm:[2,3,0,1] row_mask:0xf bank_mask:0xf bound_ctrl:1
	v_add_f32_dpp v238, v238, v238 quad_perm:[2,3,0,1] row_mask:0xf bank_mask:0xf bound_ctrl:1
	v_fmac_f32_e32 v172, v241, v58
	v_add_f32_dpp v174, v174, v174 row_half_mirror row_mask:0xf bank_mask:0xf bound_ctrl:1
	v_fmac_f32_e32 v173, v241, v59
	s_nop 0
	v_add_f32_dpp v174, v174, v174 row_mirror row_mask:0xf bank_mask:0xf bound_ctrl:1
	v_fmac_f32_e32 v170, v174, v52
	v_fmac_f32_e32 v171, v174, v53
	v_fmac_f32_e32 v172, v174, v54
	v_fmac_f32_e32 v173, v174, v55
	s_mov_b64 exec, s[10:11]
	ds_write2st64_b32 v176, v175, v238 offset0:112 offset1:116
	s_mov_b64 exec, -1
	s_waitcnt lgkmcnt(5)
	v_mul_f32_e32 v174, v170, v8
	v_mul_f32_e32 v175, v170, v20
	v_fmac_f32_e32 v174, v171, v9
	v_fmac_f32_e32 v175, v171, v21
	v_fmac_f32_e32 v174, v172, v10
	v_fmac_f32_e32 v175, v172, v22
	v_fmac_f32_e32 v174, v173, v11
	v_fmac_f32_e32 v175, v173, v23
	v_fmac_f32_e32 v170, v242, v16
	v_add_f32_dpp v174, v174, v174 quad_perm:[1,0,3,2] row_mask:0xf bank_mask:0xf bound_ctrl:1
	v_add_f32_dpp v175, v175, v175 quad_perm:[1,0,3,2] row_mask:0xf bank_mask:0xf bound_ctrl:1
	v_fmac_f32_e32 v171, v242, v17
	v_add_f32_dpp v174, v174, v174 quad_perm:[2,3,0,1] row_mask:0xf bank_mask:0xf bound_ctrl:1
	v_add_f32_dpp v175, v175, v175 quad_perm:[2,3,0,1] row_mask:0xf bank_mask:0xf bound_ctrl:1
	v_fmac_f32_e32 v172, v242, v18
	v_add_f32_dpp v174, v174, v174 row_half_mirror row_mask:0xf bank_mask:0xf bound_ctrl:1
	v_fmac_f32_e32 v173, v242, v19
	s_nop 0
	v_add_f32_dpp v174, v174, v174 row_mirror row_mask:0xf bank_mask:0xf bound_ctrl:1
	v_fmac_f32_e32 v170, v174, v12
	v_fmac_f32_e32 v171, v174, v13
	v_fmac_f32_e32 v172, v174, v14
	v_fmac_f32_e32 v173, v174, v15
	s_waitcnt lgkmcnt(1)
	v_mul_f32_e32 v174, v170, v28
	v_mul_f32_e32 v238, v170, v40
	v_fmac_f32_e32 v174, v171, v29
	v_fmac_f32_e32 v238, v171, v41
	v_fmac_f32_e32 v174, v172, v30
	v_fmac_f32_e32 v238, v172, v42
	v_fmac_f32_e32 v174, v173, v31
	v_fmac_f32_e32 v238, v173, v43
	v_fmac_f32_e32 v170, v243, v36
	v_add_f32_dpp v174, v174, v174 quad_perm:[1,0,3,2] row_mask:0xf bank_mask:0xf bound_ctrl:1
	v_add_f32_dpp v238, v238, v238 quad_perm:[1,0,3,2] row_mask:0xf bank_mask:0xf bound_ctrl:1
	v_fmac_f32_e32 v171, v243, v37
	v_add_f32_dpp v174, v174, v174 quad_perm:[2,3,0,1] row_mask:0xf bank_mask:0xf bound_ctrl:1
	v_add_f32_dpp v238, v238, v238 quad_perm:[2,3,0,1] row_mask:0xf bank_mask:0xf bound_ctrl:1
	v_fmac_f32_e32 v172, v243, v38
	v_add_f32_dpp v174, v174, v174 row_half_mirror row_mask:0xf bank_mask:0xf bound_ctrl:1
	v_fmac_f32_e32 v173, v243, v39
	s_nop 0
	v_add_f32_dpp v174, v174, v174 row_mirror row_mask:0xf bank_mask:0xf bound_ctrl:1
	v_fmac_f32_e32 v170, v174, v32
	v_fmac_f32_e32 v171, v174, v33
	v_fmac_f32_e32 v172, v174, v34
	v_fmac_f32_e32 v173, v174, v35
	s_mov_b64 exec, s[10:11]
	ds_write2st64_b32 v176, v175, v238 offset0:120 offset1:124
	s_mov_b64 exec, -1
	ds_read_b128 v[4:7], v142 offset:65280
	s_waitcnt lgkmcnt(0)
	v_mul_f32_e32 v170, v170, v4
	v_mul_f32_e32 v171, v171, v5
	v_mul_f32_e32 v172, v172, v6
	v_mul_f32_e32 v173, v173, v7
	s_waitcnt lgkmcnt(0)
	s_barrier
	s_and_saveexec_b64 s[10:11], s[8:9]
	s_cbranch_execz .LBB0_349
	v_lshrrev_b32_e32 v244, 4, v134
	v_lshl_add_u32 v244, v244, 9, v150
	ds_read_b128 v[4:7], v244
	ds_read_b128 v[8:11], v244 offset:256
	ds_read_b128 v[200:203], v244 offset:512
	ds_read_b128 v[204:207], v244 offset:768
	s_waitcnt lgkmcnt(0)
	v_pk_add_f32 v[4:5], v[4:5], v[200:201]
	v_pk_add_f32 v[6:7], v[6:7], v[202:203]
	v_pk_add_f32 v[8:9], v[8:9], v[204:205]
	v_pk_add_f32 v[10:11], v[10:11], v[206:207]
	v_pk_add_f32 v[10:11], v[6:7], v[10:11]
	v_pk_add_f32 v[8:9], v[4:5], v[8:9]
	ds_read_b128 v[4:7], v147
	s_waitcnt lgkmcnt(0)
	v_pk_add_f32 v[6:7], v[10:11], v[6:7]
	v_pk_add_f32 v[4:5], v[8:9], v[4:5]
	s_nop 0
	v_cvt_pk_bf16_f32 v4, v4, v5
	v_cvt_pk_bf16_f32 v5, v6, v7
	v_lshlrev_b64 v[6:7], 11, v[120:121]
	v_lshl_add_u64 v[6:7], v[102:103], 0, v[6:7]
	global_store_dwordx2 v[6:7], v[4:5], off
	s_branch .LBB0_349

	.amdhsa_kernel _Z14fwd_megakernel6Params
		.amdhsa_group_segment_fixed_size 16384
		.amdhsa_private_segment_fixed_size 0
		.amdhsa_kernarg_size 512
		.amdhsa_user_sgpr_count 2
		.amdhsa_user_sgpr_dispatch_ptr 0
		.amdhsa_user_sgpr_queue_ptr 0
		.amdhsa_user_sgpr_kernarg_segment_ptr 1
		.amdhsa_user_sgpr_dispatch_id 0
		.amdhsa_user_sgpr_kernarg_preload_length 0
		.amdhsa_user_sgpr_kernarg_preload_offset 0
		.amdhsa_user_sgpr_private_segment_size 0
		.amdhsa_uses_dynamic_stack 0
		.amdhsa_enable_private_segment 0
		.amdhsa_system_sgpr_workgroup_id_x 1
		.amdhsa_system_sgpr_workgroup_id_y 0
		.amdhsa_system_sgpr_workgroup_id_z 0
		.amdhsa_system_sgpr_workgroup_info 0
		.amdhsa_system_vgpr_workitem_id 2
		.amdhsa_next_free_vgpr 248
		.amdhsa_next_free_sgpr 98
		.amdhsa_accum_offset 248
		.amdhsa_reserve_vcc 1
		.amdhsa_float_round_mode_32 0
		.amdhsa_float_round_mode_16_64 0
		.amdhsa_float_denorm_mode_32 3
		.amdhsa_float_denorm_mode_16_64 3
		.amdhsa_dx10_clamp 1
		.amdhsa_ieee_mode 1
		.amdhsa_fp16_overflow 0
		.amdhsa_tg_split 0
		.amdhsa_exception_fp_ieee_invalid_op 0
		.amdhsa_exception_fp_denorm_src 0
		.amdhsa_exception_fp_ieee_div_zero 0
		.amdhsa_exception_fp_ieee_overflow 0
		.amdhsa_exception_fp_ieee_underflow 0
		.amdhsa_exception_fp_ieee_inexact 0
		.amdhsa_exception_int_div_zero 0
	.end_amdhsa_kernel

amdhsa.kernels:
  - .agpr_count:     0
    .args:
      - .offset:         0
        .size:           256
        .value_kind:     by_value
      - .offset:         256
        .size:           4
        .value_kind:     hidden_block_count_x
      - .offset:         260
        .size:           4
        .value_kind:     hidden_block_count_y
      - .offset:         264
        .size:           4
        .value_kind:     hidden_block_count_z
      - .offset:         268
        .size:           2
        .value_kind:     hidden_group_size_x
      - .offset:         270
        .size:           2
        .value_kind:     hidden_group_size_y
      - .offset:         272
        .size:           2
        .value_kind:     hidden_group_size_z
      - .offset:         274
        .size:           2
        .value_kind:     hidden_remainder_x
      - .offset:         276
        .size:           2
        .value_kind:     hidden_remainder_y
      - .offset:         278
        .size:           2
        .value_kind:     hidden_remainder_z
      - .offset:         296
        .size:           8
        .value_kind:     hidden_global_offset_x
      - .offset:         304
        .size:           8
        .value_kind:     hidden_global_offset_y
      - .offset:         312
        .size:           8
        .value_kind:     hidden_global_offset_z
      - .offset:         320
        .size:           2
        .value_kind:     hidden_grid_dims
      - .offset:         344
        .size:           8
        .value_kind:     hidden_multigrid_sync_arg
      - .offset:         376
        .size:           4
        .value_kind:     hidden_dynamic_lds_size
    .group_segment_fixed_size: 16384
    .kernarg_segment_align: 8
    .kernarg_segment_size: 512
    .language:       OpenCL C
    .language_version:
      - 2
      - 0
    .max_flat_workgroup_size: 512
    .name:           _Z14fwd_megakernel6Params
    .private_segment_fixed_size: 0
    .sgpr_count:     104
    .sgpr_spill_count: 51
    .symbol:         _Z14fwd_megakernel6Params.kd
    .uniform_work_group_size: 1
    .uses_dynamic_stack: false
    .vgpr_count:     248
    .vgpr_spill_count: 0
    .wavefront_size: 64
